# v11 plus: attention softmax shuffles via permlane swaps, SwiGLU epilogue row addresses by constant add instead of 64-bit mad, compiler vmcnt(0) before the gate-up K-loop removed
# baseline (speedup 1.0000x reference)
.LBB0_283:
	s_add_u32 s14, s14, 0x1ca00000
	s_addc_u32 s15, s15, 0
	s_add_i32 s48, s34, 0x18000
	s_or_b32 s19, s79, 0x80
	s_mov_b32 m0, s48
	s_add_i32 s49, s34, 0x1a000
	s_waitcnt vmcnt(2)
	s_barrier
	buffer_load_dwordx4 v154, s[36:39], s19 offen lds
	s_mov_b32 m0, s49
	s_add_i32 s51, s34, 0x8000
	buffer_load_dwordx4 v156, s[36:39], s19 offen lds
	s_or_b32 s19, s78, 0x80
	s_mov_b32 m0, s51
	s_add_i32 s52, s34, 0xa000
	buffer_load_dwordx4 v1, s[28:31], s19 offen lds
	s_mov_b32 m0, s52
	s_add_i32 s53, s34, 0x1c000
	buffer_load_dwordx4 v155, s[28:31], s19 offen lds
	s_or_b32 s19, s79, 0x40080
	s_mov_b32 m0, s53
	s_add_i32 s55, s34, 0x1e000
	buffer_load_dwordx4 v154, s[36:39], s19 offen lds
	s_mov_b32 m0, s55
	v_lshrrev_b32_e32 v3, 1, v2
	buffer_load_dwordx4 v156, s[36:39], s19 offen lds
	v_and_b32_e32 v159, 24, v3
	s_lshl_b32 s17, s17, 5
	v_and_b32_e32 v157, 15, v2
	v_lshlrev_b32_e32 v3, 1, v159
	v_lshlrev_b32_e32 v6, 2, v2
	s_and_b32 s57, s17, 0x60
	s_lshl_b32 s56, s18, 6
	v_lshl_or_b32 v3, v157, 6, v3
	s_lshl_b32 s18, s18, 13
	v_and_b32_e32 v6, 32, v6
	s_lshl_b32 s17, s57, 7
	v_bitop3_b32 v8, v3, s18, v6 bitop3:0xde
	v_bitop3_b32 v9, s17, v3, v6 bitop3:0xf6
	s_waitcnt vmcnt(6)
	s_add_i32 s59, s34, 0xc000
	v_mov_b32_e32 v3, v223
	s_cmpk_lt_u32 s16, 0x100
	v_mov_b32_e32 v6, v2
	v_lshl_add_u64 v[130:131], v[2:3], 2, v[4:5]
	v_add_u32_e32 v2, 0, v9
	v_or_b32_e32 v158, s56, v157
	s_cselect_b64 s[16:17], -1, 0
	s_add_i32 s60, s34, 0xe000
	s_ashr_i32 s61, s20, 31
	v_lshl_add_u64 v[132:133], v[6:7], 2, s[8:9]
	v_or_b32_e32 v160, s57, v159
	s_mov_b32 s77, 0
	v_add_u32_e32 v161, 0x10000, v2
	v_add_u32_e32 v162, 0x14000, v2
	v_add_u32_e32 v163, 0, v8
	v_add_u32_e32 v164, 0x18000, v2
	v_add_u32_e32 v165, 0x1c000, v2
	s_barrier
	s_branch .LBB0_286

.LBB0_292:
	s_lshl_b32 s18, s77, 11
	s_and_b32 s18, s18, 0x800
	s_add_i32 s18, s18, 0
	s_add_i32 s18, s18, 0x20000
	s_lshl_b32 s19, s57, 2
	s_add_i32 s19, s18, s19
	v_lshl_add_u32 v138, v159, 2, s19
	ds_read_b128 v[134:137], v138 offset:1024
	ds_read_b128 v[150:153], v138 offset:1040
	ds_read_b128 v[168:171], v138 offset:1536
	ds_read_b128 v[172:175], v138 offset:1552
	s_lshl_b32 s19, s56, 2
	s_add_i32 s18, s18, s19
	v_lshl_add_u32 v167, v157, 2, s18
	s_waitcnt lgkmcnt(0)
	v_pk_mul_f32 v[138:139], v[136:137], v[170:171]
	ds_read_b32 v170, v167
	v_cvt_f32_i32_e32 v125, v125
	v_cvt_f32_i32_e32 v124, v124
	v_cvt_f32_i32_e32 v123, v123
	v_cvt_f32_i32_e32 v122, v122
	v_cvt_f32_i32_e32 v129, v129
	v_cvt_f32_i32_e32 v128, v128
	v_cvt_f32_i32_e32 v127, v127
	v_cvt_f32_i32_e32 v126, v126
	v_cvt_f32_i32_e32 v119, v119
	v_cvt_f32_i32_e32 v118, v118
	v_cvt_f32_i32_e32 v121, v121
	v_cvt_f32_i32_e32 v120, v120
	v_cvt_f32_i32_e32 v115, v115
	v_cvt_f32_i32_e32 v114, v114
	v_cvt_f32_i32_e32 v117, v117
	v_cvt_f32_i32_e32 v116, v116
	v_lshl_add_u32 v166, s76, 8, v158
	v_lshl_or_b32 v176, s67, 7, v160
	s_mov_b32 s76, 0xbfb8aa3b
	v_pk_mul_f32 v[146:147], v[152:153], s[76:77] op_sel_hi:[1,0]
	v_pk_mul_f32 v[148:149], v[150:151], s[76:77] op_sel_hi:[1,0]
	v_ashrrev_i32_e32 v177, 31, v176
	s_waitcnt lgkmcnt(0)
	v_pk_mul_f32 v[122:123], v[170:171], v[122:123] op_sel_hi:[0,1]
	v_pk_mul_f32 v[124:125], v[170:171], v[124:125] op_sel_hi:[0,1]
	v_pk_mul_f32 v[142:143], v[136:137], s[76:77] op_sel_hi:[1,0]
	v_pk_mul_f32 v[144:145], v[134:135], s[76:77] op_sel_hi:[1,0]
	v_pk_mul_f32 v[140:141], v[134:135], v[168:169]
	v_pk_mul_f32 v[134:135], v[152:153], v[174:175]
	v_lshlrev_b64 v[152:153], 1, v[176:177]
	v_pk_mul_f32 v[126:127], v[170:171], v[126:127] op_sel_hi:[0,1]
	v_pk_mul_f32 v[128:129], v[170:171], v[128:129] op_sel_hi:[0,1]
	v_pk_mul_f32 v[174:175], v[146:147], v[124:125]
	v_pk_mul_f32 v[176:177], v[148:149], v[122:123]
	v_pk_mul_f32 v[136:137], v[150:151], v[172:173]
	v_pk_mul_f32 v[120:121], v[170:171], v[120:121] op_sel_hi:[0,1]
	v_pk_mul_f32 v[118:119], v[170:171], v[118:119] op_sel_hi:[0,1]
	v_pk_mul_f32 v[116:117], v[170:171], v[116:117] op_sel_hi:[0,1]
	v_pk_mul_f32 v[114:115], v[170:171], v[114:115] op_sel_hi:[0,1]
	v_pk_mul_f32 v[170:171], v[142:143], v[128:129]
	v_pk_mul_f32 v[172:173], v[144:145], v[126:127]
	v_exp_f32_e32 v176, v176
	v_exp_f32_e32 v177, v177
	v_exp_f32_e32 v174, v174
	v_exp_f32_e32 v175, v175
	v_exp_f32_e32 v172, v172
	v_exp_f32_e32 v173, v173
	v_exp_f32_e32 v170, v170
	v_exp_f32_e32 v171, v171
	v_pk_add_f32 v[174:175], v[174:175], 1.0 op_sel_hi:[1,0]
	v_pk_add_f32 v[176:177], v[176:177], 1.0 op_sel_hi:[1,0]
	v_pk_add_f32 v[172:173], v[172:173], 1.0 op_sel_hi:[1,0]
	v_pk_add_f32 v[170:171], v[170:171], 1.0 op_sel_hi:[1,0]
	v_rcp_f32_e32 v176, v176
	v_rcp_f32_e32 v177, v177
	v_rcp_f32_e32 v174, v174
	v_rcp_f32_e32 v175, v175
	v_rcp_f32_e32 v172, v172
	v_rcp_f32_e32 v173, v173
	v_rcp_f32_e32 v170, v170
	v_rcp_f32_e32 v171, v171
	v_mov_b64_e32 v[150:151], s[14:15]
	v_pk_mul_f32 v[114:115], v[122:123], v[114:115]
	v_pk_mul_f32 v[116:117], v[124:125], v[116:117]
	v_pk_mul_f32 v[122:123], v[136:137], v[176:177]
	v_pk_mul_f32 v[124:125], v[134:135], v[174:175]
	v_mad_i64_i32 v[168:169], s[18:19], v166, s87, v[150:151]
	v_pk_mul_f32 v[118:119], v[126:127], v[118:119]
	v_pk_mul_f32 v[120:121], v[128:129], v[120:121]
	v_pk_mul_f32 v[126:127], v[140:141], v[172:173]
	v_pk_mul_f32 v[128:129], v[138:139], v[170:171]
	v_pk_mul_f32 v[124:125], v[116:117], v[124:125]
	v_pk_mul_f32 v[116:117], v[114:115], v[122:123]
	v_lshl_add_u64 v[168:169], v[168:169], 0, v[152:153]
	v_mov_b64_e32 v[210:211], v[168:169]
	v_pk_mul_f32 v[120:121], v[120:121], v[128:129]
	v_pk_mul_f32 v[118:119], v[118:119], v[126:127]
	v_cvt_f32_i32_e32 v109, v109
	v_cvt_pk_bf16_f32 v114, v118, v119
	v_cvt_pk_bf16_f32 v115, v120, v121
	v_cvt_pk_bf16_f32 v116, v116, v117
	v_cvt_pk_bf16_f32 v117, v124, v125
	global_store_dwordx4 v[168:169], v[114:117], off
	ds_read_b32 v116, v167 offset:64
	v_cvt_f32_i32_e32 v108, v108
	v_cvt_f32_i32_e32 v107, v107
	v_cvt_f32_i32_e32 v106, v106
	v_cvt_f32_i32_e32 v113, v113
	v_cvt_f32_i32_e32 v112, v112
	v_cvt_f32_i32_e32 v111, v111
	v_cvt_f32_i32_e32 v110, v110
	v_cvt_f32_i32_e32 v103, v103
	v_cvt_f32_i32_e32 v102, v102
	v_cvt_f32_i32_e32 v105, v105
	v_cvt_f32_i32_e32 v104, v104
	v_cvt_f32_i32_e32 v99, v99
	v_cvt_f32_i32_e32 v98, v98
	v_cvt_f32_i32_e32 v101, v101
	v_cvt_f32_i32_e32 v100, v100
	s_waitcnt lgkmcnt(0)
	v_pk_mul_f32 v[106:107], v[116:117], v[106:107] op_sel_hi:[0,1]
	v_pk_mul_f32 v[108:109], v[116:117], v[108:109] op_sel_hi:[0,1]
	v_pk_mul_f32 v[110:111], v[116:117], v[110:111] op_sel_hi:[0,1]
	v_pk_mul_f32 v[112:113], v[116:117], v[112:113] op_sel_hi:[0,1]
	v_pk_mul_f32 v[120:121], v[146:147], v[108:109]
	v_pk_mul_f32 v[122:123], v[148:149], v[106:107]
	v_pk_mul_f32 v[104:105], v[116:117], v[104:105] op_sel_hi:[0,1]
	v_pk_mul_f32 v[102:103], v[116:117], v[102:103] op_sel_hi:[0,1]
	v_pk_mul_f32 v[100:101], v[116:117], v[100:101] op_sel_hi:[0,1]
	v_pk_mul_f32 v[98:99], v[116:117], v[98:99] op_sel_hi:[0,1]
	v_pk_mul_f32 v[116:117], v[142:143], v[112:113]
	v_pk_mul_f32 v[118:119], v[144:145], v[110:111]
	v_exp_f32_e32 v122, v122
	v_exp_f32_e32 v123, v123
	v_exp_f32_e32 v120, v120
	v_exp_f32_e32 v121, v121
	v_exp_f32_e32 v118, v118
	v_exp_f32_e32 v119, v119
	v_exp_f32_e32 v116, v116
	v_exp_f32_e32 v117, v117
	v_pk_add_f32 v[120:121], v[120:121], 1.0 op_sel_hi:[1,0]
	v_pk_add_f32 v[122:123], v[122:123], 1.0 op_sel_hi:[1,0]
	v_pk_add_f32 v[118:119], v[118:119], 1.0 op_sel_hi:[1,0]
	v_pk_add_f32 v[116:117], v[116:117], 1.0 op_sel_hi:[1,0]
	v_rcp_f32_e32 v122, v122
	v_rcp_f32_e32 v123, v123
	v_rcp_f32_e32 v120, v120
	v_rcp_f32_e32 v121, v121
	v_rcp_f32_e32 v118, v118
	v_rcp_f32_e32 v119, v119
	v_rcp_f32_e32 v116, v116
	v_rcp_f32_e32 v117, v117
	s_mov_b32 s98, 0x2c000
	v_pk_mul_f32 v[98:99], v[106:107], v[98:99]
	v_pk_mul_f32 v[100:101], v[108:109], v[100:101]
	v_pk_mul_f32 v[106:107], v[136:137], v[122:123]
	v_pk_mul_f32 v[108:109], v[134:135], v[120:121]
	s_mov_b32 s99, 0
	v_pk_mul_f32 v[102:103], v[110:111], v[102:103]
	v_pk_mul_f32 v[104:105], v[112:113], v[104:105]
	v_pk_mul_f32 v[110:111], v[140:141], v[118:119]
	v_pk_mul_f32 v[112:113], v[138:139], v[116:117]
	v_pk_mul_f32 v[108:109], v[100:101], v[108:109]
	v_pk_mul_f32 v[100:101], v[98:99], v[106:107]
	v_lshl_add_u64 v[114:115], v[210:211], 0, s[98:99]
	v_pk_mul_f32 v[104:105], v[104:105], v[112:113]
	v_pk_mul_f32 v[102:103], v[102:103], v[110:111]
	v_cvt_f32_i32_e32 v93, v93
	v_cvt_pk_bf16_f32 v98, v102, v103
	v_cvt_pk_bf16_f32 v99, v104, v105
	v_cvt_pk_bf16_f32 v100, v100, v101
	v_cvt_pk_bf16_f32 v101, v108, v109
	global_store_dwordx4 v[114:115], v[98:101], off
	ds_read_b32 v100, v167 offset:128
	v_cvt_f32_i32_e32 v92, v92
	v_cvt_f32_i32_e32 v91, v91
	v_cvt_f32_i32_e32 v90, v90
	v_cvt_f32_i32_e32 v97, v97
	v_cvt_f32_i32_e32 v96, v96
	v_cvt_f32_i32_e32 v95, v95
	v_cvt_f32_i32_e32 v94, v94
	v_cvt_f32_i32_e32 v87, v87
	v_cvt_f32_i32_e32 v86, v86
	v_cvt_f32_i32_e32 v89, v89
	v_cvt_f32_i32_e32 v88, v88
	v_cvt_f32_i32_e32 v83, v83
	v_cvt_f32_i32_e32 v82, v82
	v_cvt_f32_i32_e32 v85, v85
	v_cvt_f32_i32_e32 v84, v84
	s_waitcnt lgkmcnt(0)
	v_pk_mul_f32 v[90:91], v[100:101], v[90:91] op_sel_hi:[0,1]
	v_pk_mul_f32 v[92:93], v[100:101], v[92:93] op_sel_hi:[0,1]
	v_pk_mul_f32 v[94:95], v[100:101], v[94:95] op_sel_hi:[0,1]
	v_pk_mul_f32 v[96:97], v[100:101], v[96:97] op_sel_hi:[0,1]
	v_pk_mul_f32 v[104:105], v[146:147], v[92:93]
	v_pk_mul_f32 v[106:107], v[148:149], v[90:91]
	v_pk_mul_f32 v[88:89], v[100:101], v[88:89] op_sel_hi:[0,1]
	v_pk_mul_f32 v[86:87], v[100:101], v[86:87] op_sel_hi:[0,1]
	v_pk_mul_f32 v[84:85], v[100:101], v[84:85] op_sel_hi:[0,1]
	v_pk_mul_f32 v[82:83], v[100:101], v[82:83] op_sel_hi:[0,1]
	v_pk_mul_f32 v[100:101], v[142:143], v[96:97]
	v_pk_mul_f32 v[102:103], v[144:145], v[94:95]
	v_exp_f32_e32 v106, v106
	v_exp_f32_e32 v107, v107
	v_exp_f32_e32 v104, v104
	v_exp_f32_e32 v105, v105
	v_exp_f32_e32 v102, v102
	v_exp_f32_e32 v103, v103
	v_exp_f32_e32 v100, v100
	v_exp_f32_e32 v101, v101
	v_pk_add_f32 v[104:105], v[104:105], 1.0 op_sel_hi:[1,0]
	v_pk_add_f32 v[106:107], v[106:107], 1.0 op_sel_hi:[1,0]
	v_pk_add_f32 v[102:103], v[102:103], 1.0 op_sel_hi:[1,0]
	v_pk_add_f32 v[100:101], v[100:101], 1.0 op_sel_hi:[1,0]
	v_rcp_f32_e32 v106, v106
	v_rcp_f32_e32 v107, v107
	v_rcp_f32_e32 v104, v104
	v_rcp_f32_e32 v105, v105
	v_rcp_f32_e32 v102, v102
	v_rcp_f32_e32 v103, v103
	v_rcp_f32_e32 v100, v100
	v_rcp_f32_e32 v101, v101
	s_mov_b32 s98, 0x58000
	v_pk_mul_f32 v[82:83], v[90:91], v[82:83]
	v_pk_mul_f32 v[84:85], v[92:93], v[84:85]
	v_pk_mul_f32 v[90:91], v[136:137], v[106:107]
	v_pk_mul_f32 v[92:93], v[134:135], v[104:105]
	s_mov_b32 s99, 0
	v_pk_mul_f32 v[86:87], v[94:95], v[86:87]
	v_pk_mul_f32 v[88:89], v[96:97], v[88:89]
	v_pk_mul_f32 v[94:95], v[140:141], v[102:103]
	v_pk_mul_f32 v[96:97], v[138:139], v[100:101]
	v_pk_mul_f32 v[92:93], v[84:85], v[92:93]
	v_pk_mul_f32 v[84:85], v[82:83], v[90:91]
	v_lshl_add_u64 v[98:99], v[210:211], 0, s[98:99]
	v_pk_mul_f32 v[88:89], v[88:89], v[96:97]
	v_pk_mul_f32 v[86:87], v[86:87], v[94:95]
	v_cvt_f32_i32_e32 v77, v77
	v_cvt_pk_bf16_f32 v82, v86, v87
	v_cvt_pk_bf16_f32 v83, v88, v89
	v_cvt_pk_bf16_f32 v84, v84, v85
	v_cvt_pk_bf16_f32 v85, v92, v93
	global_store_dwordx4 v[98:99], v[82:85], off
	ds_read_b32 v84, v167 offset:192
	v_cvt_f32_i32_e32 v76, v76
	v_cvt_f32_i32_e32 v75, v75
	v_cvt_f32_i32_e32 v74, v74
	v_cvt_f32_i32_e32 v81, v81
	v_cvt_f32_i32_e32 v80, v80
	v_cvt_f32_i32_e32 v79, v79
	v_cvt_f32_i32_e32 v78, v78
	v_cvt_f32_i32_e32 v71, v71
	v_cvt_f32_i32_e32 v70, v70
	v_cvt_f32_i32_e32 v73, v73
	v_cvt_f32_i32_e32 v72, v72
	v_cvt_f32_i32_e32 v67, v67
	v_cvt_f32_i32_e32 v66, v66
	v_cvt_f32_i32_e32 v69, v69
	v_cvt_f32_i32_e32 v68, v68
	s_waitcnt lgkmcnt(0)
	v_pk_mul_f32 v[74:75], v[84:85], v[74:75] op_sel_hi:[0,1]
	v_pk_mul_f32 v[76:77], v[84:85], v[76:77] op_sel_hi:[0,1]
	v_pk_mul_f32 v[78:79], v[84:85], v[78:79] op_sel_hi:[0,1]
	v_pk_mul_f32 v[80:81], v[84:85], v[80:81] op_sel_hi:[0,1]
	v_pk_mul_f32 v[88:89], v[146:147], v[76:77]
	v_pk_mul_f32 v[90:91], v[148:149], v[74:75]
	v_pk_mul_f32 v[72:73], v[84:85], v[72:73] op_sel_hi:[0,1]
	v_pk_mul_f32 v[70:71], v[84:85], v[70:71] op_sel_hi:[0,1]
	v_pk_mul_f32 v[68:69], v[84:85], v[68:69] op_sel_hi:[0,1]
	v_pk_mul_f32 v[66:67], v[84:85], v[66:67] op_sel_hi:[0,1]
	v_pk_mul_f32 v[84:85], v[142:143], v[80:81]
	v_pk_mul_f32 v[86:87], v[144:145], v[78:79]
	v_exp_f32_e32 v90, v90
	v_exp_f32_e32 v91, v91
	v_exp_f32_e32 v88, v88
	v_exp_f32_e32 v89, v89
	v_exp_f32_e32 v86, v86
	v_exp_f32_e32 v87, v87
	v_exp_f32_e32 v84, v84
	v_exp_f32_e32 v85, v85
	v_pk_add_f32 v[88:89], v[88:89], 1.0 op_sel_hi:[1,0]
	v_pk_add_f32 v[90:91], v[90:91], 1.0 op_sel_hi:[1,0]
	v_pk_add_f32 v[86:87], v[86:87], 1.0 op_sel_hi:[1,0]
	v_pk_add_f32 v[84:85], v[84:85], 1.0 op_sel_hi:[1,0]
	v_rcp_f32_e32 v90, v90
	v_rcp_f32_e32 v91, v91
	v_rcp_f32_e32 v88, v88
	v_rcp_f32_e32 v89, v89
	v_rcp_f32_e32 v86, v86
	v_rcp_f32_e32 v87, v87
	v_rcp_f32_e32 v84, v84
	v_rcp_f32_e32 v85, v85
	s_mov_b32 s98, 0x84000
	v_pk_mul_f32 v[66:67], v[74:75], v[66:67]
	v_pk_mul_f32 v[68:69], v[76:77], v[68:69]
	v_pk_mul_f32 v[74:75], v[136:137], v[90:91]
	v_pk_mul_f32 v[76:77], v[134:135], v[88:89]
	s_mov_b32 s99, 0
	v_pk_mul_f32 v[70:71], v[78:79], v[70:71]
	v_pk_mul_f32 v[72:73], v[80:81], v[72:73]
	v_pk_mul_f32 v[78:79], v[140:141], v[86:87]
	v_pk_mul_f32 v[80:81], v[138:139], v[84:85]
	v_pk_mul_f32 v[76:77], v[68:69], v[76:77]
	v_pk_mul_f32 v[68:69], v[66:67], v[74:75]
	v_lshl_add_u64 v[82:83], v[210:211], 0, s[98:99]
	v_pk_mul_f32 v[72:73], v[72:73], v[80:81]
	v_pk_mul_f32 v[70:71], v[70:71], v[78:79]
	v_cvt_f32_i32_e32 v61, v61
	v_cvt_pk_bf16_f32 v66, v70, v71
	v_cvt_pk_bf16_f32 v67, v72, v73
	v_cvt_pk_bf16_f32 v68, v68, v69
	v_cvt_pk_bf16_f32 v69, v76, v77
	global_store_dwordx4 v[82:83], v[66:69], off
	ds_read_b32 v68, v167 offset:512
	v_cvt_f32_i32_e32 v60, v60
	v_cvt_f32_i32_e32 v59, v59
	v_cvt_f32_i32_e32 v58, v58
	v_cvt_f32_i32_e32 v65, v65
	v_cvt_f32_i32_e32 v64, v64
	v_cvt_f32_i32_e32 v63, v63
	v_cvt_f32_i32_e32 v62, v62
	v_cvt_f32_i32_e32 v55, v55
	v_cvt_f32_i32_e32 v54, v54
	v_cvt_f32_i32_e32 v57, v57
	v_cvt_f32_i32_e32 v56, v56
	v_cvt_f32_i32_e32 v51, v51
	v_cvt_f32_i32_e32 v50, v50
	v_cvt_f32_i32_e32 v53, v53
	v_cvt_f32_i32_e32 v52, v52
	s_waitcnt lgkmcnt(0)
	v_pk_mul_f32 v[58:59], v[68:69], v[58:59] op_sel_hi:[0,1]
	v_pk_mul_f32 v[60:61], v[68:69], v[60:61] op_sel_hi:[0,1]
	v_pk_mul_f32 v[62:63], v[68:69], v[62:63] op_sel_hi:[0,1]
	v_pk_mul_f32 v[64:65], v[68:69], v[64:65] op_sel_hi:[0,1]
	v_pk_mul_f32 v[72:73], v[146:147], v[60:61]
	v_pk_mul_f32 v[74:75], v[148:149], v[58:59]
	v_pk_mul_f32 v[56:57], v[68:69], v[56:57] op_sel_hi:[0,1]
	v_pk_mul_f32 v[54:55], v[68:69], v[54:55] op_sel_hi:[0,1]
	v_pk_mul_f32 v[52:53], v[68:69], v[52:53] op_sel_hi:[0,1]
	v_pk_mul_f32 v[50:51], v[68:69], v[50:51] op_sel_hi:[0,1]
	v_pk_mul_f32 v[68:69], v[142:143], v[64:65]
	v_pk_mul_f32 v[70:71], v[144:145], v[62:63]
	v_exp_f32_e32 v74, v74
	v_exp_f32_e32 v75, v75
	v_exp_f32_e32 v72, v72
	v_exp_f32_e32 v73, v73
	v_exp_f32_e32 v70, v70
	v_exp_f32_e32 v71, v71
	v_exp_f32_e32 v68, v68
	v_exp_f32_e32 v69, v69
	v_pk_add_f32 v[72:73], v[72:73], 1.0 op_sel_hi:[1,0]
	v_pk_add_f32 v[74:75], v[74:75], 1.0 op_sel_hi:[1,0]
	v_pk_add_f32 v[70:71], v[70:71], 1.0 op_sel_hi:[1,0]
	v_pk_add_f32 v[68:69], v[68:69], 1.0 op_sel_hi:[1,0]
	v_rcp_f32_e32 v74, v74
	v_rcp_f32_e32 v75, v75
	v_rcp_f32_e32 v72, v72
	v_rcp_f32_e32 v73, v73
	v_rcp_f32_e32 v70, v70
	v_rcp_f32_e32 v71, v71
	v_rcp_f32_e32 v68, v68
	v_rcp_f32_e32 v69, v69
	s_mov_b32 s98, 0x160000
	v_pk_mul_f32 v[50:51], v[58:59], v[50:51]
	v_pk_mul_f32 v[52:53], v[60:61], v[52:53]
	v_pk_mul_f32 v[58:59], v[136:137], v[74:75]
	v_pk_mul_f32 v[60:61], v[134:135], v[72:73]
	s_mov_b32 s99, 0
	v_pk_mul_f32 v[54:55], v[62:63], v[54:55]
	v_pk_mul_f32 v[56:57], v[64:65], v[56:57]
	v_pk_mul_f32 v[62:63], v[140:141], v[70:71]
	v_pk_mul_f32 v[64:65], v[138:139], v[68:69]
	v_pk_mul_f32 v[60:61], v[52:53], v[60:61]
	v_pk_mul_f32 v[52:53], v[50:51], v[58:59]
	v_lshl_add_u64 v[66:67], v[210:211], 0, s[98:99]
	v_pk_mul_f32 v[56:57], v[56:57], v[64:65]
	v_pk_mul_f32 v[54:55], v[54:55], v[62:63]
	v_cvt_f32_i32_e32 v45, v45
	v_cvt_pk_bf16_f32 v50, v54, v55
	v_cvt_pk_bf16_f32 v51, v56, v57
	v_cvt_pk_bf16_f32 v52, v52, v53
	v_cvt_pk_bf16_f32 v53, v60, v61
	global_store_dwordx4 v[66:67], v[50:53], off
	ds_read_b32 v52, v167 offset:576
	v_cvt_f32_i32_e32 v44, v44
	v_cvt_f32_i32_e32 v43, v43
	v_cvt_f32_i32_e32 v42, v42
	v_cvt_f32_i32_e32 v49, v49
	v_cvt_f32_i32_e32 v48, v48
	v_cvt_f32_i32_e32 v47, v47
	v_cvt_f32_i32_e32 v46, v46
	v_cvt_f32_i32_e32 v39, v39
	v_cvt_f32_i32_e32 v38, v38
	v_cvt_f32_i32_e32 v41, v41
	v_cvt_f32_i32_e32 v40, v40
	v_cvt_f32_i32_e32 v35, v35
	v_cvt_f32_i32_e32 v34, v34
	v_cvt_f32_i32_e32 v37, v37
	v_cvt_f32_i32_e32 v36, v36
	s_waitcnt lgkmcnt(0)
	v_pk_mul_f32 v[42:43], v[52:53], v[42:43] op_sel_hi:[0,1]
	v_pk_mul_f32 v[44:45], v[52:53], v[44:45] op_sel_hi:[0,1]
	v_pk_mul_f32 v[46:47], v[52:53], v[46:47] op_sel_hi:[0,1]
	v_pk_mul_f32 v[48:49], v[52:53], v[48:49] op_sel_hi:[0,1]
	v_pk_mul_f32 v[56:57], v[146:147], v[44:45]
	v_pk_mul_f32 v[58:59], v[148:149], v[42:43]
	v_pk_mul_f32 v[40:41], v[52:53], v[40:41] op_sel_hi:[0,1]
	v_pk_mul_f32 v[38:39], v[52:53], v[38:39] op_sel_hi:[0,1]
	v_pk_mul_f32 v[36:37], v[52:53], v[36:37] op_sel_hi:[0,1]
	v_pk_mul_f32 v[34:35], v[52:53], v[34:35] op_sel_hi:[0,1]
	v_pk_mul_f32 v[52:53], v[142:143], v[48:49]
	v_pk_mul_f32 v[54:55], v[144:145], v[46:47]
	v_exp_f32_e32 v58, v58
	v_exp_f32_e32 v59, v59
	v_exp_f32_e32 v56, v56
	v_exp_f32_e32 v57, v57
	v_exp_f32_e32 v54, v54
	v_exp_f32_e32 v55, v55
	v_exp_f32_e32 v52, v52
	v_exp_f32_e32 v53, v53
	v_pk_add_f32 v[56:57], v[56:57], 1.0 op_sel_hi:[1,0]
	v_pk_add_f32 v[58:59], v[58:59], 1.0 op_sel_hi:[1,0]
	v_pk_add_f32 v[54:55], v[54:55], 1.0 op_sel_hi:[1,0]
	v_pk_add_f32 v[52:53], v[52:53], 1.0 op_sel_hi:[1,0]
	v_rcp_f32_e32 v58, v58
	v_rcp_f32_e32 v59, v59
	v_rcp_f32_e32 v56, v56
	v_rcp_f32_e32 v57, v57
	v_rcp_f32_e32 v54, v54
	v_rcp_f32_e32 v55, v55
	v_rcp_f32_e32 v52, v52
	v_rcp_f32_e32 v53, v53
	s_mov_b32 s98, 0x18c000
	v_pk_mul_f32 v[34:35], v[42:43], v[34:35]
	v_pk_mul_f32 v[36:37], v[44:45], v[36:37]
	v_pk_mul_f32 v[42:43], v[136:137], v[58:59]
	v_pk_mul_f32 v[44:45], v[134:135], v[56:57]
	s_mov_b32 s99, 0
	v_pk_mul_f32 v[38:39], v[46:47], v[38:39]
	v_pk_mul_f32 v[40:41], v[48:49], v[40:41]
	v_pk_mul_f32 v[46:47], v[140:141], v[54:55]
	v_pk_mul_f32 v[48:49], v[138:139], v[52:53]
	v_pk_mul_f32 v[44:45], v[36:37], v[44:45]
	v_pk_mul_f32 v[36:37], v[34:35], v[42:43]
	v_lshl_add_u64 v[50:51], v[210:211], 0, s[98:99]
	v_pk_mul_f32 v[40:41], v[40:41], v[48:49]
	v_pk_mul_f32 v[38:39], v[38:39], v[46:47]
	v_cvt_f32_i32_e32 v29, v29
	v_cvt_pk_bf16_f32 v34, v38, v39
	v_cvt_pk_bf16_f32 v35, v40, v41
	v_cvt_pk_bf16_f32 v36, v36, v37
	v_cvt_pk_bf16_f32 v37, v44, v45
	global_store_dwordx4 v[50:51], v[34:37], off
	ds_read_b32 v36, v167 offset:640
	v_cvt_f32_i32_e32 v28, v28
	v_cvt_f32_i32_e32 v27, v27
	v_cvt_f32_i32_e32 v26, v26
	v_cvt_f32_i32_e32 v33, v33
	v_cvt_f32_i32_e32 v32, v32
	v_cvt_f32_i32_e32 v31, v31
	v_cvt_f32_i32_e32 v30, v30
	v_cvt_f32_i32_e32 v23, v23
	v_cvt_f32_i32_e32 v22, v22
	v_cvt_f32_i32_e32 v25, v25
	v_cvt_f32_i32_e32 v24, v24
	v_cvt_f32_i32_e32 v19, v19
	v_cvt_f32_i32_e32 v18, v18
	v_cvt_f32_i32_e32 v21, v21
	v_cvt_f32_i32_e32 v20, v20
	s_waitcnt lgkmcnt(0)
	v_pk_mul_f32 v[26:27], v[36:37], v[26:27] op_sel_hi:[0,1]
	v_pk_mul_f32 v[28:29], v[36:37], v[28:29] op_sel_hi:[0,1]
	v_pk_mul_f32 v[30:31], v[36:37], v[30:31] op_sel_hi:[0,1]
	v_pk_mul_f32 v[32:33], v[36:37], v[32:33] op_sel_hi:[0,1]
	v_pk_mul_f32 v[40:41], v[146:147], v[28:29]
	v_pk_mul_f32 v[42:43], v[148:149], v[26:27]
	v_pk_mul_f32 v[24:25], v[36:37], v[24:25] op_sel_hi:[0,1]
	v_pk_mul_f32 v[22:23], v[36:37], v[22:23] op_sel_hi:[0,1]
	v_pk_mul_f32 v[20:21], v[36:37], v[20:21] op_sel_hi:[0,1]
	v_pk_mul_f32 v[18:19], v[36:37], v[18:19] op_sel_hi:[0,1]
	v_pk_mul_f32 v[36:37], v[142:143], v[32:33]
	v_pk_mul_f32 v[38:39], v[144:145], v[30:31]
	v_exp_f32_e32 v42, v42
	v_exp_f32_e32 v43, v43
	v_exp_f32_e32 v40, v40
	v_exp_f32_e32 v41, v41
	v_exp_f32_e32 v38, v38
	v_exp_f32_e32 v39, v39
	v_exp_f32_e32 v36, v36
	v_exp_f32_e32 v37, v37
	v_pk_add_f32 v[40:41], v[40:41], 1.0 op_sel_hi:[1,0]
	v_pk_add_f32 v[42:43], v[42:43], 1.0 op_sel_hi:[1,0]
	v_pk_add_f32 v[38:39], v[38:39], 1.0 op_sel_hi:[1,0]
	v_pk_add_f32 v[36:37], v[36:37], 1.0 op_sel_hi:[1,0]
	v_rcp_f32_e32 v42, v42
	v_rcp_f32_e32 v43, v43
	v_rcp_f32_e32 v40, v40
	v_rcp_f32_e32 v41, v41
	v_rcp_f32_e32 v38, v38
	v_rcp_f32_e32 v39, v39
	v_rcp_f32_e32 v36, v36
	v_rcp_f32_e32 v37, v37
	s_mov_b32 s98, 0x1b8000
	v_pk_mul_f32 v[18:19], v[26:27], v[18:19]
	v_pk_mul_f32 v[20:21], v[28:29], v[20:21]
	v_pk_mul_f32 v[26:27], v[136:137], v[42:43]
	v_pk_mul_f32 v[28:29], v[134:135], v[40:41]
	s_mov_b32 s99, 0
	v_pk_mul_f32 v[22:23], v[30:31], v[22:23]
	v_pk_mul_f32 v[24:25], v[32:33], v[24:25]
	v_pk_mul_f32 v[30:31], v[140:141], v[38:39]
	v_pk_mul_f32 v[32:33], v[138:139], v[36:37]
	v_pk_mul_f32 v[28:29], v[20:21], v[28:29]
	v_pk_mul_f32 v[20:21], v[18:19], v[26:27]
	v_lshl_add_u64 v[34:35], v[210:211], 0, s[98:99]
	v_pk_mul_f32 v[24:25], v[24:25], v[32:33]
	v_pk_mul_f32 v[22:23], v[22:23], v[30:31]
	v_cvt_f32_i32_e32 v13, v13
	v_cvt_pk_bf16_f32 v18, v22, v23
	v_cvt_pk_bf16_f32 v19, v24, v25
	v_cvt_pk_bf16_f32 v20, v20, v21
	v_cvt_pk_bf16_f32 v21, v28, v29
	global_store_dwordx4 v[34:35], v[18:21], off
	ds_read_b32 v20, v167 offset:704
	v_cvt_f32_i32_e32 v12, v12
	v_cvt_f32_i32_e32 v11, v11
	v_cvt_f32_i32_e32 v10, v10
	v_cvt_f32_i32_e32 v17, v17
	v_cvt_f32_i32_e32 v16, v16
	v_cvt_f32_i32_e32 v15, v15
	v_cvt_f32_i32_e32 v14, v14
	v_cvt_f32_i32_e32 v7, v7
	v_cvt_f32_i32_e32 v6, v6
	v_cvt_f32_i32_e32 v9, v9
	v_cvt_f32_i32_e32 v8, v8
	v_cvt_f32_i32_e32 v3, v3
	v_cvt_f32_i32_e32 v2, v2
	v_cvt_f32_i32_e32 v5, v5
	v_cvt_f32_i32_e32 v4, v4
	s_waitcnt lgkmcnt(0)
	v_pk_mul_f32 v[10:11], v[20:21], v[10:11] op_sel_hi:[0,1]
	v_pk_mul_f32 v[12:13], v[20:21], v[12:13] op_sel_hi:[0,1]
	v_pk_mul_f32 v[14:15], v[20:21], v[14:15] op_sel_hi:[0,1]
	v_pk_mul_f32 v[16:17], v[20:21], v[16:17] op_sel_hi:[0,1]
	v_pk_mul_f32 v[24:25], v[146:147], v[12:13]
	v_pk_mul_f32 v[26:27], v[148:149], v[10:11]
	v_pk_mul_f32 v[8:9], v[20:21], v[8:9] op_sel_hi:[0,1]
	v_pk_mul_f32 v[6:7], v[20:21], v[6:7] op_sel_hi:[0,1]
	v_pk_mul_f32 v[4:5], v[20:21], v[4:5] op_sel_hi:[0,1]
	v_pk_mul_f32 v[2:3], v[20:21], v[2:3] op_sel_hi:[0,1]
	v_pk_mul_f32 v[20:21], v[142:143], v[16:17]
	v_pk_mul_f32 v[22:23], v[144:145], v[14:15]
	v_exp_f32_e32 v26, v26
	v_exp_f32_e32 v27, v27
	v_exp_f32_e32 v24, v24
	v_exp_f32_e32 v25, v25
	v_exp_f32_e32 v22, v22
	v_exp_f32_e32 v23, v23
	v_exp_f32_e32 v20, v20
	v_exp_f32_e32 v21, v21
	v_pk_add_f32 v[24:25], v[24:25], 1.0 op_sel_hi:[1,0]
	v_pk_add_f32 v[26:27], v[26:27], 1.0 op_sel_hi:[1,0]
	v_pk_add_f32 v[22:23], v[22:23], 1.0 op_sel_hi:[1,0]
	v_pk_add_f32 v[20:21], v[20:21], 1.0 op_sel_hi:[1,0]
	v_rcp_f32_e32 v26, v26
	v_rcp_f32_e32 v27, v27
	v_rcp_f32_e32 v24, v24
	v_rcp_f32_e32 v25, v25
	v_rcp_f32_e32 v22, v22
	v_rcp_f32_e32 v23, v23
	v_rcp_f32_e32 v20, v20
	v_rcp_f32_e32 v21, v21
	s_mov_b32 s98, 0x1e4000
	s_mov_b32 s99, 0
	v_pk_mul_f32 v[2:3], v[10:11], v[2:3]
	v_pk_mul_f32 v[4:5], v[12:13], v[4:5]
	v_pk_mul_f32 v[10:11], v[136:137], v[26:27]
	v_pk_mul_f32 v[12:13], v[134:135], v[24:25]
	v_lshl_add_u64 v[18:19], v[210:211], 0, s[98:99]
	v_pk_mul_f32 v[6:7], v[14:15], v[6:7]
	v_pk_mul_f32 v[8:9], v[16:17], v[8:9]
	v_pk_mul_f32 v[14:15], v[140:141], v[22:23]
	v_pk_mul_f32 v[16:17], v[138:139], v[20:21]
	v_pk_mul_f32 v[12:13], v[4:5], v[12:13]
	v_pk_mul_f32 v[4:5], v[2:3], v[10:11]
	s_mov_b64 s[18:19], -1
	s_andn2_b64 vcc, exec, s[8:9]
	v_pk_mul_f32 v[8:9], v[8:9], v[16:17]
	v_pk_mul_f32 v[6:7], v[6:7], v[14:15]
	s_nop 0
	v_cvt_pk_bf16_f32 v2, v6, v7
	v_cvt_pk_bf16_f32 v3, v8, v9
	v_cvt_pk_bf16_f32 v4, v4, v5
	v_cvt_pk_bf16_f32 v5, v12, v13
	global_store_dwordx4 v[18:19], v[2:5], off
	s_cbranch_vccnz .LBB0_285
	s_and_saveexec_b64 s[8:9], s[6:7]
	s_xor_b64 s[8:9], exec, s[8:9]
	s_lshl_b32 s18, s63, 8
	s_ashr_i32 s19, s18, 31
	v_lshl_add_u64 v[2:3], s[18:19], 2, v[130:131]
	s_movk_i32 s18, 0xfc00
	s_mov_b32 s19, -1
	v_lshl_add_u64 v[2:3], v[2:3], 0, s[18:19]
	s_andn2_saveexec_b64 s[8:9], s[8:9]
	s_lshl_b32 s18, s64, 8
	s_ashr_i32 s19, s18, 31
	v_lshl_add_u64 v[2:3], s[18:19], 2, v[132:133]
	s_or_b64 exec, exec, s[8:9]
	s_lshl_b32 s8, s62, 11
	s_and_b32 s8, s8, 0x800
	s_add_i32 m0, s23, s8
	s_andn2_b64 vcc, exec, s[12:13]
	global_load_lds_dword v[2:3], off
	s_cbranch_vccnz .LBB0_284
	s_barrier
	s_branch .LBB0_284

.LBB0_916:
	s_or_b64 exec, exec, s[4:5]
	s_ashr_i32 s19, s19, 2
	s_and_b32 s22, s19, -16
	v_or_b32_e32 v70, s22, v113
	v_add_u32_e32 v66, s18, v70
	s_and_b32 s18, s19, 0xffffffe0
	v_add_u32_e32 v70, 0x80, v70
	v_or_b32_e32 v71, s18, v110
	s_waitcnt vmcnt(1)
	ds_write_b128 v127, v[6:9]
	s_waitcnt vmcnt(0)
	ds_write_b128 v127, v[2:5] offset:36864
	v_mov_b64_e32 v[2:3], s[6:7]
	s_lshl_b32 s80, s15, 10
	v_sub_u32_e32 v72, v70, v71
	v_mad_i64_i32 v[2:3], s[4:5], v66, s73, v[2:3]
	s_cmp_gt_i32 s14, 0
	v_cmp_gt_u32_e32 vcc, s86, v72
	v_cvt_f32_i32_e32 v72, v72
	s_cselect_b64 s[14:15], -1, 0
	v_cmp_lt_i32_e64 s[4:5], s25, v71
	s_or_b64 s[4:5], s[14:15], s[4:5]
	s_and_b64 vcc, vcc, s[4:5]
	v_cndmask_b32_e32 v129, v248, v72, vcc
	v_xad_u32 v72, v71, -1, v70
	v_cmp_gt_u32_e32 vcc, s86, v72
	v_cvt_f32_i32_e32 v72, v72
	v_cmp_lt_i32_e64 s[4:5], s74, v71
	s_or_b64 s[4:5], s[14:15], s[4:5]
	s_and_b64 vcc, vcc, s[4:5]
	v_cndmask_b32_e32 v130, v248, v72, vcc
	v_or_b32_e32 v72, 2, v71
	v_sub_u32_e32 v73, v70, v72
	v_cmp_lt_i32_e64 s[4:5], s25, v72
	v_cvt_f32_i32_e32 v72, v73
	v_cmp_gt_u32_e32 vcc, s86, v73
	s_or_b64 s[4:5], s[14:15], s[4:5]
	s_and_b64 vcc, vcc, s[4:5]
	v_or_b32_e32 v71, 3, v71
	v_cndmask_b32_e32 v131, v248, v72, vcc
	v_sub_u32_e32 v72, v70, v71
	v_cmp_lt_i32_e64 s[4:5], s25, v71
	v_cvt_f32_i32_e32 v71, v72
	v_cmp_gt_u32_e32 vcc, s86, v72
	s_or_b64 s[4:5], s[14:15], s[4:5]
	s_and_b64 vcc, vcc, s[4:5]
	v_cndmask_b32_e32 v132, v248, v71, vcc
	v_or_b32_e32 v71, s22, v110
	v_or_b32_e32 v72, 16, v71
	v_sub_u32_e32 v73, v70, v72
	v_cmp_lt_i32_e64 s[4:5], s25, v72
	v_cvt_f32_i32_e32 v72, v73
	v_cmp_gt_u32_e32 vcc, s86, v73
	s_or_b64 s[4:5], s[14:15], s[4:5]
	s_and_b64 vcc, vcc, s[4:5]
	v_cndmask_b32_e32 v133, v248, v72, vcc
	v_or_b32_e32 v72, 17, v71
	v_sub_u32_e32 v73, v70, v72
	v_cmp_lt_i32_e64 s[4:5], s25, v72
	v_cvt_f32_i32_e32 v72, v73
	v_cmp_gt_u32_e32 vcc, s86, v73
	s_or_b64 s[4:5], s[14:15], s[4:5]
	s_and_b64 vcc, vcc, s[4:5]
	v_cndmask_b32_e32 v134, v248, v72, vcc
	v_or_b32_e32 v72, 18, v71
	v_sub_u32_e32 v73, v70, v72
	v_cmp_lt_i32_e64 s[4:5], s25, v72
	v_cvt_f32_i32_e32 v72, v73
	v_cmp_gt_u32_e32 vcc, s86, v73
	s_or_b64 s[4:5], s[14:15], s[4:5]
	s_and_b64 vcc, vcc, s[4:5]
	v_or_b32_e32 v71, 19, v71
	v_cndmask_b32_e32 v135, v248, v72, vcc
	v_sub_u32_e32 v72, v70, v71
	v_cmp_lt_i32_e64 s[4:5], s25, v71
	v_cvt_f32_i32_e32 v71, v72
	v_cmp_gt_u32_e32 vcc, s86, v72
	s_or_b64 s[4:5], s[14:15], s[4:5]
	s_and_b64 vcc, vcc, s[4:5]
	v_cndmask_b32_e32 v136, v248, v71, vcc
	v_add_u32_e32 v71, s18, v114
	v_sub_u32_e32 v72, v70, v71
	v_cmp_gt_u32_e32 vcc, s86, v72
	v_cvt_f32_i32_e32 v72, v72
	v_cmp_lt_i32_e64 s[4:5], s25, v71
	s_or_b64 s[4:5], s[14:15], s[4:5]
	s_and_b64 vcc, vcc, s[4:5]
	v_cndmask_b32_e32 v137, v248, v72, vcc
	v_xad_u32 v72, v71, -1, v70
	v_cmp_gt_u32_e32 vcc, s86, v72
	v_cvt_f32_i32_e32 v72, v72
	v_cmp_lt_i32_e64 s[4:5], s74, v71
	s_or_b64 s[4:5], s[14:15], s[4:5]
	s_and_b64 vcc, vcc, s[4:5]
	v_cndmask_b32_e32 v138, v248, v72, vcc
	v_or_b32_e32 v72, 2, v71
	v_sub_u32_e32 v73, v70, v72
	v_cmp_lt_i32_e64 s[4:5], s25, v72
	v_cvt_f32_i32_e32 v72, v73
	v_cmp_gt_u32_e32 vcc, s86, v73
	s_or_b64 s[4:5], s[14:15], s[4:5]
	s_and_b64 vcc, vcc, s[4:5]
	v_or_b32_e32 v71, 3, v71
	v_cndmask_b32_e32 v139, v248, v72, vcc
	v_sub_u32_e32 v72, v70, v71
	v_cmp_lt_i32_e64 s[4:5], s25, v71
	v_cvt_f32_i32_e32 v71, v72
	v_cmp_gt_u32_e32 vcc, s86, v72
	s_or_b64 s[4:5], s[14:15], s[4:5]
	s_and_b64 vcc, vcc, s[4:5]
	v_cndmask_b32_e32 v140, v248, v71, vcc
	v_add_u32_e32 v71, s18, v115
	v_sub_u32_e32 v72, v70, v71
	v_cmp_gt_u32_e32 vcc, s86, v72
	v_cvt_f32_i32_e32 v72, v72
	v_cmp_lt_i32_e64 s[4:5], s25, v71
	s_or_b64 s[4:5], s[14:15], s[4:5]
	s_and_b64 vcc, vcc, s[4:5]
	v_cndmask_b32_e32 v141, v248, v72, vcc
	v_xad_u32 v72, v71, -1, v70
	v_cmp_gt_u32_e32 vcc, s86, v72
	v_cvt_f32_i32_e32 v72, v72
	v_cmp_lt_i32_e64 s[4:5], s74, v71
	s_or_b64 s[4:5], s[14:15], s[4:5]
	s_and_b64 vcc, vcc, s[4:5]
	v_cndmask_b32_e32 v142, v248, v72, vcc
	v_or_b32_e32 v72, 2, v71
	v_sub_u32_e32 v73, v70, v72
	v_cmp_lt_i32_e64 s[4:5], s25, v72
	v_cvt_f32_i32_e32 v72, v73
	v_cmp_gt_u32_e32 vcc, s86, v73
	s_or_b64 s[4:5], s[14:15], s[4:5]
	s_and_b64 vcc, vcc, s[4:5]
	v_or_b32_e32 v71, 3, v71
	v_cndmask_b32_e32 v143, v248, v72, vcc
	v_sub_u32_e32 v72, v70, v71
	v_cmp_lt_i32_e64 s[4:5], s25, v71
	v_cvt_f32_i32_e32 v71, v72
	v_cmp_gt_u32_e32 vcc, s86, v72
	s_or_b64 s[4:5], s[14:15], s[4:5]
	s_and_b64 vcc, vcc, s[4:5]
	v_cndmask_b32_e32 v144, v248, v71, vcc
	v_add_u32_e32 v71, s18, v116
	v_sub_u32_e32 v72, v70, v71
	v_cmp_gt_u32_e32 vcc, s86, v72
	v_cvt_f32_i32_e32 v72, v72
	v_cmp_lt_i32_e64 s[4:5], s25, v71
	s_or_b64 s[4:5], s[14:15], s[4:5]
	s_and_b64 vcc, vcc, s[4:5]
	v_cndmask_b32_e32 v145, v248, v72, vcc
	v_xad_u32 v72, v71, -1, v70
	v_cmp_gt_u32_e32 vcc, s86, v72
	v_cvt_f32_i32_e32 v72, v72
	v_cmp_lt_i32_e64 s[4:5], s74, v71
	s_or_b64 s[4:5], s[14:15], s[4:5]
	s_and_b64 vcc, vcc, s[4:5]
	v_cndmask_b32_e32 v146, v248, v72, vcc
	v_or_b32_e32 v72, 2, v71
	v_sub_u32_e32 v73, v70, v72
	v_cmp_lt_i32_e64 s[4:5], s25, v72
	v_cvt_f32_i32_e32 v72, v73
	v_cmp_gt_u32_e32 vcc, s86, v73
	s_or_b64 s[4:5], s[14:15], s[4:5]
	s_and_b64 vcc, vcc, s[4:5]
	v_or_b32_e32 v71, 3, v71
	v_cndmask_b32_e32 v147, v248, v72, vcc
	v_sub_u32_e32 v72, v70, v71
	v_cmp_lt_i32_e64 s[4:5], s25, v71
	v_cvt_f32_i32_e32 v71, v72
	v_cmp_gt_u32_e32 vcc, s86, v72
	s_or_b64 s[4:5], s[14:15], s[4:5]
	s_and_b64 vcc, vcc, s[4:5]
	v_cndmask_b32_e32 v148, v248, v71, vcc
	v_add_u32_e32 v71, s18, v117
	v_sub_u32_e32 v72, v70, v71
	v_cmp_gt_u32_e32 vcc, s86, v72
	v_cvt_f32_i32_e32 v72, v72
	v_cmp_lt_i32_e64 s[4:5], s25, v71
	s_or_b64 s[4:5], s[14:15], s[4:5]
	s_and_b64 vcc, vcc, s[4:5]
	v_cndmask_b32_e32 v149, v248, v72, vcc
	v_xad_u32 v72, v71, -1, v70
	v_cmp_gt_u32_e32 vcc, s86, v72
	v_cvt_f32_i32_e32 v72, v72
	v_cmp_lt_i32_e64 s[4:5], s74, v71
	s_or_b64 s[4:5], s[14:15], s[4:5]
	s_and_b64 vcc, vcc, s[4:5]
	v_cndmask_b32_e32 v150, v248, v72, vcc
	v_or_b32_e32 v72, 2, v71
	v_sub_u32_e32 v73, v70, v72
	v_cmp_lt_i32_e64 s[4:5], s25, v72
	v_cvt_f32_i32_e32 v72, v73
	v_cmp_gt_u32_e32 vcc, s86, v73
	s_or_b64 s[4:5], s[14:15], s[4:5]
	s_and_b64 vcc, vcc, s[4:5]
	v_or_b32_e32 v71, 3, v71
	v_cndmask_b32_e32 v151, v248, v72, vcc
	v_sub_u32_e32 v72, v70, v71
	v_cmp_lt_i32_e64 s[4:5], s25, v71
	v_cvt_f32_i32_e32 v71, v72
	v_cmp_gt_u32_e32 vcc, s86, v72
	s_or_b64 s[4:5], s[14:15], s[4:5]
	s_and_b64 vcc, vcc, s[4:5]
	v_cndmask_b32_e32 v152, v248, v71, vcc
	v_add_u32_e32 v71, s18, v118
	v_sub_u32_e32 v72, v70, v71
	v_cmp_gt_u32_e32 vcc, s86, v72
	v_cvt_f32_i32_e32 v72, v72
	v_cmp_lt_i32_e64 s[4:5], s25, v71
	s_or_b64 s[4:5], s[14:15], s[4:5]
	s_and_b64 vcc, vcc, s[4:5]
	v_cndmask_b32_e32 v153, v248, v72, vcc
	v_xad_u32 v72, v71, -1, v70
	v_cmp_gt_u32_e32 vcc, s86, v72
	v_cvt_f32_i32_e32 v72, v72
	v_cmp_lt_i32_e64 s[4:5], s74, v71
	s_or_b64 s[4:5], s[14:15], s[4:5]
	s_and_b64 vcc, vcc, s[4:5]
	v_cndmask_b32_e32 v154, v248, v72, vcc
	v_or_b32_e32 v72, 2, v71
	v_sub_u32_e32 v73, v70, v72
	v_cmp_lt_i32_e64 s[4:5], s25, v72
	v_cvt_f32_i32_e32 v72, v73
	v_cmp_gt_u32_e32 vcc, s86, v73
	s_or_b64 s[4:5], s[14:15], s[4:5]
	s_and_b64 vcc, vcc, s[4:5]
	v_or_b32_e32 v71, 3, v71
	v_cndmask_b32_e32 v155, v248, v72, vcc
	v_sub_u32_e32 v72, v70, v71
	v_cmp_lt_i32_e64 s[4:5], s25, v71
	v_cvt_f32_i32_e32 v71, v72
	v_cmp_gt_u32_e32 vcc, s86, v72
	s_or_b64 s[4:5], s[14:15], s[4:5]
	s_and_b64 vcc, vcc, s[4:5]
	v_cndmask_b32_e32 v156, v248, v71, vcc
	v_add_u32_e32 v71, s18, v119
	v_sub_u32_e32 v72, v70, v71
	v_cmp_gt_u32_e32 vcc, s86, v72
	v_cvt_f32_i32_e32 v72, v72
	v_lshl_add_u64 v[2:3], v[2:3], 0, s[80:81]
	v_cmp_lt_i32_e64 s[4:5], s25, v71
	v_lshl_add_u64 v[2:3], v[2:3], 0, v[222:223]
	s_or_b64 s[4:5], s[14:15], s[4:5]
	s_waitcnt lgkmcnt(0)
	s_barrier
	global_load_dwordx4 v[62:65], v[2:3], off
	global_load_dwordx4 v[58:61], v[2:3], off offset:64
	global_load_dwordx4 v[54:57], v[2:3], off offset:128
	global_load_dwordx4 v[50:53], v[2:3], off offset:192
	global_load_dwordx4 v[46:49], v[2:3], off offset:256
	global_load_dwordx4 v[42:45], v[2:3], off offset:320
	global_load_dwordx4 v[38:41], v[2:3], off offset:384
	global_load_dwordx4 v[34:37], v[2:3], off offset:448
	global_load_dwordx4 v[30:33], v[2:3], off offset:512
	global_load_dwordx4 v[26:29], v[2:3], off offset:576
	global_load_dwordx4 v[22:25], v[2:3], off offset:640
	global_load_dwordx4 v[18:21], v[2:3], off offset:704
	global_load_dwordx4 v[14:17], v[2:3], off offset:768
	global_load_dwordx4 v[10:13], v[2:3], off offset:832
	global_load_dwordx4 v[6:9], v[2:3], off offset:896
	s_nop 0
	global_load_dwordx4 v[2:5], v[2:3], off offset:960
	s_and_b64 vcc, vcc, s[4:5]
	v_cndmask_b32_e32 v157, v248, v72, vcc
	v_xad_u32 v72, v71, -1, v70
	v_cmp_gt_u32_e32 vcc, s86, v72
	v_cvt_f32_i32_e32 v72, v72
	v_cmp_lt_i32_e64 s[4:5], s74, v71
	s_or_b64 s[4:5], s[14:15], s[4:5]
	s_and_b64 vcc, vcc, s[4:5]
	v_cndmask_b32_e32 v158, v248, v72, vcc
	v_or_b32_e32 v72, 2, v71
	v_sub_u32_e32 v73, v70, v72
	v_cmp_lt_i32_e64 s[4:5], s25, v72
	v_cvt_f32_i32_e32 v72, v73
	v_cmp_gt_u32_e32 vcc, s86, v73
	s_or_b64 s[4:5], s[14:15], s[4:5]
	s_and_b64 vcc, vcc, s[4:5]
	v_or_b32_e32 v71, 3, v71
	v_cndmask_b32_e32 v159, v248, v72, vcc
	v_sub_u32_e32 v72, v70, v71
	v_cmp_lt_i32_e64 s[4:5], s25, v71
	v_cvt_f32_i32_e32 v71, v72
	v_cmp_gt_u32_e32 vcc, s86, v72
	s_or_b64 s[4:5], s[14:15], s[4:5]
	s_and_b64 vcc, vcc, s[4:5]
	v_cndmask_b32_e32 v160, v248, v71, vcc
	v_add_u32_e32 v71, s18, v120
	v_sub_u32_e32 v72, v70, v71
	v_cmp_gt_u32_e32 vcc, s86, v72
	v_cvt_f32_i32_e32 v72, v72
	v_cmp_lt_i32_e64 s[4:5], s25, v71
	s_or_b64 s[4:5], s[14:15], s[4:5]
	s_and_b64 vcc, vcc, s[4:5]
	v_cndmask_b32_e32 v161, v248, v72, vcc
	v_xad_u32 v72, v71, -1, v70
	v_cmp_gt_u32_e32 vcc, s86, v72
	v_cvt_f32_i32_e32 v72, v72
	v_cmp_lt_i32_e64 s[4:5], s74, v71
	s_or_b64 s[4:5], s[14:15], s[4:5]
	s_and_b64 vcc, vcc, s[4:5]
	v_cndmask_b32_e32 v162, v248, v72, vcc
	v_or_b32_e32 v72, 2, v71
	v_sub_u32_e32 v73, v70, v72
	v_cmp_lt_i32_e64 s[4:5], s25, v72
	v_cvt_f32_i32_e32 v72, v73
	v_cmp_gt_u32_e32 vcc, s86, v73
	s_or_b64 s[4:5], s[14:15], s[4:5]
	s_and_b64 vcc, vcc, s[4:5]
	v_or_b32_e32 v71, 3, v71
	v_cndmask_b32_e32 v163, v248, v72, vcc
	v_sub_u32_e32 v72, v70, v71
	v_cmp_lt_i32_e64 s[4:5], s25, v71
	v_cvt_f32_i32_e32 v71, v72
	v_cmp_gt_u32_e32 vcc, s86, v72
	s_or_b64 s[4:5], s[14:15], s[4:5]
	s_and_b64 vcc, vcc, s[4:5]
	v_cndmask_b32_e32 v164, v248, v71, vcc
	v_add_u32_e32 v71, s18, v121
	v_sub_u32_e32 v72, v70, v71
	v_cmp_gt_u32_e32 vcc, s86, v72
	v_cvt_f32_i32_e32 v72, v72
	v_cmp_lt_i32_e64 s[4:5], s25, v71
	s_or_b64 s[4:5], s[14:15], s[4:5]
	s_and_b64 vcc, vcc, s[4:5]
	v_cndmask_b32_e32 v165, v248, v72, vcc
	v_xad_u32 v72, v71, -1, v70
	v_cmp_gt_u32_e32 vcc, s86, v72
	v_cvt_f32_i32_e32 v72, v72
	v_cmp_lt_i32_e64 s[4:5], s74, v71
	s_or_b64 s[4:5], s[14:15], s[4:5]
	s_and_b64 vcc, vcc, s[4:5]
	v_cndmask_b32_e32 v166, v248, v72, vcc
	v_or_b32_e32 v72, 2, v71
	v_sub_u32_e32 v73, v70, v72
	v_cmp_lt_i32_e64 s[4:5], s25, v72
	v_cvt_f32_i32_e32 v72, v73
	v_cmp_gt_u32_e32 vcc, s86, v73
	s_or_b64 s[4:5], s[14:15], s[4:5]
	v_or_b32_e32 v71, 3, v71
	s_and_b64 vcc, vcc, s[4:5]
	v_sub_u32_e32 v70, v70, v71
	v_cmp_lt_i32_e64 s[4:5], s25, v71
	v_or_b32_e32 v68, s18, v113
	v_or_b32_e32 v69, s18, v111
	v_cndmask_b32_e32 v167, v248, v72, vcc
	v_cmp_gt_u32_e32 vcc, s86, v70
	s_or_b64 s[4:5], s[14:15], s[4:5]
	v_ashrrev_i32_e32 v67, 31, v66
	s_and_b64 vcc, vcc, s[4:5]
	v_cvt_f32_i32_e32 v70, v70
	v_mad_u64_u32 v[100:101], s[4:5], v68, s88, v[92:93]
	v_mad_u64_u32 v[98:99], s[4:5], v69, s88, v[94:95]
	v_lshlrev_b64 v[66:67], 12, v[66:67]
	s_or_b32 s4, s17, 1
	v_lshl_add_u64 v[102:103], v[96:97], 0, v[66:67]
	v_cvt_f32_ubyte0_e32 v66, s4
	v_mul_f32_e32 v66, -0.5, v66
	v_cndmask_b32_e32 v168, v248, v70, vcc
	v_exp_f32_e32 v99, v66
	ds_read_b128 v[66:69], v100
	ds_read_b128 v[70:73], v100 offset:64
	s_waitcnt vmcnt(15) lgkmcnt(1)
	v_mfma_f32_16x16x32_bf16 v[66:69], v[66:69], v[62:65], 0
	v_readlane_b32 s4, v128, 0
	s_add_i32 s9, s9, s16
	s_waitcnt vmcnt(14) lgkmcnt(0)
	v_mfma_f32_16x16x32_bf16 v[66:69], v[70:73], v[58:61], v[66:69]
	ds_read_b128 v[70:73], v100 offset:2304
	ds_read_b128 v[74:77], v100 offset:2368
	s_waitcnt lgkmcnt(1)
	v_mfma_f32_16x16x32_bf16 v[70:73], v[70:73], v[62:65], 0
	s_waitcnt lgkmcnt(0)
	v_mfma_f32_16x16x32_bf16 v[70:73], v[74:77], v[58:61], v[70:73]
	ds_read_b128 v[74:77], v100 offset:4608
	ds_read_b128 v[78:81], v100 offset:4672
	s_waitcnt lgkmcnt(1)
	v_mfma_f32_16x16x32_bf16 v[74:77], v[74:77], v[62:65], 0
	s_waitcnt lgkmcnt(0)
	v_mfma_f32_16x16x32_bf16 v[74:77], v[78:81], v[58:61], v[74:77]
	ds_read_b128 v[78:81], v100 offset:6912
	ds_read_b128 v[82:85], v100 offset:6976
	s_waitcnt lgkmcnt(1)
	v_mfma_f32_16x16x32_bf16 v[78:81], v[78:81], v[62:65], 0
	s_waitcnt lgkmcnt(0)
	v_mfma_f32_16x16x32_bf16 v[78:81], v[82:85], v[58:61], v[78:81]
	ds_read_b128 v[82:85], v100 offset:9216
	ds_read_b128 v[86:89], v100 offset:9280
	s_waitcnt lgkmcnt(1)
	v_mfma_f32_16x16x32_bf16 v[82:85], v[82:85], v[62:65], 0
	s_waitcnt lgkmcnt(0)
	v_mfma_f32_16x16x32_bf16 v[82:85], v[86:89], v[58:61], v[82:85]
	ds_read_b128 v[86:89], v100 offset:11520
	ds_read_b128 v[170:173], v100 offset:11584
	s_waitcnt lgkmcnt(1)
	v_mfma_f32_16x16x32_bf16 v[86:89], v[86:89], v[62:65], 0
	s_waitcnt lgkmcnt(0)
	v_mfma_f32_16x16x32_bf16 v[86:89], v[170:173], v[58:61], v[86:89]
	ds_read_b128 v[170:173], v100 offset:13824
	ds_read_b128 v[174:177], v100 offset:13888
	s_waitcnt lgkmcnt(1)
	v_mfma_f32_16x16x32_bf16 v[170:173], v[170:173], v[62:65], 0
	s_waitcnt lgkmcnt(0)
	v_mfma_f32_16x16x32_bf16 v[170:173], v[174:177], v[58:61], v[170:173]
	ds_read_b128 v[174:177], v100 offset:16128
	ds_read_b128 v[178:181], v100 offset:16192
	s_waitcnt lgkmcnt(1)
	v_mfma_f32_16x16x32_bf16 v[174:177], v[174:177], v[62:65], 0
	s_nop 3
	v_mul_f32_e32 v101, 0x3e38aa3b, v172
	v_mul_f32_e32 v169, 0x3e38aa3b, v173
	s_waitcnt lgkmcnt(0)
	v_mfma_f32_16x16x32_bf16 v[174:177], v[178:181], v[58:61], v[174:177]
	ds_read_b128 v[178:181], v100 offset:18432
	ds_read_b128 v[182:185], v100 offset:18496
	s_waitcnt lgkmcnt(1)
	v_mfma_f32_16x16x32_bf16 v[178:181], v[178:181], v[62:65], 0
	s_nop 3
	v_mul_f32_e32 v172, 0x3e38aa3b, v176
	v_mul_f32_e32 v173, 0x3e38aa3b, v177
	s_waitcnt lgkmcnt(0)
	v_mfma_f32_16x16x32_bf16 v[178:181], v[182:185], v[58:61], v[178:181]
	ds_read_b128 v[182:185], v100 offset:20736
	ds_read_b128 v[186:189], v100 offset:20800
	s_waitcnt lgkmcnt(1)
	v_mfma_f32_16x16x32_bf16 v[62:65], v[182:185], v[62:65], 0
	s_nop 3
	v_mul_f32_e32 v176, 0x3e38aa3b, v180
	v_mul_f32_e32 v177, 0x3e38aa3b, v181
	s_waitcnt lgkmcnt(0)
	v_mfma_f32_16x16x32_bf16 v[58:61], v[186:189], v[58:61], v[62:65]
	s_nop 2
	v_mul_f32_e32 v62, 0xbfb8aa3b, v99
	v_mul_f32_e32 v63, 0x3e38aa3b, v66
	v_mul_f32_e32 v64, 0x3e38aa3b, v67
	v_fmac_f32_e32 v63, v129, v62
	v_fmac_f32_e32 v64, v130, v62
	v_mul_f32_e32 v66, 0x3e38aa3b, v68
	v_mul_f32_e32 v67, 0x3e38aa3b, v69
	v_max3_f32 v65, v63, s75, v64
	v_fmac_f32_e32 v66, v131, v62
	v_fmac_f32_e32 v67, v132, v62
	v_mul_f32_e32 v68, 0x3e38aa3b, v70
	v_mul_f32_e32 v69, 0x3e38aa3b, v71
	v_max3_f32 v65, v65, v66, v67
	v_fmac_f32_e32 v68, v133, v62
	v_fmac_f32_e32 v69, v134, v62
	v_mul_f32_e32 v70, 0x3e38aa3b, v72
	v_mul_f32_e32 v71, 0x3e38aa3b, v73
	v_max3_f32 v65, v65, v68, v69
	v_fmac_f32_e32 v70, v135, v62
	v_fmac_f32_e32 v71, v136, v62
	v_mul_f32_e32 v72, 0x3e38aa3b, v74
	v_mul_f32_e32 v73, 0x3e38aa3b, v75
	v_max3_f32 v65, v65, v70, v71
	v_fmac_f32_e32 v72, v137, v62
	v_fmac_f32_e32 v73, v138, v62
	v_mul_f32_e32 v74, 0x3e38aa3b, v76
	v_mul_f32_e32 v75, 0x3e38aa3b, v77
	v_max3_f32 v65, v65, v72, v73
	v_fmac_f32_e32 v74, v139, v62
	v_fmac_f32_e32 v75, v140, v62
	v_mul_f32_e32 v77, 0x3e38aa3b, v78
	v_mul_f32_e32 v78, 0x3e38aa3b, v79
	v_max3_f32 v65, v65, v74, v75
	v_fmac_f32_e32 v77, v141, v62
	v_fmac_f32_e32 v78, v142, v62
	v_mul_f32_e32 v79, 0x3e38aa3b, v80
	v_mul_f32_e32 v80, 0x3e38aa3b, v81
	v_max3_f32 v65, v65, v77, v78
	v_fmac_f32_e32 v79, v143, v62
	v_fmac_f32_e32 v80, v144, v62
	v_mul_f32_e32 v81, 0x3e38aa3b, v82
	v_mul_f32_e32 v82, 0x3e38aa3b, v83
	v_max3_f32 v65, v65, v79, v80
	v_fmac_f32_e32 v81, v145, v62
	v_fmac_f32_e32 v82, v146, v62
	v_mul_f32_e32 v83, 0x3e38aa3b, v84
	v_mul_f32_e32 v84, 0x3e38aa3b, v85
	v_max3_f32 v65, v65, v81, v82
	v_fmac_f32_e32 v83, v147, v62
	v_fmac_f32_e32 v84, v148, v62
	v_mul_f32_e32 v85, 0x3e38aa3b, v86
	v_mul_f32_e32 v86, 0x3e38aa3b, v87
	v_max3_f32 v65, v65, v83, v84
	v_fmac_f32_e32 v85, v149, v62
	v_fmac_f32_e32 v86, v150, v62
	v_mul_f32_e32 v87, 0x3e38aa3b, v88
	v_mul_f32_e32 v88, 0x3e38aa3b, v89
	v_max3_f32 v65, v65, v85, v86
	v_fmac_f32_e32 v87, v151, v62
	v_fmac_f32_e32 v88, v152, v62
	v_mul_f32_e32 v89, 0x3e38aa3b, v170
	v_mul_f32_e32 v99, 0x3e38aa3b, v171
	v_max3_f32 v65, v65, v87, v88
	v_fmac_f32_e32 v89, v153, v62
	v_fmac_f32_e32 v99, v154, v62
	v_max3_f32 v65, v65, v89, v99
	v_fmac_f32_e32 v101, v155, v62
	v_fmac_f32_e32 v169, v156, v62
	v_mul_f32_e32 v170, 0x3e38aa3b, v174
	v_mul_f32_e32 v171, 0x3e38aa3b, v175
	v_max3_f32 v65, v65, v101, v169
	v_fmac_f32_e32 v170, v157, v62
	v_fmac_f32_e32 v171, v158, v62
	v_max3_f32 v65, v65, v170, v171
	v_fmac_f32_e32 v172, v159, v62
	v_fmac_f32_e32 v173, v160, v62
	v_mul_f32_e32 v174, 0x3e38aa3b, v178
	v_mul_f32_e32 v175, 0x3e38aa3b, v179
	v_max3_f32 v65, v65, v172, v173
	v_fmac_f32_e32 v174, v161, v62
	v_fmac_f32_e32 v175, v162, v62
	v_max3_f32 v65, v65, v174, v175
	v_fmac_f32_e32 v176, v163, v62
	v_fmac_f32_e32 v177, v164, v62
	v_mul_f32_e32 v58, 0x3e38aa3b, v58
	v_mul_f32_e32 v178, 0x3e38aa3b, v59
	v_max3_f32 v65, v65, v176, v177
	v_fmac_f32_e32 v58, v165, v62
	v_fmac_f32_e32 v178, v166, v62
	v_max3_f32 v59, v65, v58, v178
	v_mul_f32_e32 v65, 0x3e38aa3b, v60
	v_mul_f32_e32 v179, 0x3e38aa3b, v61
	v_fmac_f32_e32 v65, v167, v62
	v_fmac_f32_e32 v179, v168, v62
	v_max3_f32 v59, v59, v65, v179
	v_mov_b32_e32 v61, v59
	s_nop 1
	v_permlane16_swap_b32_e32 v61, v59
	v_mul_f32_e32 v60, s4, v249
	s_waitcnt lgkmcnt(0)
	v_max_f32_e32 v61, v61, v61
	v_max_f32_e32 v59, v59, v61
	v_mov_b32_e32 v61, v59
	s_nop 1
	v_permlane32_swap_b32_e32 v61, v59
	s_waitcnt lgkmcnt(0)
	v_max3_f32 v180, v59, v61, v60
	v_sub_f32_e32 v59, v63, v180
	v_exp_f32_e32 v181, v59
	v_sub_f32_e32 v60, v64, v180
	v_exp_f32_e32 v182, v60
	v_sub_f32_e32 v60, v66, v180
	v_exp_f32_e32 v183, v60
	v_sub_f32_e32 v60, v67, v180
	v_exp_f32_e32 v184, v60
	v_sub_f32_e32 v60, v68, v180
	v_add_f32_e32 v59, 0, v181
	v_exp_f32_e32 v185, v60
	v_sub_f32_e32 v60, v69, v180
	v_add_f32_e32 v59, v182, v59
	v_exp_f32_e32 v186, v60
	v_sub_f32_e32 v60, v70, v180
	v_add_f32_e32 v59, v183, v59
	v_exp_f32_e32 v187, v60
	v_sub_f32_e32 v60, v71, v180
	v_add_f32_e32 v59, v184, v59
	v_exp_f32_e32 v188, v60
	v_sub_f32_e32 v60, v72, v180
	v_add_f32_e32 v59, v185, v59
	v_exp_f32_e32 v76, v60
	v_sub_f32_e32 v60, v73, v180
	v_add_f32_e32 v59, v186, v59
	v_exp_f32_e32 v189, v60
	v_sub_f32_e32 v60, v74, v180
	v_add_f32_e32 v59, v187, v59
	v_exp_f32_e32 v190, v60
	v_sub_f32_e32 v60, v75, v180
	v_add_f32_e32 v59, v188, v59
	v_exp_f32_e32 v191, v60
	v_sub_f32_e32 v60, v77, v180
	v_add_f32_e32 v59, v76, v59
	v_exp_f32_e32 v192, v60
	v_sub_f32_e32 v60, v78, v180
	v_add_f32_e32 v59, v189, v59
	v_exp_f32_e32 v193, v60
	v_sub_f32_e32 v60, v79, v180
	v_add_f32_e32 v59, v190, v59
	v_exp_f32_e32 v194, v60
	v_sub_f32_e32 v60, v80, v180
	v_add_f32_e32 v59, v191, v59
	v_exp_f32_e32 v195, v60
	v_sub_f32_e32 v60, v81, v180
	v_add_f32_e32 v59, v192, v59
	v_exp_f32_e32 v70, v60
	v_sub_f32_e32 v60, v82, v180
	v_add_f32_e32 v59, v193, v59
	v_exp_f32_e32 v72, v60
	v_sub_f32_e32 v60, v83, v180
	v_add_f32_e32 v59, v194, v59
	v_exp_f32_e32 v75, v60
	v_sub_f32_e32 v60, v84, v180
	v_add_f32_e32 v59, v195, v59
	v_exp_f32_e32 v78, v60
	v_sub_f32_e32 v60, v85, v180
	v_add_f32_e32 v59, v70, v59
	v_exp_f32_e32 v196, v60
	v_sub_f32_e32 v60, v86, v180
	v_add_f32_e32 v59, v72, v59
	v_exp_f32_e32 v197, v60
	v_sub_f32_e32 v60, v87, v180
	v_add_f32_e32 v59, v75, v59
	v_exp_f32_e32 v198, v60
	v_sub_f32_e32 v60, v88, v180
	v_add_f32_e32 v59, v78, v59
	v_exp_f32_e32 v88, v60
	v_sub_f32_e32 v60, v89, v180
	v_add_f32_e32 v59, v196, v59
	v_exp_f32_e32 v67, v60
	v_sub_f32_e32 v60, v99, v180
	v_add_f32_e32 v59, v197, v59
	v_exp_f32_e32 v68, v60
	v_sub_f32_e32 v60, v101, v180
	v_add_f32_e32 v59, v198, v59
	v_exp_f32_e32 v69, v60
	v_sub_f32_e32 v60, v169, v180
	v_add_f32_e32 v59, v88, v59
	v_exp_f32_e32 v71, v60
	v_sub_f32_e32 v60, v170, v180
	v_add_f32_e32 v59, v67, v59
	v_exp_f32_e32 v73, v60
	v_sub_f32_e32 v60, v171, v180
	v_add_f32_e32 v59, v68, v59
	v_exp_f32_e32 v74, v60
	v_sub_f32_e32 v60, v172, v180
	v_add_f32_e32 v59, v69, v59
	v_exp_f32_e32 v77, v60
	v_sub_f32_e32 v60, v173, v180
	v_add_f32_e32 v59, v71, v59
	v_exp_f32_e32 v79, v60
	v_add_f32_e32 v59, v73, v59
	v_add_f32_e32 v59, v74, v59
	v_add_f32_e32 v59, v77, v59
	v_add_f32_e32 v60, v79, v59
	v_sub_f32_e32 v59, v174, v180
	v_exp_f32_e32 v59, v59
	v_sub_f32_e32 v58, v58, v180
	v_sub_f32_e32 v65, v65, v180
	v_exp_f32_e32 v65, v65
	v_add_f32_e32 v61, v59, v60
	v_sub_f32_e32 v60, v175, v180
	v_exp_f32_e32 v60, v60
	v_sub_f32_e32 v66, v179, v180
	v_exp_f32_e32 v66, v66
	v_add_f32_e32 v62, v60, v61
	v_sub_f32_e32 v61, v176, v180
	v_exp_f32_e32 v61, v61
	s_nop 0
	v_add_f32_e32 v63, v61, v62
	v_sub_f32_e32 v62, v177, v180
	v_exp_f32_e32 v62, v62
	s_nop 0
	v_add_f32_e32 v64, v62, v63
	v_exp_f32_e32 v63, v58
	s_nop 0
	v_add_f32_e32 v58, v63, v64
	v_sub_f32_e32 v64, v178, v180
	v_exp_f32_e32 v64, v64
	s_nop 0
	v_add_f32_e32 v58, v64, v58
	v_add_f32_e32 v58, v65, v58
	v_add_f32_e32 v58, v66, v58
	v_mov_b32_e32 v80, v58
	s_nop 1
	v_permlane16_swap_b32_e32 v80, v58
	s_waitcnt lgkmcnt(0)
	v_add_f32_e32 v58, v58, v80
	v_mov_b32_e32 v80, v58
	s_nop 1
	v_permlane32_swap_b32_e32 v80, v58
	s_waitcnt lgkmcnt(0)
	v_add_f32_e32 v58, v58, v80
	v_fma_f32 v80, s4, v249, -v180
	v_exp_f32_e32 v80, v80
	s_nop 0
	v_add_f32_e32 v58, v80, v58
	v_cvt_pk_bf16_f32 v80, v181, v182
	v_cvt_pk_bf16_f32 v81, v183, v184
	v_cvt_pk_bf16_f32 v82, v185, v186
	v_cvt_pk_bf16_f32 v83, v187, v188
	ds_read_b64_tr_b16 v[86:87], v98 offset:39168
	ds_read_b64_tr_b16 v[84:85], v98 offset:36864
	ds_read_b64_tr_b16 v[170:171], v98 offset:36896
	ds_read_b64_tr_b16 v[172:173], v98 offset:39200
	ds_read_b64_tr_b16 v[174:175], v98 offset:36928
	ds_read_b64_tr_b16 v[176:177], v98 offset:39232
	ds_read_b64_tr_b16 v[178:179], v98 offset:36960
	ds_read_b64_tr_b16 v[180:181], v98 offset:39264
	s_waitcnt lgkmcnt(6)
	v_mfma_f32_16x16x32_bf16 v[84:87], v[84:87], v[80:83], 0
	s_waitcnt lgkmcnt(4)
	v_mfma_f32_16x16x32_bf16 v[170:173], v[170:173], v[80:83], 0
	s_waitcnt lgkmcnt(2)
	v_mfma_f32_16x16x32_bf16 v[174:177], v[174:177], v[80:83], 0
	s_waitcnt lgkmcnt(0)
	v_mfma_f32_16x16x32_bf16 v[80:83], v[178:181], v[80:83], 0
	v_cvt_pk_bf16_f32 v178, v76, v189
	v_cvt_pk_bf16_f32 v179, v190, v191
	v_cvt_pk_bf16_f32 v180, v192, v193
	v_cvt_pk_bf16_f32 v181, v194, v195
	ds_read_b64_tr_b16 v[184:185], v98 offset:43776
	ds_read_b64_tr_b16 v[182:183], v98 offset:41472
	ds_read_b64_tr_b16 v[186:187], v98 offset:41504
	s_waitcnt lgkmcnt(1)
	v_mfma_f32_16x16x32_bf16 v[84:87], v[182:185], v[178:181], v[84:87]
	ds_read_b64_tr_b16 v[188:189], v98 offset:43808
	ds_read_b64_tr_b16 v[182:183], v98 offset:41536
	ds_read_b64_tr_b16 v[184:185], v98 offset:43840
	s_waitcnt lgkmcnt(0)
	v_mfma_f32_16x16x32_bf16 v[174:177], v[182:185], v[178:181], v[174:177]
	ds_read_b64_tr_b16 v[182:183], v98 offset:41568
	ds_read_b64_tr_b16 v[184:185], v98 offset:43872
	v_mfma_f32_16x16x32_bf16 v[170:173], v[186:189], v[178:181], v[170:173]
	s_waitcnt lgkmcnt(0)
	v_mfma_f32_16x16x32_bf16 v[80:83], v[182:185], v[178:181], v[80:83]
	v_cvt_pk_bf16_f32 v178, v70, v72
	v_cvt_pk_bf16_f32 v179, v75, v78
	v_cvt_pk_bf16_f32 v180, v196, v197
	v_cvt_pk_bf16_f32 v181, v198, v88
	ds_read_b64_tr_b16 v[184:185], v98 offset:48384
	ds_read_b64_tr_b16 v[182:183], v98 offset:46080
	ds_read_b64_tr_b16 v[186:187], v98 offset:46112
	s_waitcnt lgkmcnt(1)
	v_mfma_f32_16x16x32_bf16 v[84:87], v[182:185], v[178:181], v[84:87]
	ds_read_b64_tr_b16 v[188:189], v98 offset:48416
	ds_read_b64_tr_b16 v[182:183], v98 offset:46144
	ds_read_b64_tr_b16 v[184:185], v98 offset:48448
	s_waitcnt lgkmcnt(0)
	v_mfma_f32_16x16x32_bf16 v[174:177], v[182:185], v[178:181], v[174:177]
	ds_read_b64_tr_b16 v[182:183], v98 offset:46176
	ds_read_b64_tr_b16 v[184:185], v98 offset:48480
	v_cvt_pk_bf16_f32 v68, v67, v68
	v_cvt_pk_bf16_f32 v69, v69, v71
	v_cvt_pk_bf16_f32 v70, v73, v74
	v_cvt_pk_bf16_f32 v71, v77, v79
	ds_read_b64_tr_b16 v[74:75], v98 offset:52992
	ds_read_b64_tr_b16 v[72:73], v98 offset:50688
	ds_read_b64_tr_b16 v[76:77], v98 offset:50720
	ds_read_b64_tr_b16 v[78:79], v98 offset:53024
	v_mfma_f32_16x16x32_bf16 v[170:173], v[186:189], v[178:181], v[170:173]
	s_waitcnt lgkmcnt(2)
	v_mfma_f32_16x16x32_bf16 v[72:75], v[72:75], v[68:71], v[84:87]
	s_nop 2
	ds_read_b64_tr_b16 v[84:85], v98 offset:50752
	ds_read_b64_tr_b16 v[86:87], v98 offset:53056
	s_waitcnt lgkmcnt(2)
	v_mfma_f32_16x16x32_bf16 v[76:79], v[76:79], v[68:71], v[170:173]
	s_nop 2
	ds_read_b64_tr_b16 v[170:171], v98 offset:50784
	ds_read_b64_tr_b16 v[172:173], v98 offset:53088
	v_cvt_pk_bf16_f32 v60, v59, v60
	v_cvt_pk_bf16_f32 v61, v61, v62
	v_mfma_f32_16x16x32_bf16 v[80:83], v[182:185], v[178:181], v[80:83]
	v_cvt_pk_bf16_f32 v62, v63, v64
	v_cvt_pk_bf16_f32 v63, v65, v66
	v_div_scale_f32 v59, s[4:5], v58, v58, 1.0
	s_waitcnt lgkmcnt(2)
	v_mfma_f32_16x16x32_bf16 v[84:87], v[84:87], v[68:71], v[174:177]
	s_or_b32 s4, s17, 2
	s_waitcnt lgkmcnt(0)
	v_mfma_f32_16x16x32_bf16 v[68:71], v[170:173], v[68:71], v[80:83]
	ds_read_b64_tr_b16 v[66:67], v98 offset:57600
	ds_read_b64_tr_b16 v[64:65], v98 offset:55296
	s_nop 0
	ds_read_b64_tr_b16 v[80:81], v98 offset:55328
	ds_read_b64_tr_b16 v[82:83], v98 offset:57632
	s_waitcnt lgkmcnt(2)
	v_mfma_f32_16x16x32_bf16 v[64:67], v[64:67], v[60:63], v[72:75]
	s_waitcnt lgkmcnt(0)
	v_mfma_f32_16x16x32_bf16 v[72:75], v[80:83], v[60:63], v[76:79]
	s_nop 2
	ds_read_b64_tr_b16 v[76:77], v98 offset:55360
	ds_read_b64_tr_b16 v[78:79], v98 offset:57664
	ds_read_b64_tr_b16 v[80:81], v98 offset:55392
	ds_read_b64_tr_b16 v[82:83], v98 offset:57696
	s_waitcnt lgkmcnt(2)
	v_mfma_f32_16x16x32_bf16 v[76:79], v[76:79], v[60:63], v[84:87]
	s_waitcnt lgkmcnt(0)
	v_mfma_f32_16x16x32_bf16 v[60:63], v[80:83], v[60:63], v[68:71]
	s_nop 2
	v_rcp_f32_e32 v68, v59
	s_nop 0
	v_fma_f32 v69, -v59, v68, 1.0
	v_fmac_f32_e32 v68, v69, v68
	v_div_scale_f32 v69, vcc, 1.0, v58, 1.0
	v_mul_f32_e32 v70, v69, v68
	v_fma_f32 v71, -v59, v70, v69
	v_fmac_f32_e32 v70, v71, v68
	v_fma_f32 v59, -v59, v70, v69
	v_div_fmas_f32 v59, v59, v68, v70
	v_div_fixup_f32 v68, v59, v58, 1.0
	v_pk_mul_f32 v[66:67], v[68:69], v[66:67] op_sel_hi:[0,1]
	v_pk_mul_f32 v[64:65], v[68:69], v[64:65] op_sel_hi:[0,1]
	v_lshl_add_u64 v[58:59], v[102:103], 0, s[80:81]
	v_pk_mul_f32 v[70:71], v[68:69], v[74:75] op_sel_hi:[0,1]
	v_pk_mul_f32 v[72:73], v[68:69], v[72:73] op_sel_hi:[0,1]
	v_cvt_pk_bf16_f32 v64, v64, v65
	v_cvt_pk_bf16_f32 v65, v66, v67
	v_cvt_pk_bf16_f32 v66, v72, v73
	v_cvt_pk_bf16_f32 v67, v70, v71
	global_store_dwordx4 v[58:59], v[64:67], off
	v_pk_mul_f32 v[70:71], v[68:69], v[62:63] op_sel_hi:[0,1]
	v_pk_mul_f32 v[62:63], v[68:69], v[60:61] op_sel_hi:[0,1]
	v_pk_mul_f32 v[66:67], v[68:69], v[76:77] op_sel_hi:[0,1]
	v_cvt_pk_bf16_f32 v60, v66, v67
	v_pk_mul_f32 v[64:65], v[68:69], v[78:79] op_sel_hi:[0,1]
	v_cvt_pk_bf16_f32 v61, v64, v65
	v_cvt_pk_bf16_f32 v62, v62, v63
	v_cvt_pk_bf16_f32 v63, v70, v71
	global_store_dwordx4 v[58:59], v[60:63], off offset:64
	s_nop 1
	v_cvt_f32_ubyte0_e32 v60, s4
	v_mul_f32_e32 v60, -0.5, v60
	v_exp_f32_e32 v88, v60
	ds_read_b128 v[60:63], v100
	ds_read_b128 v[64:67], v100 offset:64
	s_waitcnt vmcnt(15) lgkmcnt(1)
	v_mfma_f32_16x16x32_bf16 v[60:63], v[60:63], v[54:57], 0
	v_readlane_b32 s4, v128, 1
	s_waitcnt vmcnt(14) lgkmcnt(0)
	v_mfma_f32_16x16x32_bf16 v[60:63], v[64:67], v[50:53], v[60:63]
	ds_read_b128 v[64:67], v100 offset:2304
	ds_read_b128 v[68:71], v100 offset:2368
	s_waitcnt lgkmcnt(1)
	v_mfma_f32_16x16x32_bf16 v[64:67], v[64:67], v[54:57], 0
	s_waitcnt lgkmcnt(0)
	v_mfma_f32_16x16x32_bf16 v[64:67], v[68:71], v[50:53], v[64:67]
	ds_read_b128 v[68:71], v100 offset:4608
	ds_read_b128 v[72:75], v100 offset:4672
	s_waitcnt lgkmcnt(1)
	v_mfma_f32_16x16x32_bf16 v[68:71], v[68:71], v[54:57], 0
	s_waitcnt lgkmcnt(0)
	v_mfma_f32_16x16x32_bf16 v[68:71], v[72:75], v[50:53], v[68:71]
	ds_read_b128 v[72:75], v100 offset:6912
	ds_read_b128 v[76:79], v100 offset:6976
	s_waitcnt lgkmcnt(1)
	v_mfma_f32_16x16x32_bf16 v[72:75], v[72:75], v[54:57], 0
	s_waitcnt lgkmcnt(0)
	v_mfma_f32_16x16x32_bf16 v[72:75], v[76:79], v[50:53], v[72:75]
	ds_read_b128 v[76:79], v100 offset:9216
	ds_read_b128 v[80:83], v100 offset:9280
	s_waitcnt lgkmcnt(1)
	v_mfma_f32_16x16x32_bf16 v[76:79], v[76:79], v[54:57], 0
	s_waitcnt lgkmcnt(0)
	v_mfma_f32_16x16x32_bf16 v[76:79], v[80:83], v[50:53], v[76:79]
	ds_read_b128 v[80:83], v100 offset:11520
	ds_read_b128 v[84:87], v100 offset:11584
	s_waitcnt lgkmcnt(1)
	v_mfma_f32_16x16x32_bf16 v[80:83], v[80:83], v[54:57], 0
	s_waitcnt lgkmcnt(0)
	v_mfma_f32_16x16x32_bf16 v[80:83], v[84:87], v[50:53], v[80:83]
	ds_read_b128 v[84:87], v100 offset:13824
	ds_read_b128 v[170:173], v100 offset:13888
	s_waitcnt lgkmcnt(1)
	v_mfma_f32_16x16x32_bf16 v[84:87], v[84:87], v[54:57], 0
	s_waitcnt lgkmcnt(0)
	v_mfma_f32_16x16x32_bf16 v[84:87], v[170:173], v[50:53], v[84:87]
	ds_read_b128 v[170:173], v100 offset:16128
	ds_read_b128 v[174:177], v100 offset:16192
	s_waitcnt lgkmcnt(1)
	v_mfma_f32_16x16x32_bf16 v[170:173], v[170:173], v[54:57], 0
	s_waitcnt lgkmcnt(0)
	v_mfma_f32_16x16x32_bf16 v[170:173], v[174:177], v[50:53], v[170:173]
	ds_read_b128 v[174:177], v100 offset:18432
	ds_read_b128 v[178:181], v100 offset:18496
	s_waitcnt lgkmcnt(1)
	v_mfma_f32_16x16x32_bf16 v[174:177], v[174:177], v[54:57], 0
	s_nop 3
	v_mul_f32_e32 v89, 0x3e38aa3b, v172
	v_mul_f32_e32 v99, 0x3e38aa3b, v173
	s_waitcnt lgkmcnt(0)
	v_mfma_f32_16x16x32_bf16 v[174:177], v[178:181], v[50:53], v[174:177]
	ds_read_b128 v[178:181], v100 offset:20736
	ds_read_b128 v[182:185], v100 offset:20800
	s_waitcnt lgkmcnt(1)
	v_mfma_f32_16x16x32_bf16 v[54:57], v[178:181], v[54:57], 0
	s_nop 3
	v_mul_f32_e32 v101, 0x3e38aa3b, v174
	v_mul_f32_e32 v102, 0x3e38aa3b, v175
	v_mul_f32_e32 v103, 0x3e38aa3b, v176
	s_waitcnt lgkmcnt(0)
	v_mfma_f32_16x16x32_bf16 v[50:53], v[182:185], v[50:53], v[54:57]
	v_mul_f32_e32 v169, 0x3e38aa3b, v177
	s_nop 1
	v_mul_f32_e32 v54, 0xbfb8aa3b, v88
	v_mul_f32_e32 v55, 0x3e38aa3b, v60
	v_mul_f32_e32 v56, 0x3e38aa3b, v61
	v_fmac_f32_e32 v55, v129, v54
	v_fmac_f32_e32 v56, v130, v54
	v_mul_f32_e32 v60, 0x3e38aa3b, v62
	v_mul_f32_e32 v61, 0x3e38aa3b, v63
	v_max3_f32 v57, v55, s75, v56
	v_fmac_f32_e32 v60, v131, v54
	v_fmac_f32_e32 v61, v132, v54
	v_mul_f32_e32 v62, 0x3e38aa3b, v64
	v_mul_f32_e32 v63, 0x3e38aa3b, v65
	v_max3_f32 v57, v57, v60, v61
	v_fmac_f32_e32 v62, v133, v54
	v_fmac_f32_e32 v63, v134, v54
	v_mul_f32_e32 v64, 0x3e38aa3b, v66
	v_mul_f32_e32 v65, 0x3e38aa3b, v67
	v_max3_f32 v57, v57, v62, v63
	v_fmac_f32_e32 v64, v135, v54
	v_fmac_f32_e32 v65, v136, v54
	v_mul_f32_e32 v66, 0x3e38aa3b, v68
	v_mul_f32_e32 v67, 0x3e38aa3b, v69
	v_max3_f32 v57, v57, v64, v65
	v_fmac_f32_e32 v66, v137, v54
	v_fmac_f32_e32 v67, v138, v54
	v_mul_f32_e32 v68, 0x3e38aa3b, v70
	v_mul_f32_e32 v70, 0x3e38aa3b, v71
	v_max3_f32 v57, v57, v66, v67
	v_fmac_f32_e32 v68, v139, v54
	v_fmac_f32_e32 v70, v140, v54
	v_mul_f32_e32 v71, 0x3e38aa3b, v72
	v_mul_f32_e32 v72, 0x3e38aa3b, v73
	v_max3_f32 v57, v57, v68, v70
	v_fmac_f32_e32 v71, v141, v54
	v_fmac_f32_e32 v72, v142, v54
	v_mul_f32_e32 v73, 0x3e38aa3b, v74
	v_mul_f32_e32 v74, 0x3e38aa3b, v75
	v_max3_f32 v57, v57, v71, v72
	v_fmac_f32_e32 v73, v143, v54
	v_fmac_f32_e32 v74, v144, v54
	v_mul_f32_e32 v75, 0x3e38aa3b, v76
	v_mul_f32_e32 v76, 0x3e38aa3b, v77
	v_max3_f32 v57, v57, v73, v74
	v_fmac_f32_e32 v75, v145, v54
	v_fmac_f32_e32 v76, v146, v54
	v_mul_f32_e32 v77, 0x3e38aa3b, v78
	v_mul_f32_e32 v78, 0x3e38aa3b, v79
	v_max3_f32 v57, v57, v75, v76
	v_fmac_f32_e32 v77, v147, v54
	v_fmac_f32_e32 v78, v148, v54
	v_mul_f32_e32 v79, 0x3e38aa3b, v80
	v_mul_f32_e32 v80, 0x3e38aa3b, v81
	v_max3_f32 v57, v57, v77, v78
	v_fmac_f32_e32 v79, v149, v54
	v_fmac_f32_e32 v80, v150, v54
	v_mul_f32_e32 v81, 0x3e38aa3b, v82
	v_mul_f32_e32 v82, 0x3e38aa3b, v83
	v_max3_f32 v57, v57, v79, v80
	v_fmac_f32_e32 v81, v151, v54
	v_fmac_f32_e32 v82, v152, v54
	v_mul_f32_e32 v83, 0x3e38aa3b, v84
	v_mul_f32_e32 v84, 0x3e38aa3b, v85
	v_max3_f32 v57, v57, v81, v82
	v_fmac_f32_e32 v83, v153, v54
	v_fmac_f32_e32 v84, v154, v54
	v_mul_f32_e32 v85, 0x3e38aa3b, v86
	v_mul_f32_e32 v86, 0x3e38aa3b, v87
	v_max3_f32 v57, v57, v83, v84
	v_fmac_f32_e32 v85, v155, v54
	v_fmac_f32_e32 v86, v156, v54
	v_mul_f32_e32 v87, 0x3e38aa3b, v170
	v_mul_f32_e32 v88, 0x3e38aa3b, v171
	v_max3_f32 v57, v57, v85, v86
	v_fmac_f32_e32 v87, v157, v54
	v_fmac_f32_e32 v88, v158, v54
	v_max3_f32 v57, v57, v87, v88
	v_fmac_f32_e32 v89, v159, v54
	v_fmac_f32_e32 v99, v160, v54
	v_max3_f32 v57, v57, v89, v99
	v_fmac_f32_e32 v101, v161, v54
	v_fmac_f32_e32 v102, v162, v54
	v_max3_f32 v57, v57, v101, v102
	v_fmac_f32_e32 v103, v163, v54
	v_fmac_f32_e32 v169, v164, v54
	v_mul_f32_e32 v50, 0x3e38aa3b, v50
	v_mul_f32_e32 v170, 0x3e38aa3b, v51
	v_max3_f32 v57, v57, v103, v169
	v_fmac_f32_e32 v50, v165, v54
	v_fmac_f32_e32 v170, v166, v54
	v_max3_f32 v51, v57, v50, v170
	v_mul_f32_e32 v57, 0x3e38aa3b, v52
	v_mul_f32_e32 v171, 0x3e38aa3b, v53
	v_fmac_f32_e32 v57, v167, v54
	v_fmac_f32_e32 v171, v168, v54
	v_max3_f32 v51, v51, v57, v171
	v_mov_b32_e32 v53, v51
	s_nop 1
	v_permlane16_swap_b32_e32 v53, v51
	v_mul_f32_e32 v52, s4, v249
	s_waitcnt lgkmcnt(0)
	v_max_f32_e32 v53, v53, v53
	v_max_f32_e32 v51, v51, v53
	v_mov_b32_e32 v53, v51
	s_nop 1
	v_permlane32_swap_b32_e32 v53, v51
	s_waitcnt lgkmcnt(0)
	v_max3_f32 v172, v51, v53, v52
	v_sub_f32_e32 v51, v55, v172
	v_exp_f32_e32 v173, v51
	v_sub_f32_e32 v52, v56, v172
	v_exp_f32_e32 v174, v52
	v_sub_f32_e32 v52, v60, v172
	v_exp_f32_e32 v175, v52
	v_sub_f32_e32 v52, v61, v172
	v_exp_f32_e32 v176, v52
	v_sub_f32_e32 v52, v62, v172
	v_add_f32_e32 v51, 0, v173
	v_exp_f32_e32 v177, v52
	v_sub_f32_e32 v52, v63, v172
	v_add_f32_e32 v51, v174, v51
	v_exp_f32_e32 v178, v52
	v_sub_f32_e32 v52, v64, v172
	v_add_f32_e32 v51, v175, v51
	v_exp_f32_e32 v179, v52
	v_sub_f32_e32 v52, v65, v172
	v_add_f32_e32 v51, v176, v51
	v_exp_f32_e32 v180, v52
	v_sub_f32_e32 v52, v66, v172
	v_add_f32_e32 v51, v177, v51
	v_exp_f32_e32 v69, v52
	v_sub_f32_e32 v52, v67, v172
	v_add_f32_e32 v51, v178, v51
	v_exp_f32_e32 v181, v52
	v_sub_f32_e32 v52, v68, v172
	v_add_f32_e32 v51, v179, v51
	v_exp_f32_e32 v182, v52
	v_sub_f32_e32 v52, v70, v172
	v_add_f32_e32 v51, v180, v51
	v_exp_f32_e32 v183, v52
	v_sub_f32_e32 v52, v71, v172
	v_add_f32_e32 v51, v69, v51
	v_exp_f32_e32 v184, v52
	v_sub_f32_e32 v52, v72, v172
	v_add_f32_e32 v51, v181, v51
	v_exp_f32_e32 v185, v52
	v_sub_f32_e32 v52, v73, v172
	v_add_f32_e32 v51, v182, v51
	v_exp_f32_e32 v73, v52
	v_sub_f32_e32 v52, v74, v172
	v_add_f32_e32 v51, v183, v51
	v_exp_f32_e32 v186, v52
	v_sub_f32_e32 v52, v75, v172
	v_add_f32_e32 v51, v184, v51
	v_exp_f32_e32 v64, v52
	v_sub_f32_e32 v52, v76, v172
	v_add_f32_e32 v51, v185, v51
	v_exp_f32_e32 v67, v52
	v_sub_f32_e32 v52, v77, v172
	v_add_f32_e32 v51, v73, v51
	v_exp_f32_e32 v68, v52
	v_sub_f32_e32 v52, v78, v172
	v_add_f32_e32 v51, v186, v51
	v_exp_f32_e32 v72, v52
	v_sub_f32_e32 v52, v79, v172
	v_add_f32_e32 v51, v64, v51
	v_exp_f32_e32 v187, v52
	v_sub_f32_e32 v52, v80, v172
	v_add_f32_e32 v51, v67, v51
	v_exp_f32_e32 v188, v52
	v_sub_f32_e32 v52, v81, v172
	v_add_f32_e32 v51, v68, v51
	v_exp_f32_e32 v189, v52
	v_sub_f32_e32 v52, v82, v172
	v_add_f32_e32 v51, v72, v51
	v_exp_f32_e32 v190, v52
	v_sub_f32_e32 v52, v83, v172
	v_add_f32_e32 v51, v187, v51
	v_exp_f32_e32 v61, v52
	v_sub_f32_e32 v52, v84, v172
	v_add_f32_e32 v51, v188, v51
	v_exp_f32_e32 v62, v52
	v_sub_f32_e32 v52, v85, v172
	v_add_f32_e32 v51, v189, v51
	v_exp_f32_e32 v63, v52
	v_sub_f32_e32 v52, v86, v172
	v_add_f32_e32 v51, v190, v51
	v_exp_f32_e32 v65, v52
	v_sub_f32_e32 v52, v87, v172
	v_add_f32_e32 v51, v61, v51
	v_exp_f32_e32 v66, v52
	v_sub_f32_e32 v52, v88, v172
	v_add_f32_e32 v51, v62, v51
	v_exp_f32_e32 v70, v52
	v_sub_f32_e32 v52, v89, v172
	v_add_f32_e32 v51, v63, v51
	v_exp_f32_e32 v71, v52
	v_sub_f32_e32 v52, v99, v172
	v_add_f32_e32 v51, v65, v51
	v_exp_f32_e32 v99, v52
	v_add_f32_e32 v51, v66, v51
	v_add_f32_e32 v51, v70, v51
	v_add_f32_e32 v51, v71, v51
	v_add_f32_e32 v52, v99, v51
	v_sub_f32_e32 v51, v101, v172
	v_exp_f32_e32 v51, v51
	v_sub_f32_e32 v50, v50, v172
	v_sub_f32_e32 v57, v57, v172
	v_exp_f32_e32 v57, v57
	v_add_f32_e32 v53, v51, v52
	v_sub_f32_e32 v52, v102, v172
	v_exp_f32_e32 v52, v52
	v_sub_f32_e32 v60, v171, v172
	v_exp_f32_e32 v60, v60
	v_add_f32_e32 v54, v52, v53
	v_sub_f32_e32 v53, v103, v172
	v_exp_f32_e32 v53, v53
	s_nop 0
	v_add_f32_e32 v55, v53, v54
	v_sub_f32_e32 v54, v169, v172
	v_exp_f32_e32 v54, v54
	s_nop 0
	v_add_f32_e32 v56, v54, v55
	v_exp_f32_e32 v55, v50
	s_nop 0
	v_add_f32_e32 v50, v55, v56
	v_sub_f32_e32 v56, v170, v172
	v_exp_f32_e32 v56, v56
	s_nop 0
	v_add_f32_e32 v50, v56, v50
	v_add_f32_e32 v50, v57, v50
	v_add_f32_e32 v50, v60, v50
	v_mov_b32_e32 v74, v50
	s_nop 1
	v_permlane16_swap_b32_e32 v74, v50
	s_waitcnt lgkmcnt(0)
	v_add_f32_e32 v50, v50, v74
	v_mov_b32_e32 v74, v50
	s_nop 1
	v_permlane32_swap_b32_e32 v74, v50
	s_waitcnt lgkmcnt(0)
	v_add_f32_e32 v50, v50, v74
	v_fma_f32 v74, s4, v249, -v172
	v_exp_f32_e32 v74, v74
	s_nop 0
	v_add_f32_e32 v50, v74, v50
	v_cvt_pk_bf16_f32 v74, v173, v174
	v_cvt_pk_bf16_f32 v75, v175, v176
	v_cvt_pk_bf16_f32 v76, v177, v178
	v_cvt_pk_bf16_f32 v77, v179, v180
	ds_read_b64_tr_b16 v[80:81], v98 offset:39168
	ds_read_b64_tr_b16 v[78:79], v98 offset:36864
	ds_read_b64_tr_b16 v[82:83], v98 offset:36896
	ds_read_b64_tr_b16 v[84:85], v98 offset:39200
	ds_read_b64_tr_b16 v[86:87], v98 offset:36928
	ds_read_b64_tr_b16 v[88:89], v98 offset:39232
	ds_read_b64_tr_b16 v[170:171], v98 offset:36960
	ds_read_b64_tr_b16 v[172:173], v98 offset:39264
	s_waitcnt lgkmcnt(6)
	v_mfma_f32_16x16x32_bf16 v[78:81], v[78:81], v[74:77], 0
	s_waitcnt lgkmcnt(4)
	v_mfma_f32_16x16x32_bf16 v[82:85], v[82:85], v[74:77], 0
	s_waitcnt lgkmcnt(2)
	v_mfma_f32_16x16x32_bf16 v[86:89], v[86:89], v[74:77], 0
	s_waitcnt lgkmcnt(0)
	v_mfma_f32_16x16x32_bf16 v[74:77], v[170:173], v[74:77], 0
	v_cvt_pk_bf16_f32 v170, v69, v181
	v_cvt_pk_bf16_f32 v171, v182, v183
	v_cvt_pk_bf16_f32 v172, v184, v185
	v_cvt_pk_bf16_f32 v173, v73, v186
	ds_read_b64_tr_b16 v[176:177], v98 offset:43776
	ds_read_b64_tr_b16 v[174:175], v98 offset:41472
	ds_read_b64_tr_b16 v[178:179], v98 offset:41504
	s_waitcnt lgkmcnt(1)
	v_mfma_f32_16x16x32_bf16 v[78:81], v[174:177], v[170:173], v[78:81]
	ds_read_b64_tr_b16 v[180:181], v98 offset:43808
	ds_read_b64_tr_b16 v[174:175], v98 offset:41536
	ds_read_b64_tr_b16 v[176:177], v98 offset:43840
	s_waitcnt lgkmcnt(0)
	v_mfma_f32_16x16x32_bf16 v[86:89], v[174:177], v[170:173], v[86:89]
	ds_read_b64_tr_b16 v[174:175], v98 offset:41568
	ds_read_b64_tr_b16 v[176:177], v98 offset:43872
	v_mfma_f32_16x16x32_bf16 v[82:85], v[178:181], v[170:173], v[82:85]
	s_waitcnt lgkmcnt(0)
	v_mfma_f32_16x16x32_bf16 v[74:77], v[174:177], v[170:173], v[74:77]
	v_cvt_pk_bf16_f32 v170, v64, v67
	v_cvt_pk_bf16_f32 v171, v68, v72
	v_cvt_pk_bf16_f32 v172, v187, v188
	v_cvt_pk_bf16_f32 v173, v189, v190
	ds_read_b64_tr_b16 v[176:177], v98 offset:48384
	ds_read_b64_tr_b16 v[174:175], v98 offset:46080
	ds_read_b64_tr_b16 v[178:179], v98 offset:46112
	s_waitcnt lgkmcnt(1)
	v_mfma_f32_16x16x32_bf16 v[78:81], v[174:177], v[170:173], v[78:81]
	ds_read_b64_tr_b16 v[180:181], v98 offset:48416
	ds_read_b64_tr_b16 v[174:175], v98 offset:46144
	ds_read_b64_tr_b16 v[176:177], v98 offset:48448
	s_waitcnt lgkmcnt(0)
	v_mfma_f32_16x16x32_bf16 v[86:89], v[174:177], v[170:173], v[86:89]
	ds_read_b64_tr_b16 v[174:175], v98 offset:46176
	ds_read_b64_tr_b16 v[176:177], v98 offset:48480
	v_cvt_pk_bf16_f32 v62, v61, v62
	v_cvt_pk_bf16_f32 v63, v63, v65
	s_waitcnt lgkmcnt(0)
	v_mfma_f32_16x16x32_bf16 v[72:75], v[174:177], v[170:173], v[74:77]
	v_cvt_pk_bf16_f32 v64, v66, v70
	v_cvt_pk_bf16_f32 v65, v71, v99
	ds_read_b64_tr_b16 v[68:69], v98 offset:52992
	ds_read_b64_tr_b16 v[66:67], v98 offset:50688
	s_nop 0
	ds_read_b64_tr_b16 v[76:77], v98 offset:50720
	s_waitcnt lgkmcnt(1)
	v_mfma_f32_16x16x32_bf16 v[66:69], v[66:69], v[62:65], v[78:81]
	s_nop 2
	ds_read_b64_tr_b16 v[78:79], v98 offset:53024
	v_mfma_f32_16x16x32_bf16 v[82:85], v[178:181], v[170:173], v[82:85]
	s_waitcnt lgkmcnt(0)
	v_mfma_f32_16x16x32_bf16 v[76:79], v[76:79], v[62:65], v[82:85]
	ds_read_b64_tr_b16 v[80:81], v98 offset:50752
	s_nop 4
	ds_read_b64_tr_b16 v[82:83], v98 offset:53056
	s_waitcnt lgkmcnt(0)
	v_mfma_f32_16x16x32_bf16 v[80:83], v[80:83], v[62:65], v[86:89]
	ds_read_b64_tr_b16 v[84:85], v98 offset:50784
	s_nop 1
	ds_read_b64_tr_b16 v[86:87], v98 offset:53088
	v_cvt_pk_bf16_f32 v52, v51, v52
	v_cvt_pk_bf16_f32 v53, v53, v54
	s_waitcnt lgkmcnt(0)
	v_mfma_f32_16x16x32_bf16 v[62:65], v[84:87], v[62:65], v[72:75]
	v_cvt_pk_bf16_f32 v54, v55, v56
	v_cvt_pk_bf16_f32 v55, v57, v60
	s_nop 2
	ds_read_b64_tr_b16 v[72:73], v98 offset:57600
	ds_read_b64_tr_b16 v[70:71], v98 offset:55296
	ds_read_b64_tr_b16 v[84:85], v98 offset:55328
	ds_read_b64_tr_b16 v[86:87], v98 offset:57632
	v_div_scale_f32 v51, s[4:5], v50, v50, 1.0
	s_waitcnt lgkmcnt(2)
	v_mfma_f32_16x16x32_bf16 v[66:69], v[70:73], v[52:55], v[66:69]
	v_rcp_f32_e32 v56, v51
	s_or_b32 s4, s17, 3
	v_fma_f32 v57, -v51, v56, 1.0
	s_waitcnt lgkmcnt(0)
	v_mfma_f32_16x16x32_bf16 v[70:73], v[84:87], v[52:55], v[76:79]
	ds_read_b64_tr_b16 v[74:75], v98 offset:55360
	s_nop 1
	ds_read_b64_tr_b16 v[76:77], v98 offset:57664
	v_fmac_f32_e32 v56, v57, v56
	v_div_scale_f32 v57, vcc, 1.0, v50, 1.0
	s_waitcnt lgkmcnt(0)
	v_mfma_f32_16x16x32_bf16 v[74:77], v[74:77], v[52:55], v[80:83]
	ds_read_b64_tr_b16 v[78:79], v98 offset:55392
	s_nop 1
	ds_read_b64_tr_b16 v[80:81], v98 offset:57696
	v_mul_f32_e32 v60, v57, v56
	v_fma_f32 v61, -v51, v60, v57
	v_fmac_f32_e32 v60, v61, v56
	v_fma_f32 v51, -v51, v60, v57
	s_waitcnt lgkmcnt(0)
	v_mfma_f32_16x16x32_bf16 v[52:55], v[78:81], v[52:55], v[62:65]
	v_div_fmas_f32 v51, v51, v56, v60
	v_div_fixup_f32 v50, v51, v50, 1.0
	v_pk_mul_f32 v[60:61], v[50:51], v[66:67] op_sel_hi:[0,1]
	v_pk_mul_f32 v[56:57], v[50:51], v[68:69] op_sel_hi:[0,1]
	v_pk_mul_f32 v[62:63], v[50:51], v[70:71] op_sel_hi:[0,1]
	v_cvt_pk_bf16_f32 v60, v60, v61
	v_cvt_pk_bf16_f32 v61, v56, v57
	v_pk_mul_f32 v[64:65], v[50:51], v[72:73] op_sel_hi:[0,1]
	v_cvt_pk_bf16_f32 v62, v62, v63
	v_cvt_pk_bf16_f32 v63, v64, v65
	global_store_dwordx4 v[58:59], v[60:63], off offset:128
	v_pk_mul_f32 v[56:57], v[50:51], v[76:77] op_sel_hi:[0,1]
	v_pk_mul_f32 v[54:55], v[50:51], v[54:55] op_sel_hi:[0,1]
	v_pk_mul_f32 v[60:61], v[50:51], v[74:75] op_sel_hi:[0,1]
	v_pk_mul_f32 v[52:53], v[50:51], v[52:53] op_sel_hi:[0,1]
	v_cvt_pk_bf16_f32 v50, v60, v61
	v_cvt_pk_bf16_f32 v51, v56, v57
	v_cvt_pk_bf16_f32 v52, v52, v53
	v_cvt_pk_bf16_f32 v53, v54, v55
	global_store_dwordx4 v[58:59], v[50:53], off offset:192
	s_nop 1
	v_cvt_f32_ubyte0_e32 v50, s4
	v_mul_f32_e32 v50, -0.5, v50
	v_exp_f32_e32 v88, v50
	ds_read_b128 v[50:53], v100
	ds_read_b128 v[54:57], v100 offset:64
	s_waitcnt vmcnt(15) lgkmcnt(1)
	v_mfma_f32_16x16x32_bf16 v[50:53], v[50:53], v[46:49], 0
	v_readlane_b32 s4, v128, 2
	s_waitcnt vmcnt(14) lgkmcnt(0)
	v_mfma_f32_16x16x32_bf16 v[50:53], v[54:57], v[42:45], v[50:53]
	ds_read_b128 v[54:57], v100 offset:2304
	ds_read_b128 v[60:63], v100 offset:2368
	s_waitcnt lgkmcnt(1)
	v_mfma_f32_16x16x32_bf16 v[54:57], v[54:57], v[46:49], 0
	s_waitcnt lgkmcnt(0)
	v_mfma_f32_16x16x32_bf16 v[54:57], v[60:63], v[42:45], v[54:57]
	ds_read_b128 v[60:63], v100 offset:4608
	ds_read_b128 v[64:67], v100 offset:4672
	s_waitcnt lgkmcnt(1)
	v_mfma_f32_16x16x32_bf16 v[60:63], v[60:63], v[46:49], 0
	s_waitcnt lgkmcnt(0)
	v_mfma_f32_16x16x32_bf16 v[60:63], v[64:67], v[42:45], v[60:63]
	ds_read_b128 v[64:67], v100 offset:6912
	ds_read_b128 v[68:71], v100 offset:6976
	s_waitcnt lgkmcnt(1)
	v_mfma_f32_16x16x32_bf16 v[64:67], v[64:67], v[46:49], 0
	s_waitcnt lgkmcnt(0)
	v_mfma_f32_16x16x32_bf16 v[64:67], v[68:71], v[42:45], v[64:67]
	ds_read_b128 v[68:71], v100 offset:9216
	ds_read_b128 v[72:75], v100 offset:9280
	s_waitcnt lgkmcnt(1)
	v_mfma_f32_16x16x32_bf16 v[68:71], v[68:71], v[46:49], 0
	s_waitcnt lgkmcnt(0)
	v_mfma_f32_16x16x32_bf16 v[68:71], v[72:75], v[42:45], v[68:71]
	ds_read_b128 v[72:75], v100 offset:11520
	ds_read_b128 v[76:79], v100 offset:11584
	s_waitcnt lgkmcnt(1)
	v_mfma_f32_16x16x32_bf16 v[72:75], v[72:75], v[46:49], 0
	s_waitcnt lgkmcnt(0)
	v_mfma_f32_16x16x32_bf16 v[72:75], v[76:79], v[42:45], v[72:75]
	ds_read_b128 v[76:79], v100 offset:13824
	ds_read_b128 v[80:83], v100 offset:13888
	s_waitcnt lgkmcnt(1)
	v_mfma_f32_16x16x32_bf16 v[76:79], v[76:79], v[46:49], 0
	s_waitcnt lgkmcnt(0)
	v_mfma_f32_16x16x32_bf16 v[76:79], v[80:83], v[42:45], v[76:79]
	ds_read_b128 v[80:83], v100 offset:16128
	ds_read_b128 v[84:87], v100 offset:16192
	s_waitcnt lgkmcnt(1)
	v_mfma_f32_16x16x32_bf16 v[80:83], v[80:83], v[46:49], 0
	s_waitcnt lgkmcnt(0)
	v_mfma_f32_16x16x32_bf16 v[80:83], v[84:87], v[42:45], v[80:83]
	ds_read_b128 v[84:87], v100 offset:18432
	ds_read_b128 v[170:173], v100 offset:18496
	s_waitcnt lgkmcnt(1)
	v_mfma_f32_16x16x32_bf16 v[84:87], v[84:87], v[46:49], 0
	s_waitcnt lgkmcnt(0)
	v_mfma_f32_16x16x32_bf16 v[84:87], v[170:173], v[42:45], v[84:87]
	ds_read_b128 v[170:173], v100 offset:20736
	ds_read_b128 v[174:177], v100 offset:20800
	s_waitcnt lgkmcnt(1)
	v_mfma_f32_16x16x32_bf16 v[46:49], v[170:173], v[46:49], 0
	s_waitcnt lgkmcnt(0)
	v_mfma_f32_16x16x32_bf16 v[42:45], v[174:177], v[42:45], v[46:49]
	s_nop 5
	v_mul_f32_e32 v46, 0xbfb8aa3b, v88
	v_mul_f32_e32 v47, 0x3e38aa3b, v50
	v_mul_f32_e32 v48, 0x3e38aa3b, v51
	v_fmac_f32_e32 v47, v129, v46
	v_fmac_f32_e32 v48, v130, v46
	v_mul_f32_e32 v50, 0x3e38aa3b, v52
	v_mul_f32_e32 v51, 0x3e38aa3b, v53
	v_max3_f32 v49, v47, s75, v48
	v_fmac_f32_e32 v50, v131, v46
	v_fmac_f32_e32 v51, v132, v46
	v_mul_f32_e32 v52, 0x3e38aa3b, v54
	v_mul_f32_e32 v53, 0x3e38aa3b, v55
	v_max3_f32 v49, v49, v50, v51
	v_fmac_f32_e32 v52, v133, v46
	v_fmac_f32_e32 v53, v134, v46
	v_mul_f32_e32 v54, 0x3e38aa3b, v56
	v_mul_f32_e32 v55, 0x3e38aa3b, v57
	v_max3_f32 v49, v49, v52, v53
	v_fmac_f32_e32 v54, v135, v46
	v_fmac_f32_e32 v55, v136, v46
	v_mul_f32_e32 v56, 0x3e38aa3b, v60
	v_mul_f32_e32 v57, 0x3e38aa3b, v61
	v_max3_f32 v49, v49, v54, v55
	v_fmac_f32_e32 v56, v137, v46
	v_fmac_f32_e32 v57, v138, v46
	v_mul_f32_e32 v60, 0x3e38aa3b, v62
	v_mul_f32_e32 v62, 0x3e38aa3b, v63
	v_max3_f32 v49, v49, v56, v57
	v_fmac_f32_e32 v60, v139, v46
	v_fmac_f32_e32 v62, v140, v46
	v_mul_f32_e32 v63, 0x3e38aa3b, v64
	v_mul_f32_e32 v64, 0x3e38aa3b, v65
	v_max3_f32 v49, v49, v60, v62
	v_fmac_f32_e32 v63, v141, v46
	v_fmac_f32_e32 v64, v142, v46
	v_mul_f32_e32 v65, 0x3e38aa3b, v66
	v_mul_f32_e32 v66, 0x3e38aa3b, v67
	v_max3_f32 v49, v49, v63, v64
	v_fmac_f32_e32 v65, v143, v46
	v_fmac_f32_e32 v66, v144, v46
	v_mul_f32_e32 v67, 0x3e38aa3b, v68
	v_mul_f32_e32 v68, 0x3e38aa3b, v69
	v_max3_f32 v49, v49, v65, v66
	v_fmac_f32_e32 v67, v145, v46
	v_fmac_f32_e32 v68, v146, v46
	v_mul_f32_e32 v69, 0x3e38aa3b, v70
	v_mul_f32_e32 v70, 0x3e38aa3b, v71
	v_max3_f32 v49, v49, v67, v68
	v_fmac_f32_e32 v69, v147, v46
	v_fmac_f32_e32 v70, v148, v46
	v_mul_f32_e32 v71, 0x3e38aa3b, v72
	v_mul_f32_e32 v72, 0x3e38aa3b, v73
	v_max3_f32 v49, v49, v69, v70
	v_fmac_f32_e32 v71, v149, v46
	v_fmac_f32_e32 v72, v150, v46
	v_mul_f32_e32 v73, 0x3e38aa3b, v74
	v_mul_f32_e32 v74, 0x3e38aa3b, v75
	v_max3_f32 v49, v49, v71, v72
	v_fmac_f32_e32 v73, v151, v46
	v_fmac_f32_e32 v74, v152, v46
	v_mul_f32_e32 v75, 0x3e38aa3b, v76
	v_mul_f32_e32 v76, 0x3e38aa3b, v77
	v_max3_f32 v49, v49, v73, v74
	v_fmac_f32_e32 v75, v153, v46
	v_fmac_f32_e32 v76, v154, v46
	v_mul_f32_e32 v77, 0x3e38aa3b, v78
	v_mul_f32_e32 v78, 0x3e38aa3b, v79
	v_max3_f32 v49, v49, v75, v76
	v_fmac_f32_e32 v77, v155, v46
	v_fmac_f32_e32 v78, v156, v46
	v_mul_f32_e32 v79, 0x3e38aa3b, v80
	v_mul_f32_e32 v80, 0x3e38aa3b, v81
	v_max3_f32 v49, v49, v77, v78
	v_fmac_f32_e32 v79, v157, v46
	v_fmac_f32_e32 v80, v158, v46
	v_mul_f32_e32 v81, 0x3e38aa3b, v82
	v_mul_f32_e32 v82, 0x3e38aa3b, v83
	v_max3_f32 v49, v49, v79, v80
	v_fmac_f32_e32 v81, v159, v46
	v_fmac_f32_e32 v82, v160, v46
	v_mul_f32_e32 v83, 0x3e38aa3b, v84
	v_mul_f32_e32 v84, 0x3e38aa3b, v85
	v_max3_f32 v49, v49, v81, v82
	v_fmac_f32_e32 v83, v161, v46
	v_fmac_f32_e32 v84, v162, v46
	v_mul_f32_e32 v85, 0x3e38aa3b, v86
	v_mul_f32_e32 v86, 0x3e38aa3b, v87
	v_max3_f32 v49, v49, v83, v84
	v_fmac_f32_e32 v85, v163, v46
	v_fmac_f32_e32 v86, v164, v46
	v_mul_f32_e32 v42, 0x3e38aa3b, v42
	v_mul_f32_e32 v87, 0x3e38aa3b, v43
	v_max3_f32 v49, v49, v85, v86
	v_fmac_f32_e32 v42, v165, v46
	v_fmac_f32_e32 v87, v166, v46
	v_max3_f32 v43, v49, v42, v87
	v_mul_f32_e32 v49, 0x3e38aa3b, v44
	v_mul_f32_e32 v88, 0x3e38aa3b, v45
	v_fmac_f32_e32 v49, v167, v46
	v_fmac_f32_e32 v88, v168, v46
	v_max3_f32 v43, v43, v49, v88
	v_mov_b32_e32 v45, v43
	s_nop 1
	v_permlane16_swap_b32_e32 v45, v43
	v_mul_f32_e32 v44, s4, v249
	s_waitcnt lgkmcnt(0)
	v_max_f32_e32 v45, v45, v45
	v_max_f32_e32 v43, v43, v45
	v_mov_b32_e32 v45, v43
	s_nop 1
	v_permlane32_swap_b32_e32 v45, v43
	s_waitcnt lgkmcnt(0)
	v_max3_f32 v89, v43, v45, v44
	v_sub_f32_e32 v43, v47, v89
	v_exp_f32_e32 v99, v43
	v_sub_f32_e32 v44, v48, v89
	v_exp_f32_e32 v101, v44
	v_sub_f32_e32 v44, v50, v89
	v_exp_f32_e32 v102, v44
	v_sub_f32_e32 v44, v51, v89
	v_exp_f32_e32 v103, v44
	v_sub_f32_e32 v44, v52, v89
	v_add_f32_e32 v43, 0, v99
	v_exp_f32_e32 v169, v44
	v_sub_f32_e32 v44, v53, v89
	v_add_f32_e32 v43, v101, v43
	v_exp_f32_e32 v170, v44
	v_sub_f32_e32 v44, v54, v89
	v_add_f32_e32 v43, v102, v43
	v_exp_f32_e32 v171, v44
	v_sub_f32_e32 v44, v55, v89
	v_add_f32_e32 v43, v103, v43
	v_exp_f32_e32 v172, v44
	v_sub_f32_e32 v44, v56, v89
	v_add_f32_e32 v43, v169, v43
	v_exp_f32_e32 v61, v44
	v_sub_f32_e32 v44, v57, v89
	v_add_f32_e32 v43, v170, v43
	v_exp_f32_e32 v173, v44
	v_sub_f32_e32 v44, v60, v89
	v_add_f32_e32 v43, v171, v43
	v_exp_f32_e32 v174, v44
	v_sub_f32_e32 v44, v62, v89
	v_add_f32_e32 v43, v172, v43
	v_exp_f32_e32 v175, v44
	v_sub_f32_e32 v44, v63, v89
	v_add_f32_e32 v43, v61, v43
	v_exp_f32_e32 v176, v44
	v_sub_f32_e32 v44, v64, v89
	v_add_f32_e32 v43, v173, v43
	v_exp_f32_e32 v177, v44
	v_sub_f32_e32 v44, v65, v89
	v_add_f32_e32 v43, v174, v43
	v_exp_f32_e32 v65, v44
	v_sub_f32_e32 v44, v66, v89
	v_add_f32_e32 v43, v175, v43
	v_exp_f32_e32 v178, v44
	v_sub_f32_e32 v44, v67, v89
	v_add_f32_e32 v43, v176, v43
	v_exp_f32_e32 v54, v44
	v_sub_f32_e32 v44, v68, v89
	v_add_f32_e32 v43, v177, v43
	v_exp_f32_e32 v57, v44
	v_sub_f32_e32 v44, v69, v89
	v_add_f32_e32 v43, v65, v43
	v_exp_f32_e32 v60, v44
	v_sub_f32_e32 v44, v70, v89
	v_add_f32_e32 v43, v178, v43
	v_exp_f32_e32 v64, v44
	v_sub_f32_e32 v44, v71, v89
	v_add_f32_e32 v43, v54, v43
	v_exp_f32_e32 v179, v44
	v_sub_f32_e32 v44, v72, v89
	v_add_f32_e32 v43, v57, v43
	v_exp_f32_e32 v180, v44
	v_sub_f32_e32 v44, v73, v89
	v_add_f32_e32 v43, v60, v43
	v_exp_f32_e32 v181, v44
	v_sub_f32_e32 v44, v74, v89
	v_add_f32_e32 v43, v64, v43
	v_exp_f32_e32 v182, v44
	v_sub_f32_e32 v44, v75, v89
	v_add_f32_e32 v43, v179, v43
	v_exp_f32_e32 v51, v44
	v_sub_f32_e32 v44, v76, v89
	v_add_f32_e32 v43, v180, v43
	v_exp_f32_e32 v52, v44
	v_sub_f32_e32 v44, v77, v89
	v_add_f32_e32 v43, v181, v43
	v_exp_f32_e32 v53, v44
	v_sub_f32_e32 v44, v78, v89
	v_add_f32_e32 v43, v182, v43
	v_exp_f32_e32 v55, v44
	v_sub_f32_e32 v44, v79, v89
	v_add_f32_e32 v43, v51, v43
	v_exp_f32_e32 v56, v44
	v_sub_f32_e32 v44, v80, v89
	v_add_f32_e32 v43, v52, v43
	v_exp_f32_e32 v62, v44
	v_sub_f32_e32 v44, v81, v89
	v_add_f32_e32 v43, v53, v43
	v_exp_f32_e32 v63, v44
	v_sub_f32_e32 v44, v82, v89
	v_add_f32_e32 v43, v55, v43
	v_exp_f32_e32 v183, v44
	v_add_f32_e32 v43, v56, v43
	v_add_f32_e32 v43, v62, v43
	v_add_f32_e32 v43, v63, v43
	v_add_f32_e32 v44, v183, v43
	v_sub_f32_e32 v43, v83, v89
	v_exp_f32_e32 v43, v43
	v_sub_f32_e32 v42, v42, v89
	v_sub_f32_e32 v49, v49, v89
	v_exp_f32_e32 v49, v49
	v_add_f32_e32 v45, v43, v44
	v_sub_f32_e32 v44, v84, v89
	v_exp_f32_e32 v44, v44
	v_sub_f32_e32 v50, v88, v89
	v_exp_f32_e32 v50, v50
	v_add_f32_e32 v46, v44, v45
	v_sub_f32_e32 v45, v85, v89
	v_exp_f32_e32 v45, v45
	s_nop 0
	v_add_f32_e32 v47, v45, v46
	v_sub_f32_e32 v46, v86, v89
	v_exp_f32_e32 v46, v46
	s_nop 0
	v_add_f32_e32 v48, v46, v47
	v_exp_f32_e32 v47, v42
	s_nop 0
	v_add_f32_e32 v42, v47, v48
	v_sub_f32_e32 v48, v87, v89
	v_exp_f32_e32 v48, v48
	s_nop 0
	v_add_f32_e32 v42, v48, v42
	v_add_f32_e32 v42, v49, v42
	v_add_f32_e32 v42, v50, v42
	v_mov_b32_e32 v66, v42
	s_nop 1
	v_permlane16_swap_b32_e32 v66, v42
	s_waitcnt lgkmcnt(0)
	v_add_f32_e32 v42, v42, v66
	v_mov_b32_e32 v66, v42
	s_nop 1
	v_permlane32_swap_b32_e32 v66, v42
	s_waitcnt lgkmcnt(0)
	v_add_f32_e32 v42, v42, v66
	v_fma_f32 v66, s4, v249, -v89
	v_exp_f32_e32 v66, v66
	s_nop 0
	v_add_f32_e32 v42, v66, v42
	v_cvt_pk_bf16_f32 v66, v99, v101
	v_cvt_pk_bf16_f32 v67, v102, v103
	v_cvt_pk_bf16_f32 v68, v169, v170
	v_cvt_pk_bf16_f32 v69, v171, v172
	ds_read_b64_tr_b16 v[72:73], v98 offset:39168
	ds_read_b64_tr_b16 v[70:71], v98 offset:36864
	ds_read_b64_tr_b16 v[74:75], v98 offset:36896
	ds_read_b64_tr_b16 v[76:77], v98 offset:39200
	ds_read_b64_tr_b16 v[78:79], v98 offset:36928
	ds_read_b64_tr_b16 v[80:81], v98 offset:39232
	ds_read_b64_tr_b16 v[82:83], v98 offset:36960
	ds_read_b64_tr_b16 v[84:85], v98 offset:39264
	s_waitcnt lgkmcnt(6)
	v_mfma_f32_16x16x32_bf16 v[70:73], v[70:73], v[66:69], 0
	s_waitcnt lgkmcnt(4)
	v_mfma_f32_16x16x32_bf16 v[74:77], v[74:77], v[66:69], 0
	s_waitcnt lgkmcnt(2)
	v_mfma_f32_16x16x32_bf16 v[78:81], v[78:81], v[66:69], 0
	s_waitcnt lgkmcnt(0)
	v_mfma_f32_16x16x32_bf16 v[66:69], v[82:85], v[66:69], 0
	v_cvt_pk_bf16_f32 v82, v61, v173
	v_cvt_pk_bf16_f32 v83, v174, v175
	v_cvt_pk_bf16_f32 v84, v176, v177
	v_cvt_pk_bf16_f32 v85, v65, v178
	ds_read_b64_tr_b16 v[88:89], v98 offset:43776
	ds_read_b64_tr_b16 v[86:87], v98 offset:41472
	ds_read_b64_tr_b16 v[170:171], v98 offset:41504
	s_waitcnt lgkmcnt(1)
	v_mfma_f32_16x16x32_bf16 v[70:73], v[86:89], v[82:85], v[70:73]
	ds_read_b64_tr_b16 v[172:173], v98 offset:43808
	ds_read_b64_tr_b16 v[86:87], v98 offset:41536
	ds_read_b64_tr_b16 v[88:89], v98 offset:43840
	s_waitcnt lgkmcnt(0)
	v_mfma_f32_16x16x32_bf16 v[78:81], v[86:89], v[82:85], v[78:81]
	ds_read_b64_tr_b16 v[86:87], v98 offset:41568
	ds_read_b64_tr_b16 v[88:89], v98 offset:43872
	v_mfma_f32_16x16x32_bf16 v[74:77], v[170:173], v[82:85], v[74:77]
	s_waitcnt lgkmcnt(0)
	v_mfma_f32_16x16x32_bf16 v[66:69], v[86:89], v[82:85], v[66:69]
	v_cvt_pk_bf16_f32 v82, v54, v57
	v_cvt_pk_bf16_f32 v83, v60, v64
	v_cvt_pk_bf16_f32 v84, v179, v180
	v_cvt_pk_bf16_f32 v85, v181, v182
	ds_read_b64_tr_b16 v[88:89], v98 offset:48384
	ds_read_b64_tr_b16 v[86:87], v98 offset:46080
	ds_read_b64_tr_b16 v[170:171], v98 offset:46112
	s_waitcnt lgkmcnt(1)
	v_mfma_f32_16x16x32_bf16 v[70:73], v[86:89], v[82:85], v[70:73]
	ds_read_b64_tr_b16 v[172:173], v98 offset:48416
	ds_read_b64_tr_b16 v[86:87], v98 offset:46144
	ds_read_b64_tr_b16 v[88:89], v98 offset:48448
	s_waitcnt lgkmcnt(0)
	v_mfma_f32_16x16x32_bf16 v[78:81], v[86:89], v[82:85], v[78:81]
	ds_read_b64_tr_b16 v[86:87], v98 offset:46176
	ds_read_b64_tr_b16 v[88:89], v98 offset:48480
	v_cvt_pk_bf16_f32 v52, v51, v52
	v_cvt_pk_bf16_f32 v53, v53, v55
	s_waitcnt lgkmcnt(0)
	v_mfma_f32_16x16x32_bf16 v[64:67], v[86:89], v[82:85], v[66:69]
	v_cvt_pk_bf16_f32 v54, v56, v62
	v_cvt_pk_bf16_f32 v55, v63, v183
	ds_read_b64_tr_b16 v[62:63], v98 offset:52992
	ds_read_b64_tr_b16 v[60:61], v98 offset:50688
	s_nop 0
	ds_read_b64_tr_b16 v[68:69], v98 offset:50720
	s_waitcnt lgkmcnt(1)
	v_mfma_f32_16x16x32_bf16 v[60:63], v[60:63], v[52:55], v[70:73]
	s_nop 2
	ds_read_b64_tr_b16 v[70:71], v98 offset:53024
	v_mfma_f32_16x16x32_bf16 v[74:77], v[170:173], v[82:85], v[74:77]
	s_waitcnt lgkmcnt(0)
	v_mfma_f32_16x16x32_bf16 v[68:71], v[68:71], v[52:55], v[74:77]
	ds_read_b64_tr_b16 v[72:73], v98 offset:50752
	s_nop 4
	ds_read_b64_tr_b16 v[74:75], v98 offset:53056
	s_waitcnt lgkmcnt(0)
	v_mfma_f32_16x16x32_bf16 v[72:75], v[72:75], v[52:55], v[78:81]
	ds_read_b64_tr_b16 v[76:77], v98 offset:50784
	s_nop 1
	ds_read_b64_tr_b16 v[78:79], v98 offset:53088
	v_cvt_pk_bf16_f32 v44, v43, v44
	v_cvt_pk_bf16_f32 v45, v45, v46
	s_waitcnt lgkmcnt(0)
	v_mfma_f32_16x16x32_bf16 v[52:55], v[76:79], v[52:55], v[64:67]
	v_cvt_pk_bf16_f32 v46, v47, v48
	v_cvt_pk_bf16_f32 v47, v49, v50
	ds_read_b64_tr_b16 v[50:51], v98 offset:57600
	ds_read_b64_tr_b16 v[48:49], v98 offset:55296
	s_nop 0
	ds_read_b64_tr_b16 v[64:65], v98 offset:55328
	ds_read_b64_tr_b16 v[66:67], v98 offset:57632
	s_waitcnt lgkmcnt(2)
	v_mfma_f32_16x16x32_bf16 v[48:51], v[48:51], v[44:47], v[60:63]
	v_div_scale_f32 v43, s[4:5], v42, v42, 1.0
	s_or_b32 s4, s17, 4
	s_waitcnt lgkmcnt(0)
	v_mfma_f32_16x16x32_bf16 v[60:63], v[64:67], v[44:47], v[68:71]
	ds_read_b64_tr_b16 v[64:65], v98 offset:55360
	ds_read_b64_tr_b16 v[66:67], v98 offset:57664
	s_nop 0
	ds_read_b64_tr_b16 v[68:69], v98 offset:55392
	ds_read_b64_tr_b16 v[70:71], v98 offset:57696
	s_waitcnt lgkmcnt(2)
	v_mfma_f32_16x16x32_bf16 v[64:67], v[64:67], v[44:47], v[72:75]
	s_waitcnt lgkmcnt(0)
	v_mfma_f32_16x16x32_bf16 v[44:47], v[68:71], v[44:47], v[52:55]
	s_nop 2
	v_rcp_f32_e32 v52, v43
	s_nop 0
	v_fma_f32 v53, -v43, v52, 1.0
	v_fmac_f32_e32 v52, v53, v52
	v_div_scale_f32 v53, vcc, 1.0, v42, 1.0
	v_mul_f32_e32 v54, v53, v52
	v_fma_f32 v55, -v43, v54, v53
	v_fmac_f32_e32 v54, v55, v52
	v_fma_f32 v43, -v43, v54, v53
	v_div_fmas_f32 v43, v43, v52, v54
	v_div_fixup_f32 v42, v43, v42, 1.0
	v_pk_mul_f32 v[50:51], v[42:43], v[50:51] op_sel_hi:[0,1]
	v_pk_mul_f32 v[48:49], v[42:43], v[48:49] op_sel_hi:[0,1]
	v_pk_mul_f32 v[52:53], v[42:43], v[62:63] op_sel_hi:[0,1]
	v_pk_mul_f32 v[54:55], v[42:43], v[60:61] op_sel_hi:[0,1]
	v_cvt_pk_bf16_f32 v48, v48, v49
	v_cvt_pk_bf16_f32 v49, v50, v51
	v_cvt_pk_bf16_f32 v50, v54, v55
	v_cvt_pk_bf16_f32 v51, v52, v53
	global_store_dwordx4 v[58:59], v[48:51], off offset:256
	v_pk_mul_f32 v[46:47], v[42:43], v[46:47] op_sel_hi:[0,1]
	v_pk_mul_f32 v[44:45], v[42:43], v[44:45] op_sel_hi:[0,1]
	v_pk_mul_f32 v[48:49], v[42:43], v[66:67] op_sel_hi:[0,1]
	v_pk_mul_f32 v[50:51], v[42:43], v[64:65] op_sel_hi:[0,1]
	v_cvt_pk_bf16_f32 v42, v50, v51
	v_cvt_pk_bf16_f32 v43, v48, v49
	v_cvt_pk_bf16_f32 v44, v44, v45
	v_cvt_pk_bf16_f32 v45, v46, v47
	global_store_dwordx4 v[58:59], v[42:45], off offset:320
	s_nop 1
	v_cvt_f32_ubyte0_e32 v42, s4
	v_mul_f32_e32 v42, -0.5, v42
	v_exp_f32_e32 v88, v42
	ds_read_b128 v[42:45], v100
	ds_read_b128 v[46:49], v100 offset:64
	s_waitcnt vmcnt(15) lgkmcnt(1)
	v_mfma_f32_16x16x32_bf16 v[42:45], v[42:45], v[38:41], 0
	v_readlane_b32 s4, v128, 3
	s_waitcnt vmcnt(14) lgkmcnt(0)
	v_mfma_f32_16x16x32_bf16 v[42:45], v[46:49], v[34:37], v[42:45]
	ds_read_b128 v[46:49], v100 offset:2304
	ds_read_b128 v[50:53], v100 offset:2368
	s_waitcnt lgkmcnt(1)
	v_mfma_f32_16x16x32_bf16 v[46:49], v[46:49], v[38:41], 0
	s_waitcnt lgkmcnt(0)
	v_mfma_f32_16x16x32_bf16 v[46:49], v[50:53], v[34:37], v[46:49]
	ds_read_b128 v[50:53], v100 offset:4608
	ds_read_b128 v[54:57], v100 offset:4672
	s_waitcnt lgkmcnt(1)
	v_mfma_f32_16x16x32_bf16 v[50:53], v[50:53], v[38:41], 0
	s_waitcnt lgkmcnt(0)
	v_mfma_f32_16x16x32_bf16 v[50:53], v[54:57], v[34:37], v[50:53]
	ds_read_b128 v[54:57], v100 offset:6912
	ds_read_b128 v[60:63], v100 offset:6976
	s_waitcnt lgkmcnt(1)
	v_mfma_f32_16x16x32_bf16 v[54:57], v[54:57], v[38:41], 0
	s_waitcnt lgkmcnt(0)
	v_mfma_f32_16x16x32_bf16 v[54:57], v[60:63], v[34:37], v[54:57]
	ds_read_b128 v[60:63], v100 offset:9216
	ds_read_b128 v[64:67], v100 offset:9280
	s_waitcnt lgkmcnt(1)
	v_mfma_f32_16x16x32_bf16 v[60:63], v[60:63], v[38:41], 0
	s_waitcnt lgkmcnt(0)
	v_mfma_f32_16x16x32_bf16 v[60:63], v[64:67], v[34:37], v[60:63]
	ds_read_b128 v[64:67], v100 offset:11520
	ds_read_b128 v[68:71], v100 offset:11584
	s_waitcnt lgkmcnt(1)
	v_mfma_f32_16x16x32_bf16 v[64:67], v[64:67], v[38:41], 0
	s_waitcnt lgkmcnt(0)
	v_mfma_f32_16x16x32_bf16 v[64:67], v[68:71], v[34:37], v[64:67]
	ds_read_b128 v[68:71], v100 offset:13824
	ds_read_b128 v[72:75], v100 offset:13888
	s_waitcnt lgkmcnt(1)
	v_mfma_f32_16x16x32_bf16 v[68:71], v[68:71], v[38:41], 0
	s_waitcnt lgkmcnt(0)
	v_mfma_f32_16x16x32_bf16 v[68:71], v[72:75], v[34:37], v[68:71]
	ds_read_b128 v[72:75], v100 offset:16128
	ds_read_b128 v[76:79], v100 offset:16192
	s_waitcnt lgkmcnt(1)
	v_mfma_f32_16x16x32_bf16 v[72:75], v[72:75], v[38:41], 0
	s_waitcnt lgkmcnt(0)
	v_mfma_f32_16x16x32_bf16 v[72:75], v[76:79], v[34:37], v[72:75]
	ds_read_b128 v[76:79], v100 offset:18432
	ds_read_b128 v[80:83], v100 offset:18496
	s_waitcnt lgkmcnt(1)
	v_mfma_f32_16x16x32_bf16 v[76:79], v[76:79], v[38:41], 0
	s_waitcnt lgkmcnt(0)
	v_mfma_f32_16x16x32_bf16 v[76:79], v[80:83], v[34:37], v[76:79]
	ds_read_b128 v[80:83], v100 offset:20736
	ds_read_b128 v[84:87], v100 offset:20800
	s_waitcnt lgkmcnt(1)
	v_mfma_f32_16x16x32_bf16 v[38:41], v[80:83], v[38:41], 0
	s_waitcnt lgkmcnt(0)
	v_mfma_f32_16x16x32_bf16 v[34:37], v[84:87], v[34:37], v[38:41]
	s_nop 5
	v_mul_f32_e32 v38, 0xbfb8aa3b, v88
	v_mul_f32_e32 v39, 0x3e38aa3b, v42
	v_mul_f32_e32 v40, 0x3e38aa3b, v43
	v_fmac_f32_e32 v39, v129, v38
	v_fmac_f32_e32 v40, v130, v38
	v_mul_f32_e32 v42, 0x3e38aa3b, v44
	v_mul_f32_e32 v43, 0x3e38aa3b, v45
	v_max3_f32 v41, v39, s75, v40
	v_fmac_f32_e32 v42, v131, v38
	v_fmac_f32_e32 v43, v132, v38
	v_mul_f32_e32 v44, 0x3e38aa3b, v46
	v_mul_f32_e32 v45, 0x3e38aa3b, v47
	v_max3_f32 v41, v41, v42, v43
	v_fmac_f32_e32 v44, v133, v38
	v_fmac_f32_e32 v45, v134, v38
	v_mul_f32_e32 v46, 0x3e38aa3b, v48
	v_mul_f32_e32 v47, 0x3e38aa3b, v49
	v_max3_f32 v41, v41, v44, v45
	v_fmac_f32_e32 v46, v135, v38
	v_fmac_f32_e32 v47, v136, v38
	v_mul_f32_e32 v48, 0x3e38aa3b, v50
	v_mul_f32_e32 v49, 0x3e38aa3b, v51
	v_max3_f32 v41, v41, v46, v47
	v_fmac_f32_e32 v48, v137, v38
	v_fmac_f32_e32 v49, v138, v38
	v_mul_f32_e32 v50, 0x3e38aa3b, v52
	v_mul_f32_e32 v52, 0x3e38aa3b, v53
	v_max3_f32 v41, v41, v48, v49
	v_fmac_f32_e32 v50, v139, v38
	v_fmac_f32_e32 v52, v140, v38
	v_mul_f32_e32 v53, 0x3e38aa3b, v54
	v_mul_f32_e32 v54, 0x3e38aa3b, v55
	v_max3_f32 v41, v41, v50, v52
	v_fmac_f32_e32 v53, v141, v38
	v_fmac_f32_e32 v54, v142, v38
	v_mul_f32_e32 v55, 0x3e38aa3b, v56
	v_mul_f32_e32 v56, 0x3e38aa3b, v57
	v_max3_f32 v41, v41, v53, v54
	v_fmac_f32_e32 v55, v143, v38
	v_fmac_f32_e32 v56, v144, v38
	v_mul_f32_e32 v57, 0x3e38aa3b, v60
	v_mul_f32_e32 v60, 0x3e38aa3b, v61
	v_max3_f32 v41, v41, v55, v56
	v_fmac_f32_e32 v57, v145, v38
	v_fmac_f32_e32 v60, v146, v38
	v_mul_f32_e32 v61, 0x3e38aa3b, v62
	v_mul_f32_e32 v62, 0x3e38aa3b, v63
	v_max3_f32 v41, v41, v57, v60
	v_fmac_f32_e32 v61, v147, v38
	v_fmac_f32_e32 v62, v148, v38
	v_mul_f32_e32 v63, 0x3e38aa3b, v64
	v_mul_f32_e32 v64, 0x3e38aa3b, v65
	v_max3_f32 v41, v41, v61, v62
	v_fmac_f32_e32 v63, v149, v38
	v_fmac_f32_e32 v64, v150, v38
	v_mul_f32_e32 v65, 0x3e38aa3b, v66
	v_mul_f32_e32 v66, 0x3e38aa3b, v67
	v_max3_f32 v41, v41, v63, v64
	v_fmac_f32_e32 v65, v151, v38
	v_fmac_f32_e32 v66, v152, v38
	v_mul_f32_e32 v67, 0x3e38aa3b, v68
	v_mul_f32_e32 v68, 0x3e38aa3b, v69
	v_max3_f32 v41, v41, v65, v66
	v_fmac_f32_e32 v67, v153, v38
	v_fmac_f32_e32 v68, v154, v38
	v_mul_f32_e32 v69, 0x3e38aa3b, v70
	v_mul_f32_e32 v70, 0x3e38aa3b, v71
	v_max3_f32 v41, v41, v67, v68
	v_fmac_f32_e32 v69, v155, v38
	v_fmac_f32_e32 v70, v156, v38
	v_mul_f32_e32 v71, 0x3e38aa3b, v72
	v_mul_f32_e32 v72, 0x3e38aa3b, v73
	v_max3_f32 v41, v41, v69, v70
	v_fmac_f32_e32 v71, v157, v38
	v_fmac_f32_e32 v72, v158, v38
	v_mul_f32_e32 v73, 0x3e38aa3b, v74
	v_mul_f32_e32 v74, 0x3e38aa3b, v75
	v_max3_f32 v41, v41, v71, v72
	v_fmac_f32_e32 v73, v159, v38
	v_fmac_f32_e32 v74, v160, v38
	v_mul_f32_e32 v75, 0x3e38aa3b, v76
	v_mul_f32_e32 v76, 0x3e38aa3b, v77
	v_max3_f32 v41, v41, v73, v74
	v_fmac_f32_e32 v75, v161, v38
	v_fmac_f32_e32 v76, v162, v38
	v_mul_f32_e32 v77, 0x3e38aa3b, v78
	v_mul_f32_e32 v78, 0x3e38aa3b, v79
	v_max3_f32 v41, v41, v75, v76
	v_fmac_f32_e32 v77, v163, v38
	v_fmac_f32_e32 v78, v164, v38
	v_mul_f32_e32 v34, 0x3e38aa3b, v34
	v_mul_f32_e32 v79, 0x3e38aa3b, v35
	v_max3_f32 v41, v41, v77, v78
	v_fmac_f32_e32 v34, v165, v38
	v_fmac_f32_e32 v79, v166, v38
	v_max3_f32 v35, v41, v34, v79
	v_mul_f32_e32 v41, 0x3e38aa3b, v36
	v_mul_f32_e32 v80, 0x3e38aa3b, v37
	v_fmac_f32_e32 v41, v167, v38
	v_fmac_f32_e32 v80, v168, v38
	v_max3_f32 v35, v35, v41, v80
	v_mov_b32_e32 v37, v35
	s_nop 1
	v_permlane16_swap_b32_e32 v37, v35
	v_mul_f32_e32 v36, s4, v249
	s_waitcnt lgkmcnt(0)
	v_max_f32_e32 v37, v37, v37
	v_max_f32_e32 v35, v35, v37
	v_mov_b32_e32 v37, v35
	s_nop 1
	v_permlane32_swap_b32_e32 v37, v35
	s_waitcnt lgkmcnt(0)
	v_max3_f32 v81, v35, v37, v36
	v_sub_f32_e32 v35, v39, v81
	v_exp_f32_e32 v82, v35
	v_sub_f32_e32 v36, v40, v81
	v_exp_f32_e32 v83, v36
	v_sub_f32_e32 v36, v42, v81
	v_exp_f32_e32 v84, v36
	v_sub_f32_e32 v36, v43, v81
	v_exp_f32_e32 v85, v36
	v_sub_f32_e32 v36, v44, v81
	v_add_f32_e32 v35, 0, v82
	v_exp_f32_e32 v86, v36
	v_sub_f32_e32 v36, v45, v81
	v_add_f32_e32 v35, v83, v35
	v_exp_f32_e32 v87, v36
	v_sub_f32_e32 v36, v46, v81
	v_add_f32_e32 v35, v84, v35
	v_exp_f32_e32 v88, v36
	v_sub_f32_e32 v36, v47, v81
	v_add_f32_e32 v35, v85, v35
	v_exp_f32_e32 v89, v36
	v_sub_f32_e32 v36, v48, v81
	v_add_f32_e32 v35, v86, v35
	v_exp_f32_e32 v51, v36
	v_sub_f32_e32 v36, v49, v81
	v_add_f32_e32 v35, v87, v35
	v_exp_f32_e32 v99, v36
	v_sub_f32_e32 v36, v50, v81
	v_add_f32_e32 v35, v88, v35
	v_exp_f32_e32 v101, v36
	v_sub_f32_e32 v36, v52, v81
	v_add_f32_e32 v35, v89, v35
	v_exp_f32_e32 v102, v36
	v_sub_f32_e32 v36, v53, v81
	v_add_f32_e32 v35, v51, v35
	v_exp_f32_e32 v103, v36
	v_sub_f32_e32 v36, v54, v81
	v_add_f32_e32 v35, v99, v35
	v_exp_f32_e32 v169, v36
	v_sub_f32_e32 v36, v55, v81
	v_add_f32_e32 v35, v101, v35
	v_exp_f32_e32 v55, v36
	v_sub_f32_e32 v36, v56, v81
	v_add_f32_e32 v35, v102, v35
	v_exp_f32_e32 v56, v36
	v_sub_f32_e32 v36, v57, v81
	v_add_f32_e32 v35, v103, v35
	v_exp_f32_e32 v46, v36
	v_sub_f32_e32 v36, v60, v81
	v_add_f32_e32 v35, v169, v35
	v_exp_f32_e32 v49, v36
	v_sub_f32_e32 v36, v61, v81
	v_add_f32_e32 v35, v55, v35
	v_exp_f32_e32 v50, v36
	v_sub_f32_e32 v36, v62, v81
	v_add_f32_e32 v35, v56, v35
	v_exp_f32_e32 v54, v36
	v_sub_f32_e32 v36, v63, v81
	v_add_f32_e32 v35, v46, v35
	v_exp_f32_e32 v57, v36
	v_sub_f32_e32 v36, v64, v81
	v_add_f32_e32 v35, v49, v35
	v_exp_f32_e32 v170, v36
	v_sub_f32_e32 v36, v65, v81
	v_add_f32_e32 v35, v50, v35
	v_exp_f32_e32 v171, v36
	v_sub_f32_e32 v36, v66, v81
	v_add_f32_e32 v35, v54, v35
	v_exp_f32_e32 v172, v36
	v_sub_f32_e32 v36, v67, v81
	v_add_f32_e32 v35, v57, v35
	v_exp_f32_e32 v43, v36
	v_sub_f32_e32 v36, v68, v81
	v_add_f32_e32 v35, v170, v35
	v_exp_f32_e32 v44, v36
	v_sub_f32_e32 v36, v69, v81
	v_add_f32_e32 v35, v171, v35
	v_exp_f32_e32 v45, v36
	v_sub_f32_e32 v36, v70, v81
	v_add_f32_e32 v35, v172, v35
	v_exp_f32_e32 v47, v36
	v_sub_f32_e32 v36, v71, v81
	v_add_f32_e32 v35, v43, v35
	v_exp_f32_e32 v48, v36
	v_sub_f32_e32 v36, v72, v81
	v_add_f32_e32 v35, v44, v35
	v_exp_f32_e32 v52, v36
	v_sub_f32_e32 v36, v73, v81
	v_add_f32_e32 v35, v45, v35
	v_exp_f32_e32 v53, v36
	v_sub_f32_e32 v36, v74, v81
	v_add_f32_e32 v35, v47, v35
	v_exp_f32_e32 v173, v36
	v_add_f32_e32 v35, v48, v35
	v_add_f32_e32 v35, v52, v35
	v_add_f32_e32 v35, v53, v35
	v_add_f32_e32 v36, v173, v35
	v_sub_f32_e32 v35, v75, v81
	v_exp_f32_e32 v35, v35
	v_sub_f32_e32 v34, v34, v81
	v_sub_f32_e32 v41, v41, v81
	v_exp_f32_e32 v41, v41
	v_add_f32_e32 v37, v35, v36
	v_sub_f32_e32 v36, v76, v81
	v_exp_f32_e32 v36, v36
	v_sub_f32_e32 v42, v80, v81
	v_exp_f32_e32 v42, v42
	v_add_f32_e32 v38, v36, v37
	v_sub_f32_e32 v37, v77, v81
	v_exp_f32_e32 v37, v37
	s_nop 0
	v_add_f32_e32 v39, v37, v38
	v_sub_f32_e32 v38, v78, v81
	v_exp_f32_e32 v38, v38
	s_nop 0
	v_add_f32_e32 v40, v38, v39
	v_exp_f32_e32 v39, v34
	s_nop 0
	v_add_f32_e32 v34, v39, v40
	v_sub_f32_e32 v40, v79, v81
	v_exp_f32_e32 v40, v40
	s_nop 0
	v_add_f32_e32 v34, v40, v34
	v_add_f32_e32 v34, v41, v34
	v_add_f32_e32 v34, v42, v34
	v_mov_b32_e32 v60, v34
	s_nop 1
	v_permlane16_swap_b32_e32 v60, v34
	s_waitcnt lgkmcnt(0)
	v_add_f32_e32 v34, v34, v60
	v_mov_b32_e32 v60, v34
	s_nop 1
	v_permlane32_swap_b32_e32 v60, v34
	s_waitcnt lgkmcnt(0)
	v_add_f32_e32 v34, v34, v60
	v_fma_f32 v60, s4, v249, -v81
	v_exp_f32_e32 v60, v60
	s_nop 0
	v_add_f32_e32 v34, v60, v34
	v_cvt_pk_bf16_f32 v60, v82, v83
	v_cvt_pk_bf16_f32 v61, v84, v85
	v_cvt_pk_bf16_f32 v62, v86, v87
	v_cvt_pk_bf16_f32 v63, v88, v89
	ds_read_b64_tr_b16 v[66:67], v98 offset:39168
	ds_read_b64_tr_b16 v[64:65], v98 offset:36864
	ds_read_b64_tr_b16 v[68:69], v98 offset:36896
	ds_read_b64_tr_b16 v[70:71], v98 offset:39200
	ds_read_b64_tr_b16 v[72:73], v98 offset:36928
	ds_read_b64_tr_b16 v[74:75], v98 offset:39232
	ds_read_b64_tr_b16 v[76:77], v98 offset:36960
	ds_read_b64_tr_b16 v[78:79], v98 offset:39264
	s_waitcnt lgkmcnt(6)
	v_mfma_f32_16x16x32_bf16 v[64:67], v[64:67], v[60:63], 0
	s_waitcnt lgkmcnt(4)
	v_mfma_f32_16x16x32_bf16 v[68:71], v[68:71], v[60:63], 0
	s_waitcnt lgkmcnt(2)
	v_mfma_f32_16x16x32_bf16 v[72:75], v[72:75], v[60:63], 0
	s_waitcnt lgkmcnt(0)
	v_mfma_f32_16x16x32_bf16 v[60:63], v[76:79], v[60:63], 0
	v_cvt_pk_bf16_f32 v76, v51, v99
	v_cvt_pk_bf16_f32 v77, v101, v102
	v_cvt_pk_bf16_f32 v78, v103, v169
	v_cvt_pk_bf16_f32 v79, v55, v56
	ds_read_b64_tr_b16 v[82:83], v98 offset:43776
	ds_read_b64_tr_b16 v[80:81], v98 offset:41472
	ds_read_b64_tr_b16 v[84:85], v98 offset:41504
	s_waitcnt lgkmcnt(1)
	v_mfma_f32_16x16x32_bf16 v[64:67], v[80:83], v[76:79], v[64:67]
	ds_read_b64_tr_b16 v[86:87], v98 offset:43808
	ds_read_b64_tr_b16 v[80:81], v98 offset:41536
	ds_read_b64_tr_b16 v[82:83], v98 offset:43840
	s_waitcnt lgkmcnt(0)
	v_mfma_f32_16x16x32_bf16 v[72:75], v[80:83], v[76:79], v[72:75]
	ds_read_b64_tr_b16 v[80:81], v98 offset:41568
	ds_read_b64_tr_b16 v[82:83], v98 offset:43872
	v_mfma_f32_16x16x32_bf16 v[68:71], v[84:87], v[76:79], v[68:71]
	s_waitcnt lgkmcnt(0)
	v_mfma_f32_16x16x32_bf16 v[60:63], v[80:83], v[76:79], v[60:63]
	v_cvt_pk_bf16_f32 v76, v46, v49
	v_cvt_pk_bf16_f32 v77, v50, v54
	v_cvt_pk_bf16_f32 v78, v57, v170
	v_cvt_pk_bf16_f32 v79, v171, v172
	ds_read_b64_tr_b16 v[56:57], v98 offset:48384
	ds_read_b64_tr_b16 v[54:55], v98 offset:46080
	ds_read_b64_tr_b16 v[80:81], v98 offset:46112
	ds_read_b64_tr_b16 v[82:83], v98 offset:48416
	s_waitcnt lgkmcnt(2)
	v_mfma_f32_16x16x32_bf16 v[54:57], v[54:57], v[76:79], v[64:67]
	s_waitcnt lgkmcnt(0)
	v_mfma_f32_16x16x32_bf16 v[64:67], v[80:83], v[76:79], v[68:71]
	s_nop 2
	ds_read_b64_tr_b16 v[68:69], v98 offset:46144
	ds_read_b64_tr_b16 v[70:71], v98 offset:48448
	s_waitcnt lgkmcnt(0)
	v_mfma_f32_16x16x32_bf16 v[68:71], v[68:71], v[76:79], v[72:75]
	s_nop 2
	ds_read_b64_tr_b16 v[72:73], v98 offset:46176
	ds_read_b64_tr_b16 v[74:75], v98 offset:48480
	v_cvt_pk_bf16_f32 v44, v43, v44
	v_cvt_pk_bf16_f32 v45, v45, v47
	v_cvt_pk_bf16_f32 v46, v48, v52
	v_cvt_pk_bf16_f32 v47, v53, v173
	ds_read_b64_tr_b16 v[50:51], v98 offset:52992
	ds_read_b64_tr_b16 v[48:49], v98 offset:50688
	ds_read_b64_tr_b16 v[52:53], v98 offset:50720
	s_waitcnt lgkmcnt(1)
	v_mfma_f32_16x16x32_bf16 v[48:51], v[48:51], v[44:47], v[54:57]
	s_nop 2
	ds_read_b64_tr_b16 v[54:55], v98 offset:53024
	s_waitcnt lgkmcnt(0)
	v_mfma_f32_16x16x32_bf16 v[52:55], v[52:55], v[44:47], v[64:67]
	s_nop 2
	ds_read_b64_tr_b16 v[64:65], v98 offset:50752
	ds_read_b64_tr_b16 v[66:67], v98 offset:53056
	s_waitcnt lgkmcnt(0)
	v_mfma_f32_16x16x32_bf16 v[64:67], v[64:67], v[44:47], v[68:71]
	s_nop 2
	ds_read_b64_tr_b16 v[68:69], v98 offset:50784
	ds_read_b64_tr_b16 v[70:71], v98 offset:53088
	v_cvt_pk_bf16_f32 v36, v35, v36
	v_cvt_pk_bf16_f32 v37, v37, v38
	v_mfma_f32_16x16x32_bf16 v[60:63], v[72:75], v[76:79], v[60:63]
	v_cvt_pk_bf16_f32 v38, v39, v40
	v_cvt_pk_bf16_f32 v39, v41, v42
	v_div_scale_f32 v35, s[4:5], v34, v34, 1.0
	s_waitcnt lgkmcnt(0)
	v_mfma_f32_16x16x32_bf16 v[44:47], v[68:71], v[44:47], v[60:63]
	ds_read_b64_tr_b16 v[42:43], v98 offset:57600
	ds_read_b64_tr_b16 v[40:41], v98 offset:55296
	s_nop 2
	ds_read_b64_tr_b16 v[60:61], v98 offset:55328
	ds_read_b64_tr_b16 v[62:63], v98 offset:57632
	s_or_b32 s4, s17, 5
	s_waitcnt lgkmcnt(2)
	v_mfma_f32_16x16x32_bf16 v[40:43], v[40:43], v[36:39], v[48:51]
	s_waitcnt lgkmcnt(0)
	v_mfma_f32_16x16x32_bf16 v[48:51], v[60:63], v[36:39], v[52:55]
	s_nop 2
	ds_read_b64_tr_b16 v[52:53], v98 offset:55360
	ds_read_b64_tr_b16 v[54:55], v98 offset:57664
	ds_read_b64_tr_b16 v[60:61], v98 offset:55392
	ds_read_b64_tr_b16 v[62:63], v98 offset:57696
	s_waitcnt lgkmcnt(2)
	v_mfma_f32_16x16x32_bf16 v[52:55], v[52:55], v[36:39], v[64:67]
	s_waitcnt lgkmcnt(0)
	v_mfma_f32_16x16x32_bf16 v[36:39], v[60:63], v[36:39], v[44:47]
	s_nop 2
	v_rcp_f32_e32 v44, v35
	s_nop 0
	v_fma_f32 v45, -v35, v44, 1.0
	v_fmac_f32_e32 v44, v45, v44
	v_div_scale_f32 v45, vcc, 1.0, v34, 1.0
	v_mul_f32_e32 v46, v45, v44
	v_fma_f32 v47, -v35, v46, v45
	v_fmac_f32_e32 v46, v47, v44
	v_fma_f32 v35, -v35, v46, v45
	v_div_fmas_f32 v35, v35, v44, v46
	v_div_fixup_f32 v34, v35, v34, 1.0
	v_pk_mul_f32 v[42:43], v[34:35], v[42:43] op_sel_hi:[0,1]
	v_pk_mul_f32 v[40:41], v[34:35], v[40:41] op_sel_hi:[0,1]
	v_pk_mul_f32 v[44:45], v[34:35], v[50:51] op_sel_hi:[0,1]
	v_pk_mul_f32 v[46:47], v[34:35], v[48:49] op_sel_hi:[0,1]
	v_cvt_pk_bf16_f32 v40, v40, v41
	v_cvt_pk_bf16_f32 v41, v42, v43
	v_cvt_pk_bf16_f32 v42, v46, v47
	v_cvt_pk_bf16_f32 v43, v44, v45
	global_store_dwordx4 v[58:59], v[40:43], off offset:384
	v_pk_mul_f32 v[38:39], v[34:35], v[38:39] op_sel_hi:[0,1]
	v_pk_mul_f32 v[36:37], v[34:35], v[36:37] op_sel_hi:[0,1]
	v_pk_mul_f32 v[40:41], v[34:35], v[54:55] op_sel_hi:[0,1]
	v_pk_mul_f32 v[42:43], v[34:35], v[52:53] op_sel_hi:[0,1]
	v_cvt_pk_bf16_f32 v34, v42, v43
	v_cvt_pk_bf16_f32 v35, v40, v41
	v_cvt_pk_bf16_f32 v36, v36, v37
	v_cvt_pk_bf16_f32 v37, v38, v39
	global_store_dwordx4 v[58:59], v[34:37], off offset:448
	s_nop 1
	v_cvt_f32_ubyte0_e32 v34, s4
	v_mul_f32_e32 v34, -0.5, v34
	v_exp_f32_e32 v80, v34
	ds_read_b128 v[34:37], v100
	ds_read_b128 v[38:41], v100 offset:64
	s_waitcnt vmcnt(15) lgkmcnt(1)
	v_mfma_f32_16x16x32_bf16 v[34:37], v[34:37], v[30:33], 0
	v_readlane_b32 s4, v128, 4
	s_waitcnt vmcnt(14) lgkmcnt(0)
	v_mfma_f32_16x16x32_bf16 v[34:37], v[38:41], v[26:29], v[34:37]
	ds_read_b128 v[38:41], v100 offset:2304
	ds_read_b128 v[42:45], v100 offset:2368
	s_waitcnt lgkmcnt(1)
	v_mfma_f32_16x16x32_bf16 v[38:41], v[38:41], v[30:33], 0
	s_waitcnt lgkmcnt(0)
	v_mfma_f32_16x16x32_bf16 v[38:41], v[42:45], v[26:29], v[38:41]
	ds_read_b128 v[42:45], v100 offset:4608
	ds_read_b128 v[46:49], v100 offset:4672
	s_waitcnt lgkmcnt(1)
	v_mfma_f32_16x16x32_bf16 v[42:45], v[42:45], v[30:33], 0
	s_waitcnt lgkmcnt(0)
	v_mfma_f32_16x16x32_bf16 v[42:45], v[46:49], v[26:29], v[42:45]
	ds_read_b128 v[46:49], v100 offset:6912
	ds_read_b128 v[50:53], v100 offset:6976
	s_waitcnt lgkmcnt(1)
	v_mfma_f32_16x16x32_bf16 v[46:49], v[46:49], v[30:33], 0
	s_waitcnt lgkmcnt(0)
	v_mfma_f32_16x16x32_bf16 v[46:49], v[50:53], v[26:29], v[46:49]
	ds_read_b128 v[50:53], v100 offset:9216
	ds_read_b128 v[54:57], v100 offset:9280
	s_waitcnt lgkmcnt(1)
	v_mfma_f32_16x16x32_bf16 v[50:53], v[50:53], v[30:33], 0
	s_waitcnt lgkmcnt(0)
	v_mfma_f32_16x16x32_bf16 v[50:53], v[54:57], v[26:29], v[50:53]
	ds_read_b128 v[54:57], v100 offset:11520
	ds_read_b128 v[60:63], v100 offset:11584
	s_waitcnt lgkmcnt(1)
	v_mfma_f32_16x16x32_bf16 v[54:57], v[54:57], v[30:33], 0
	s_waitcnt lgkmcnt(0)
	v_mfma_f32_16x16x32_bf16 v[54:57], v[60:63], v[26:29], v[54:57]
	ds_read_b128 v[60:63], v100 offset:13824
	ds_read_b128 v[64:67], v100 offset:13888
	s_waitcnt lgkmcnt(1)
	v_mfma_f32_16x16x32_bf16 v[60:63], v[60:63], v[30:33], 0
	s_waitcnt lgkmcnt(0)
	v_mfma_f32_16x16x32_bf16 v[60:63], v[64:67], v[26:29], v[60:63]
	ds_read_b128 v[64:67], v100 offset:16128
	ds_read_b128 v[68:71], v100 offset:16192
	s_waitcnt lgkmcnt(1)
	v_mfma_f32_16x16x32_bf16 v[64:67], v[64:67], v[30:33], 0
	s_waitcnt lgkmcnt(0)
	v_mfma_f32_16x16x32_bf16 v[64:67], v[68:71], v[26:29], v[64:67]
	ds_read_b128 v[68:71], v100 offset:18432
	ds_read_b128 v[72:75], v100 offset:18496
	s_waitcnt lgkmcnt(1)
	v_mfma_f32_16x16x32_bf16 v[68:71], v[68:71], v[30:33], 0
	s_waitcnt lgkmcnt(0)
	v_mfma_f32_16x16x32_bf16 v[68:71], v[72:75], v[26:29], v[68:71]
	ds_read_b128 v[72:75], v100 offset:20736
	ds_read_b128 v[76:79], v100 offset:20800
	s_waitcnt lgkmcnt(1)
	v_mfma_f32_16x16x32_bf16 v[30:33], v[72:75], v[30:33], 0
	s_waitcnt lgkmcnt(0)
	v_mfma_f32_16x16x32_bf16 v[26:29], v[76:79], v[26:29], v[30:33]
	s_nop 5
	v_mul_f32_e32 v30, 0xbfb8aa3b, v80
	v_mul_f32_e32 v31, 0x3e38aa3b, v34
	v_mul_f32_e32 v32, 0x3e38aa3b, v35
	v_fmac_f32_e32 v31, v129, v30
	v_fmac_f32_e32 v32, v130, v30
	v_mul_f32_e32 v34, 0x3e38aa3b, v36
	v_mul_f32_e32 v35, 0x3e38aa3b, v37
	v_max3_f32 v33, v31, s75, v32
	v_fmac_f32_e32 v34, v131, v30
	v_fmac_f32_e32 v35, v132, v30
	v_mul_f32_e32 v36, 0x3e38aa3b, v38
	v_mul_f32_e32 v37, 0x3e38aa3b, v39
	v_max3_f32 v33, v33, v34, v35
	v_fmac_f32_e32 v36, v133, v30
	v_fmac_f32_e32 v37, v134, v30
	v_mul_f32_e32 v38, 0x3e38aa3b, v40
	v_mul_f32_e32 v39, 0x3e38aa3b, v41
	v_max3_f32 v33, v33, v36, v37
	v_fmac_f32_e32 v38, v135, v30
	v_fmac_f32_e32 v39, v136, v30
	v_mul_f32_e32 v40, 0x3e38aa3b, v42
	v_mul_f32_e32 v41, 0x3e38aa3b, v43
	v_max3_f32 v33, v33, v38, v39
	v_fmac_f32_e32 v40, v137, v30
	v_fmac_f32_e32 v41, v138, v30
	v_mul_f32_e32 v42, 0x3e38aa3b, v44
	v_mul_f32_e32 v44, 0x3e38aa3b, v45
	v_max3_f32 v33, v33, v40, v41
	v_fmac_f32_e32 v42, v139, v30
	v_fmac_f32_e32 v44, v140, v30
	v_mul_f32_e32 v45, 0x3e38aa3b, v46
	v_mul_f32_e32 v46, 0x3e38aa3b, v47
	v_max3_f32 v33, v33, v42, v44
	v_fmac_f32_e32 v45, v141, v30
	v_fmac_f32_e32 v46, v142, v30
	v_mul_f32_e32 v47, 0x3e38aa3b, v48
	v_mul_f32_e32 v48, 0x3e38aa3b, v49
	v_max3_f32 v33, v33, v45, v46
	v_fmac_f32_e32 v47, v143, v30
	v_fmac_f32_e32 v48, v144, v30
	v_mul_f32_e32 v49, 0x3e38aa3b, v50
	v_mul_f32_e32 v50, 0x3e38aa3b, v51
	v_max3_f32 v33, v33, v47, v48
	v_fmac_f32_e32 v49, v145, v30
	v_fmac_f32_e32 v50, v146, v30
	v_mul_f32_e32 v51, 0x3e38aa3b, v52
	v_mul_f32_e32 v52, 0x3e38aa3b, v53
	v_max3_f32 v33, v33, v49, v50
	v_fmac_f32_e32 v51, v147, v30
	v_fmac_f32_e32 v52, v148, v30
	v_mul_f32_e32 v53, 0x3e38aa3b, v54
	v_mul_f32_e32 v54, 0x3e38aa3b, v55
	v_max3_f32 v33, v33, v51, v52
	v_fmac_f32_e32 v53, v149, v30
	v_fmac_f32_e32 v54, v150, v30
	v_mul_f32_e32 v55, 0x3e38aa3b, v56
	v_mul_f32_e32 v56, 0x3e38aa3b, v57
	v_max3_f32 v33, v33, v53, v54
	v_fmac_f32_e32 v55, v151, v30
	v_fmac_f32_e32 v56, v152, v30
	v_mul_f32_e32 v57, 0x3e38aa3b, v60
	v_mul_f32_e32 v60, 0x3e38aa3b, v61
	v_max3_f32 v33, v33, v55, v56
	v_fmac_f32_e32 v57, v153, v30
	v_fmac_f32_e32 v60, v154, v30
	v_mul_f32_e32 v61, 0x3e38aa3b, v62
	v_mul_f32_e32 v62, 0x3e38aa3b, v63
	v_max3_f32 v33, v33, v57, v60
	v_fmac_f32_e32 v61, v155, v30
	v_fmac_f32_e32 v62, v156, v30
	v_mul_f32_e32 v63, 0x3e38aa3b, v64
	v_mul_f32_e32 v64, 0x3e38aa3b, v65
	v_max3_f32 v33, v33, v61, v62
	v_fmac_f32_e32 v63, v157, v30
	v_fmac_f32_e32 v64, v158, v30
	v_mul_f32_e32 v65, 0x3e38aa3b, v66
	v_mul_f32_e32 v66, 0x3e38aa3b, v67
	v_max3_f32 v33, v33, v63, v64
	v_fmac_f32_e32 v65, v159, v30
	v_fmac_f32_e32 v66, v160, v30
	v_mul_f32_e32 v67, 0x3e38aa3b, v68
	v_mul_f32_e32 v68, 0x3e38aa3b, v69
	v_max3_f32 v33, v33, v65, v66
	v_fmac_f32_e32 v67, v161, v30
	v_fmac_f32_e32 v68, v162, v30
	v_mul_f32_e32 v69, 0x3e38aa3b, v70
	v_mul_f32_e32 v70, 0x3e38aa3b, v71
	v_max3_f32 v33, v33, v67, v68
	v_fmac_f32_e32 v69, v163, v30
	v_fmac_f32_e32 v70, v164, v30
	v_mul_f32_e32 v26, 0x3e38aa3b, v26
	v_mul_f32_e32 v71, 0x3e38aa3b, v27
	v_max3_f32 v33, v33, v69, v70
	v_fmac_f32_e32 v26, v165, v30
	v_fmac_f32_e32 v71, v166, v30
	v_max3_f32 v27, v33, v26, v71
	v_mul_f32_e32 v33, 0x3e38aa3b, v28
	v_mul_f32_e32 v72, 0x3e38aa3b, v29
	v_fmac_f32_e32 v33, v167, v30
	v_fmac_f32_e32 v72, v168, v30
	v_max3_f32 v27, v27, v33, v72
	v_mov_b32_e32 v29, v27
	s_nop 1
	v_permlane16_swap_b32_e32 v29, v27
	v_mul_f32_e32 v28, s4, v249
	s_waitcnt lgkmcnt(0)
	v_max_f32_e32 v29, v29, v29
	v_max_f32_e32 v27, v27, v29
	v_mov_b32_e32 v29, v27
	s_nop 1
	v_permlane32_swap_b32_e32 v29, v27
	s_waitcnt lgkmcnt(0)
	v_max3_f32 v73, v27, v29, v28
	v_sub_f32_e32 v27, v31, v73
	v_exp_f32_e32 v74, v27
	v_sub_f32_e32 v28, v32, v73
	v_exp_f32_e32 v75, v28
	v_sub_f32_e32 v28, v34, v73
	v_exp_f32_e32 v76, v28
	v_sub_f32_e32 v28, v35, v73
	v_exp_f32_e32 v77, v28
	v_sub_f32_e32 v28, v36, v73
	v_add_f32_e32 v27, 0, v74
	v_exp_f32_e32 v78, v28
	v_sub_f32_e32 v28, v37, v73
	v_add_f32_e32 v27, v75, v27
	v_exp_f32_e32 v79, v28
	v_sub_f32_e32 v28, v38, v73
	v_add_f32_e32 v27, v76, v27
	v_exp_f32_e32 v80, v28
	v_sub_f32_e32 v28, v39, v73
	v_add_f32_e32 v27, v77, v27
	v_exp_f32_e32 v81, v28
	v_sub_f32_e32 v28, v40, v73
	v_add_f32_e32 v27, v78, v27
	v_exp_f32_e32 v43, v28
	v_sub_f32_e32 v28, v41, v73
	v_add_f32_e32 v27, v79, v27
	v_exp_f32_e32 v82, v28
	v_sub_f32_e32 v28, v42, v73
	v_add_f32_e32 v27, v80, v27
	v_exp_f32_e32 v83, v28
	v_sub_f32_e32 v28, v44, v73
	v_add_f32_e32 v27, v81, v27
	v_exp_f32_e32 v84, v28
	v_sub_f32_e32 v28, v45, v73
	v_add_f32_e32 v27, v43, v27
	v_exp_f32_e32 v85, v28
	v_sub_f32_e32 v28, v46, v73
	v_add_f32_e32 v27, v82, v27
	v_exp_f32_e32 v86, v28
	v_sub_f32_e32 v28, v47, v73
	v_add_f32_e32 v27, v83, v27
	v_exp_f32_e32 v47, v28
	v_sub_f32_e32 v28, v48, v73
	v_add_f32_e32 v27, v84, v27
	v_exp_f32_e32 v87, v28
	v_sub_f32_e32 v28, v49, v73
	v_add_f32_e32 v27, v85, v27
	v_exp_f32_e32 v38, v28
	v_sub_f32_e32 v28, v50, v73
	v_add_f32_e32 v27, v86, v27
	v_exp_f32_e32 v41, v28
	v_sub_f32_e32 v28, v51, v73
	v_add_f32_e32 v27, v47, v27
	v_exp_f32_e32 v42, v28
	v_sub_f32_e32 v28, v52, v73
	v_add_f32_e32 v27, v87, v27
	v_exp_f32_e32 v46, v28
	v_sub_f32_e32 v28, v53, v73
	v_add_f32_e32 v27, v38, v27
	v_exp_f32_e32 v88, v28
	v_sub_f32_e32 v28, v54, v73
	v_add_f32_e32 v27, v41, v27
	v_exp_f32_e32 v89, v28
	v_sub_f32_e32 v28, v55, v73
	v_add_f32_e32 v27, v42, v27
	v_exp_f32_e32 v99, v28
	v_sub_f32_e32 v28, v56, v73
	v_add_f32_e32 v27, v46, v27
	v_exp_f32_e32 v56, v28
	v_sub_f32_e32 v28, v57, v73
	v_add_f32_e32 v27, v88, v27
	v_exp_f32_e32 v35, v28
	v_sub_f32_e32 v28, v60, v73
	v_add_f32_e32 v27, v89, v27
	v_exp_f32_e32 v36, v28
	v_sub_f32_e32 v28, v61, v73
	v_add_f32_e32 v27, v99, v27
	v_exp_f32_e32 v37, v28
	v_sub_f32_e32 v28, v62, v73
	v_add_f32_e32 v27, v56, v27
	v_exp_f32_e32 v39, v28
	v_sub_f32_e32 v28, v63, v73
	v_add_f32_e32 v27, v35, v27
	v_exp_f32_e32 v40, v28
	v_sub_f32_e32 v28, v64, v73
	v_add_f32_e32 v27, v36, v27
	v_exp_f32_e32 v44, v28
	v_sub_f32_e32 v28, v65, v73
	v_add_f32_e32 v27, v37, v27
	v_exp_f32_e32 v45, v28
	v_sub_f32_e32 v28, v66, v73
	v_add_f32_e32 v27, v39, v27
	v_exp_f32_e32 v57, v28
	v_add_f32_e32 v27, v40, v27
	v_add_f32_e32 v27, v44, v27
	v_add_f32_e32 v27, v45, v27
	v_add_f32_e32 v28, v57, v27
	v_sub_f32_e32 v27, v67, v73
	v_exp_f32_e32 v27, v27
	v_sub_f32_e32 v26, v26, v73
	v_sub_f32_e32 v33, v33, v73
	v_exp_f32_e32 v33, v33
	v_add_f32_e32 v29, v27, v28
	v_sub_f32_e32 v28, v68, v73
	v_exp_f32_e32 v28, v28
	v_sub_f32_e32 v34, v72, v73
	v_exp_f32_e32 v34, v34
	v_add_f32_e32 v30, v28, v29
	v_sub_f32_e32 v29, v69, v73
	v_exp_f32_e32 v29, v29
	s_nop 0
	v_add_f32_e32 v31, v29, v30
	v_sub_f32_e32 v30, v70, v73
	v_exp_f32_e32 v30, v30
	s_nop 0
	v_add_f32_e32 v32, v30, v31
	v_exp_f32_e32 v31, v26
	s_nop 0
	v_add_f32_e32 v26, v31, v32
	v_sub_f32_e32 v32, v71, v73
	v_exp_f32_e32 v32, v32
	s_nop 0
	v_add_f32_e32 v26, v32, v26
	v_add_f32_e32 v26, v33, v26
	v_add_f32_e32 v26, v34, v26
	v_mov_b32_e32 v48, v26
	s_nop 1
	v_permlane16_swap_b32_e32 v48, v26
	s_waitcnt lgkmcnt(0)
	v_add_f32_e32 v26, v26, v48
	v_mov_b32_e32 v48, v26
	s_nop 1
	v_permlane32_swap_b32_e32 v48, v26
	s_waitcnt lgkmcnt(0)
	v_add_f32_e32 v26, v26, v48
	v_fma_f32 v48, s4, v249, -v73
	v_exp_f32_e32 v48, v48
	s_nop 0
	v_add_f32_e32 v26, v48, v26
	v_cvt_pk_bf16_f32 v48, v74, v75
	v_cvt_pk_bf16_f32 v49, v76, v77
	v_cvt_pk_bf16_f32 v50, v78, v79
	v_cvt_pk_bf16_f32 v51, v80, v81
	ds_read_b64_tr_b16 v[54:55], v98 offset:39168
	ds_read_b64_tr_b16 v[52:53], v98 offset:36864
	ds_read_b64_tr_b16 v[60:61], v98 offset:36896
	ds_read_b64_tr_b16 v[62:63], v98 offset:39200
	ds_read_b64_tr_b16 v[64:65], v98 offset:36928
	ds_read_b64_tr_b16 v[66:67], v98 offset:39232
	ds_read_b64_tr_b16 v[68:69], v98 offset:36960
	ds_read_b64_tr_b16 v[70:71], v98 offset:39264
	s_waitcnt lgkmcnt(6)
	v_mfma_f32_16x16x32_bf16 v[52:55], v[52:55], v[48:51], 0
	s_waitcnt lgkmcnt(4)
	v_mfma_f32_16x16x32_bf16 v[60:63], v[60:63], v[48:51], 0
	s_waitcnt lgkmcnt(2)
	v_mfma_f32_16x16x32_bf16 v[64:67], v[64:67], v[48:51], 0
	s_waitcnt lgkmcnt(0)
	v_mfma_f32_16x16x32_bf16 v[48:51], v[68:71], v[48:51], 0
	v_cvt_pk_bf16_f32 v68, v43, v82
	v_cvt_pk_bf16_f32 v69, v83, v84
	v_cvt_pk_bf16_f32 v70, v85, v86
	v_cvt_pk_bf16_f32 v71, v47, v87
	ds_read_b64_tr_b16 v[74:75], v98 offset:43776
	ds_read_b64_tr_b16 v[72:73], v98 offset:41472
	ds_read_b64_tr_b16 v[76:77], v98 offset:41504
	s_waitcnt lgkmcnt(1)
	v_mfma_f32_16x16x32_bf16 v[52:55], v[72:75], v[68:71], v[52:55]
	ds_read_b64_tr_b16 v[78:79], v98 offset:43808
	ds_read_b64_tr_b16 v[72:73], v98 offset:41536
	ds_read_b64_tr_b16 v[74:75], v98 offset:43840
	s_waitcnt lgkmcnt(0)
	v_mfma_f32_16x16x32_bf16 v[64:67], v[72:75], v[68:71], v[64:67]
	ds_read_b64_tr_b16 v[72:73], v98 offset:41568
	ds_read_b64_tr_b16 v[74:75], v98 offset:43872
	v_mfma_f32_16x16x32_bf16 v[60:63], v[76:79], v[68:71], v[60:63]
	s_waitcnt lgkmcnt(0)
	v_mfma_f32_16x16x32_bf16 v[48:51], v[72:75], v[68:71], v[48:51]
	v_cvt_pk_bf16_f32 v68, v38, v41
	v_cvt_pk_bf16_f32 v69, v42, v46
	v_cvt_pk_bf16_f32 v70, v88, v89
	v_cvt_pk_bf16_f32 v71, v99, v56
	ds_read_b64_tr_b16 v[74:75], v98 offset:48384
	ds_read_b64_tr_b16 v[72:73], v98 offset:46080
	ds_read_b64_tr_b16 v[76:77], v98 offset:46112
	s_waitcnt lgkmcnt(1)
	v_mfma_f32_16x16x32_bf16 v[52:55], v[72:75], v[68:71], v[52:55]
	ds_read_b64_tr_b16 v[78:79], v98 offset:48416
	ds_read_b64_tr_b16 v[72:73], v98 offset:46144
	ds_read_b64_tr_b16 v[74:75], v98 offset:48448
	s_waitcnt lgkmcnt(0)
	v_mfma_f32_16x16x32_bf16 v[64:67], v[72:75], v[68:71], v[64:67]
	ds_read_b64_tr_b16 v[72:73], v98 offset:46176
	ds_read_b64_tr_b16 v[74:75], v98 offset:48480
	v_cvt_pk_bf16_f32 v36, v35, v36
	v_cvt_pk_bf16_f32 v37, v37, v39
	s_waitcnt lgkmcnt(0)
	v_mfma_f32_16x16x32_bf16 v[46:49], v[72:75], v[68:71], v[48:51]
	v_cvt_pk_bf16_f32 v38, v40, v44
	v_cvt_pk_bf16_f32 v39, v45, v57
	ds_read_b64_tr_b16 v[42:43], v98 offset:52992
	ds_read_b64_tr_b16 v[40:41], v98 offset:50688
	s_nop 0
	ds_read_b64_tr_b16 v[50:51], v98 offset:50720
	s_waitcnt lgkmcnt(1)
	v_mfma_f32_16x16x32_bf16 v[40:43], v[40:43], v[36:39], v[52:55]
	s_nop 2
	ds_read_b64_tr_b16 v[52:53], v98 offset:53024
	ds_read_b64_tr_b16 v[54:55], v98 offset:50752
	ds_read_b64_tr_b16 v[56:57], v98 offset:53056
	v_mfma_f32_16x16x32_bf16 v[60:63], v[76:79], v[68:71], v[60:63]
	s_waitcnt lgkmcnt(2)
	v_mfma_f32_16x16x32_bf16 v[50:53], v[50:53], v[36:39], v[60:63]
	s_nop 5
	ds_read_b64_tr_b16 v[60:61], v98 offset:50784
	ds_read_b64_tr_b16 v[62:63], v98 offset:53088
	v_cvt_pk_bf16_f32 v28, v27, v28
	v_cvt_pk_bf16_f32 v29, v29, v30
	s_waitcnt lgkmcnt(2)
	v_mfma_f32_16x16x32_bf16 v[54:57], v[54:57], v[36:39], v[64:67]
	v_cvt_pk_bf16_f32 v30, v31, v32
	v_cvt_pk_bf16_f32 v31, v33, v34
	ds_read_b64_tr_b16 v[34:35], v98 offset:57600
	ds_read_b64_tr_b16 v[32:33], v98 offset:55296
	ds_read_b64_tr_b16 v[44:45], v98 offset:55328
	s_waitcnt lgkmcnt(3)
	v_mfma_f32_16x16x32_bf16 v[36:39], v[60:63], v[36:39], v[46:49]
	v_div_scale_f32 v27, s[4:5], v26, v26, 1.0
	s_or_b32 s4, s17, 6
	s_nop 0
	ds_read_b64_tr_b16 v[46:47], v98 offset:57632
	s_waitcnt lgkmcnt(2)
	v_mfma_f32_16x16x32_bf16 v[32:35], v[32:35], v[28:31], v[40:43]
	s_waitcnt lgkmcnt(0)
	v_mfma_f32_16x16x32_bf16 v[40:43], v[44:47], v[28:31], v[50:53]
	ds_read_b64_tr_b16 v[44:45], v98 offset:55360
	ds_read_b64_tr_b16 v[46:47], v98 offset:57664
	ds_read_b64_tr_b16 v[48:49], v98 offset:55392
	ds_read_b64_tr_b16 v[50:51], v98 offset:57696
	s_waitcnt lgkmcnt(2)
	v_mfma_f32_16x16x32_bf16 v[44:47], v[44:47], v[28:31], v[54:57]
	s_waitcnt lgkmcnt(0)
	v_mfma_f32_16x16x32_bf16 v[28:31], v[48:51], v[28:31], v[36:39]
	s_nop 2
	v_rcp_f32_e32 v36, v27
	s_nop 0
	v_fma_f32 v37, -v27, v36, 1.0
	v_fmac_f32_e32 v36, v37, v36
	v_div_scale_f32 v37, vcc, 1.0, v26, 1.0
	v_mul_f32_e32 v38, v37, v36
	v_fma_f32 v39, -v27, v38, v37
	v_fmac_f32_e32 v38, v39, v36
	v_fma_f32 v27, -v27, v38, v37
	v_div_fmas_f32 v27, v27, v36, v38
	v_div_fixup_f32 v26, v27, v26, 1.0
	v_pk_mul_f32 v[34:35], v[26:27], v[34:35] op_sel_hi:[0,1]
	v_pk_mul_f32 v[32:33], v[26:27], v[32:33] op_sel_hi:[0,1]
	v_pk_mul_f32 v[36:37], v[26:27], v[42:43] op_sel_hi:[0,1]
	v_pk_mul_f32 v[38:39], v[26:27], v[40:41] op_sel_hi:[0,1]
	v_cvt_pk_bf16_f32 v32, v32, v33
	v_cvt_pk_bf16_f32 v33, v34, v35
	v_cvt_pk_bf16_f32 v34, v38, v39
	v_cvt_pk_bf16_f32 v35, v36, v37
	global_store_dwordx4 v[58:59], v[32:35], off offset:512
	v_pk_mul_f32 v[30:31], v[26:27], v[30:31] op_sel_hi:[0,1]
	v_pk_mul_f32 v[28:29], v[26:27], v[28:29] op_sel_hi:[0,1]
	v_pk_mul_f32 v[32:33], v[26:27], v[46:47] op_sel_hi:[0,1]
	v_pk_mul_f32 v[34:35], v[26:27], v[44:45] op_sel_hi:[0,1]
	v_cvt_pk_bf16_f32 v26, v34, v35
	v_cvt_pk_bf16_f32 v27, v32, v33
	v_cvt_pk_bf16_f32 v28, v28, v29
	v_cvt_pk_bf16_f32 v29, v30, v31
	global_store_dwordx4 v[58:59], v[26:29], off offset:576
	s_nop 1
	v_cvt_f32_ubyte0_e32 v26, s4
	v_mul_f32_e32 v26, -0.5, v26
	v_exp_f32_e32 v72, v26
	ds_read_b128 v[26:29], v100
	ds_read_b128 v[30:33], v100 offset:64
	s_waitcnt vmcnt(15) lgkmcnt(1)
	v_mfma_f32_16x16x32_bf16 v[26:29], v[26:29], v[22:25], 0
	v_readlane_b32 s4, v128, 5
	s_waitcnt vmcnt(14) lgkmcnt(0)
	v_mfma_f32_16x16x32_bf16 v[26:29], v[30:33], v[18:21], v[26:29]
	ds_read_b128 v[30:33], v100 offset:2304
	ds_read_b128 v[34:37], v100 offset:2368
	s_waitcnt lgkmcnt(1)
	v_mfma_f32_16x16x32_bf16 v[30:33], v[30:33], v[22:25], 0
	s_waitcnt lgkmcnt(0)
	v_mfma_f32_16x16x32_bf16 v[30:33], v[34:37], v[18:21], v[30:33]
	ds_read_b128 v[34:37], v100 offset:4608
	ds_read_b128 v[38:41], v100 offset:4672
	s_waitcnt lgkmcnt(1)
	v_mfma_f32_16x16x32_bf16 v[34:37], v[34:37], v[22:25], 0
	s_waitcnt lgkmcnt(0)
	v_mfma_f32_16x16x32_bf16 v[34:37], v[38:41], v[18:21], v[34:37]
	ds_read_b128 v[38:41], v100 offset:6912
	ds_read_b128 v[42:45], v100 offset:6976
	s_waitcnt lgkmcnt(1)
	v_mfma_f32_16x16x32_bf16 v[38:41], v[38:41], v[22:25], 0
	s_waitcnt lgkmcnt(0)
	v_mfma_f32_16x16x32_bf16 v[38:41], v[42:45], v[18:21], v[38:41]
	ds_read_b128 v[42:45], v100 offset:9216
	ds_read_b128 v[46:49], v100 offset:9280
	s_waitcnt lgkmcnt(1)
	v_mfma_f32_16x16x32_bf16 v[42:45], v[42:45], v[22:25], 0
	s_waitcnt lgkmcnt(0)
	v_mfma_f32_16x16x32_bf16 v[42:45], v[46:49], v[18:21], v[42:45]
	ds_read_b128 v[46:49], v100 offset:11520
	ds_read_b128 v[50:53], v100 offset:11584
	s_waitcnt lgkmcnt(1)
	v_mfma_f32_16x16x32_bf16 v[46:49], v[46:49], v[22:25], 0
	s_waitcnt lgkmcnt(0)
	v_mfma_f32_16x16x32_bf16 v[46:49], v[50:53], v[18:21], v[46:49]
	ds_read_b128 v[50:53], v100 offset:13824
	ds_read_b128 v[54:57], v100 offset:13888
	s_waitcnt lgkmcnt(1)
	v_mfma_f32_16x16x32_bf16 v[50:53], v[50:53], v[22:25], 0
	s_waitcnt lgkmcnt(0)
	v_mfma_f32_16x16x32_bf16 v[50:53], v[54:57], v[18:21], v[50:53]
	ds_read_b128 v[54:57], v100 offset:16128
	ds_read_b128 v[60:63], v100 offset:16192
	s_waitcnt lgkmcnt(1)
	v_mfma_f32_16x16x32_bf16 v[54:57], v[54:57], v[22:25], 0
	s_waitcnt lgkmcnt(0)
	v_mfma_f32_16x16x32_bf16 v[54:57], v[60:63], v[18:21], v[54:57]
	ds_read_b128 v[60:63], v100 offset:18432
	ds_read_b128 v[64:67], v100 offset:18496
	s_waitcnt lgkmcnt(1)
	v_mfma_f32_16x16x32_bf16 v[60:63], v[60:63], v[22:25], 0
	s_waitcnt lgkmcnt(0)
	v_mfma_f32_16x16x32_bf16 v[60:63], v[64:67], v[18:21], v[60:63]
	ds_read_b128 v[64:67], v100 offset:20736
	ds_read_b128 v[68:71], v100 offset:20800
	s_waitcnt lgkmcnt(1)
	v_mfma_f32_16x16x32_bf16 v[22:25], v[64:67], v[22:25], 0
	s_waitcnt lgkmcnt(0)
	v_mfma_f32_16x16x32_bf16 v[18:21], v[68:71], v[18:21], v[22:25]
	s_nop 5
	v_mul_f32_e32 v22, 0xbfb8aa3b, v72
	v_mul_f32_e32 v23, 0x3e38aa3b, v26
	v_mul_f32_e32 v24, 0x3e38aa3b, v27
	v_fmac_f32_e32 v23, v129, v22
	v_fmac_f32_e32 v24, v130, v22
	v_mul_f32_e32 v26, 0x3e38aa3b, v28
	v_mul_f32_e32 v27, 0x3e38aa3b, v29
	v_max3_f32 v25, v23, s75, v24
	v_fmac_f32_e32 v26, v131, v22
	v_fmac_f32_e32 v27, v132, v22
	v_mul_f32_e32 v28, 0x3e38aa3b, v30
	v_mul_f32_e32 v29, 0x3e38aa3b, v31
	v_max3_f32 v25, v25, v26, v27
	v_fmac_f32_e32 v28, v133, v22
	v_fmac_f32_e32 v29, v134, v22
	v_mul_f32_e32 v30, 0x3e38aa3b, v32
	v_mul_f32_e32 v31, 0x3e38aa3b, v33
	v_max3_f32 v25, v25, v28, v29
	v_fmac_f32_e32 v30, v135, v22
	v_fmac_f32_e32 v31, v136, v22
	v_mul_f32_e32 v32, 0x3e38aa3b, v34
	v_mul_f32_e32 v33, 0x3e38aa3b, v35
	v_max3_f32 v25, v25, v30, v31
	v_fmac_f32_e32 v32, v137, v22
	v_fmac_f32_e32 v33, v138, v22
	v_mul_f32_e32 v34, 0x3e38aa3b, v36
	v_mul_f32_e32 v36, 0x3e38aa3b, v37
	v_max3_f32 v25, v25, v32, v33
	v_fmac_f32_e32 v34, v139, v22
	v_fmac_f32_e32 v36, v140, v22
	v_mul_f32_e32 v37, 0x3e38aa3b, v38
	v_mul_f32_e32 v38, 0x3e38aa3b, v39
	v_max3_f32 v25, v25, v34, v36
	v_fmac_f32_e32 v37, v141, v22
	v_fmac_f32_e32 v38, v142, v22
	v_mul_f32_e32 v39, 0x3e38aa3b, v40
	v_mul_f32_e32 v40, 0x3e38aa3b, v41
	v_max3_f32 v25, v25, v37, v38
	v_fmac_f32_e32 v39, v143, v22
	v_fmac_f32_e32 v40, v144, v22
	v_mul_f32_e32 v41, 0x3e38aa3b, v42
	v_mul_f32_e32 v42, 0x3e38aa3b, v43
	v_max3_f32 v25, v25, v39, v40
	v_fmac_f32_e32 v41, v145, v22
	v_fmac_f32_e32 v42, v146, v22
	v_mul_f32_e32 v43, 0x3e38aa3b, v44
	v_mul_f32_e32 v44, 0x3e38aa3b, v45
	v_max3_f32 v25, v25, v41, v42
	v_fmac_f32_e32 v43, v147, v22
	v_fmac_f32_e32 v44, v148, v22
	v_mul_f32_e32 v45, 0x3e38aa3b, v46
	v_mul_f32_e32 v46, 0x3e38aa3b, v47
	v_max3_f32 v25, v25, v43, v44
	v_fmac_f32_e32 v45, v149, v22
	v_fmac_f32_e32 v46, v150, v22
	v_mul_f32_e32 v47, 0x3e38aa3b, v48
	v_mul_f32_e32 v48, 0x3e38aa3b, v49
	v_max3_f32 v25, v25, v45, v46
	v_fmac_f32_e32 v47, v151, v22
	v_fmac_f32_e32 v48, v152, v22
	v_mul_f32_e32 v49, 0x3e38aa3b, v50
	v_mul_f32_e32 v50, 0x3e38aa3b, v51
	v_max3_f32 v25, v25, v47, v48
	v_fmac_f32_e32 v49, v153, v22
	v_fmac_f32_e32 v50, v154, v22
	v_mul_f32_e32 v51, 0x3e38aa3b, v52
	v_mul_f32_e32 v52, 0x3e38aa3b, v53
	v_max3_f32 v25, v25, v49, v50
	v_fmac_f32_e32 v51, v155, v22
	v_fmac_f32_e32 v52, v156, v22
	v_mul_f32_e32 v53, 0x3e38aa3b, v54
	v_mul_f32_e32 v54, 0x3e38aa3b, v55
	v_max3_f32 v25, v25, v51, v52
	v_fmac_f32_e32 v53, v157, v22
	v_fmac_f32_e32 v54, v158, v22
	v_mul_f32_e32 v55, 0x3e38aa3b, v56
	v_mul_f32_e32 v56, 0x3e38aa3b, v57
	v_max3_f32 v25, v25, v53, v54
	v_fmac_f32_e32 v55, v159, v22
	v_fmac_f32_e32 v56, v160, v22
	v_mul_f32_e32 v57, 0x3e38aa3b, v60
	v_mul_f32_e32 v60, 0x3e38aa3b, v61
	v_max3_f32 v25, v25, v55, v56
	v_fmac_f32_e32 v57, v161, v22
	v_fmac_f32_e32 v60, v162, v22
	v_mul_f32_e32 v61, 0x3e38aa3b, v62
	v_mul_f32_e32 v62, 0x3e38aa3b, v63
	v_max3_f32 v25, v25, v57, v60
	v_fmac_f32_e32 v61, v163, v22
	v_fmac_f32_e32 v62, v164, v22
	v_mul_f32_e32 v18, 0x3e38aa3b, v18
	v_mul_f32_e32 v63, 0x3e38aa3b, v19
	v_max3_f32 v25, v25, v61, v62
	v_fmac_f32_e32 v18, v165, v22
	v_fmac_f32_e32 v63, v166, v22
	v_max3_f32 v19, v25, v18, v63
	v_mul_f32_e32 v25, 0x3e38aa3b, v20
	v_mul_f32_e32 v64, 0x3e38aa3b, v21
	v_fmac_f32_e32 v25, v167, v22
	v_fmac_f32_e32 v64, v168, v22
	v_max3_f32 v19, v19, v25, v64
	v_mov_b32_e32 v21, v19
	s_nop 1
	v_permlane16_swap_b32_e32 v21, v19
	v_mul_f32_e32 v20, s4, v249
	s_waitcnt lgkmcnt(0)
	v_max_f32_e32 v21, v21, v21
	v_max_f32_e32 v19, v19, v21
	v_mov_b32_e32 v21, v19
	s_nop 1
	v_permlane32_swap_b32_e32 v21, v19
	s_waitcnt lgkmcnt(0)
	v_max3_f32 v65, v19, v21, v20
	v_sub_f32_e32 v19, v23, v65
	v_exp_f32_e32 v66, v19
	v_sub_f32_e32 v20, v24, v65
	v_exp_f32_e32 v67, v20
	v_sub_f32_e32 v20, v26, v65
	v_exp_f32_e32 v68, v20
	v_sub_f32_e32 v20, v27, v65
	v_exp_f32_e32 v69, v20
	v_sub_f32_e32 v20, v28, v65
	v_add_f32_e32 v19, 0, v66
	v_exp_f32_e32 v70, v20
	v_sub_f32_e32 v20, v29, v65
	v_add_f32_e32 v19, v67, v19
	v_exp_f32_e32 v71, v20
	v_sub_f32_e32 v20, v30, v65
	v_add_f32_e32 v19, v68, v19
	v_exp_f32_e32 v72, v20
	v_sub_f32_e32 v20, v31, v65
	v_add_f32_e32 v19, v69, v19
	v_exp_f32_e32 v73, v20
	v_sub_f32_e32 v20, v32, v65
	v_add_f32_e32 v19, v70, v19
	v_exp_f32_e32 v35, v20
	v_sub_f32_e32 v20, v33, v65
	v_add_f32_e32 v19, v71, v19
	v_exp_f32_e32 v74, v20
	v_sub_f32_e32 v20, v34, v65
	v_add_f32_e32 v19, v72, v19
	v_exp_f32_e32 v75, v20
	v_sub_f32_e32 v20, v36, v65
	v_add_f32_e32 v19, v73, v19
	v_exp_f32_e32 v76, v20
	v_sub_f32_e32 v20, v37, v65
	v_add_f32_e32 v19, v35, v19
	v_exp_f32_e32 v77, v20
	v_sub_f32_e32 v20, v38, v65
	v_add_f32_e32 v19, v74, v19
	v_exp_f32_e32 v78, v20
	v_sub_f32_e32 v20, v39, v65
	v_add_f32_e32 v19, v75, v19
	v_exp_f32_e32 v39, v20
	v_sub_f32_e32 v20, v40, v65
	v_add_f32_e32 v19, v76, v19
	v_exp_f32_e32 v79, v20
	v_sub_f32_e32 v20, v41, v65
	v_add_f32_e32 v19, v77, v19
	v_exp_f32_e32 v30, v20
	v_sub_f32_e32 v20, v42, v65
	v_add_f32_e32 v19, v78, v19
	v_exp_f32_e32 v33, v20
	v_sub_f32_e32 v20, v43, v65
	v_add_f32_e32 v19, v39, v19
	v_exp_f32_e32 v34, v20
	v_sub_f32_e32 v20, v44, v65
	v_add_f32_e32 v19, v79, v19
	v_exp_f32_e32 v38, v20
	v_sub_f32_e32 v20, v45, v65
	v_add_f32_e32 v19, v30, v19
	v_exp_f32_e32 v80, v20
	v_sub_f32_e32 v20, v46, v65
	v_add_f32_e32 v19, v33, v19
	v_exp_f32_e32 v81, v20
	v_sub_f32_e32 v20, v47, v65
	v_add_f32_e32 v19, v34, v19
	v_exp_f32_e32 v82, v20
	v_sub_f32_e32 v20, v48, v65
	v_add_f32_e32 v19, v38, v19
	v_exp_f32_e32 v83, v20
	v_sub_f32_e32 v20, v49, v65
	v_add_f32_e32 v19, v80, v19
	v_exp_f32_e32 v27, v20
	v_sub_f32_e32 v20, v50, v65
	v_add_f32_e32 v19, v81, v19
	v_exp_f32_e32 v28, v20
	v_sub_f32_e32 v20, v51, v65
	v_add_f32_e32 v19, v82, v19
	v_exp_f32_e32 v29, v20
	v_sub_f32_e32 v20, v52, v65
	v_add_f32_e32 v19, v83, v19
	v_exp_f32_e32 v31, v20
	v_sub_f32_e32 v20, v53, v65
	v_add_f32_e32 v19, v27, v19
	v_exp_f32_e32 v32, v20
	v_sub_f32_e32 v20, v54, v65
	v_add_f32_e32 v19, v28, v19
	v_exp_f32_e32 v36, v20
	v_sub_f32_e32 v20, v55, v65
	v_add_f32_e32 v19, v29, v19
	v_exp_f32_e32 v37, v20
	v_sub_f32_e32 v20, v56, v65
	v_add_f32_e32 v19, v31, v19
	v_exp_f32_e32 v56, v20
	v_add_f32_e32 v19, v32, v19
	v_add_f32_e32 v19, v36, v19
	v_add_f32_e32 v19, v37, v19
	v_add_f32_e32 v20, v56, v19
	v_sub_f32_e32 v19, v57, v65
	v_exp_f32_e32 v19, v19
	v_sub_f32_e32 v18, v18, v65
	v_sub_f32_e32 v25, v25, v65
	v_exp_f32_e32 v25, v25
	v_add_f32_e32 v21, v19, v20
	v_sub_f32_e32 v20, v60, v65
	v_exp_f32_e32 v20, v20
	v_sub_f32_e32 v26, v64, v65
	v_exp_f32_e32 v26, v26
	v_add_f32_e32 v22, v20, v21
	v_sub_f32_e32 v21, v61, v65
	v_exp_f32_e32 v21, v21
	s_nop 0
	v_add_f32_e32 v23, v21, v22
	v_sub_f32_e32 v22, v62, v65
	v_exp_f32_e32 v22, v22
	s_nop 0
	v_add_f32_e32 v24, v22, v23
	v_exp_f32_e32 v23, v18
	s_nop 0
	v_add_f32_e32 v18, v23, v24
	v_sub_f32_e32 v24, v63, v65
	v_exp_f32_e32 v24, v24
	s_nop 0
	v_add_f32_e32 v18, v24, v18
	v_add_f32_e32 v18, v25, v18
	v_add_f32_e32 v18, v26, v18
	v_mov_b32_e32 v40, v18
	s_nop 1
	v_permlane16_swap_b32_e32 v40, v18
	s_waitcnt lgkmcnt(0)
	v_add_f32_e32 v18, v18, v40
	v_mov_b32_e32 v40, v18
	s_nop 1
	v_permlane32_swap_b32_e32 v40, v18
	s_waitcnt lgkmcnt(0)
	v_add_f32_e32 v18, v18, v40
	v_fma_f32 v40, s4, v249, -v65
	v_exp_f32_e32 v40, v40
	s_nop 0
	v_add_f32_e32 v18, v40, v18
	v_cvt_pk_bf16_f32 v40, v66, v67
	v_cvt_pk_bf16_f32 v41, v68, v69
	v_cvt_pk_bf16_f32 v42, v70, v71
	v_cvt_pk_bf16_f32 v43, v72, v73
	ds_read_b64_tr_b16 v[46:47], v98 offset:39168
	ds_read_b64_tr_b16 v[44:45], v98 offset:36864
	ds_read_b64_tr_b16 v[48:49], v98 offset:36896
	ds_read_b64_tr_b16 v[50:51], v98 offset:39200
	ds_read_b64_tr_b16 v[52:53], v98 offset:36928
	ds_read_b64_tr_b16 v[54:55], v98 offset:39232
	ds_read_b64_tr_b16 v[60:61], v98 offset:36960
	ds_read_b64_tr_b16 v[62:63], v98 offset:39264
	s_waitcnt lgkmcnt(6)
	v_mfma_f32_16x16x32_bf16 v[44:47], v[44:47], v[40:43], 0
	s_waitcnt lgkmcnt(4)
	v_mfma_f32_16x16x32_bf16 v[48:51], v[48:51], v[40:43], 0
	s_waitcnt lgkmcnt(2)
	v_mfma_f32_16x16x32_bf16 v[52:55], v[52:55], v[40:43], 0
	s_waitcnt lgkmcnt(0)
	v_mfma_f32_16x16x32_bf16 v[40:43], v[60:63], v[40:43], 0
	v_cvt_pk_bf16_f32 v60, v35, v74
	v_cvt_pk_bf16_f32 v61, v75, v76
	v_cvt_pk_bf16_f32 v62, v77, v78
	v_cvt_pk_bf16_f32 v63, v39, v79
	ds_read_b64_tr_b16 v[66:67], v98 offset:43776
	ds_read_b64_tr_b16 v[64:65], v98 offset:41472
	ds_read_b64_tr_b16 v[68:69], v98 offset:41504
	s_waitcnt lgkmcnt(1)
	v_mfma_f32_16x16x32_bf16 v[44:47], v[64:67], v[60:63], v[44:47]
	ds_read_b64_tr_b16 v[70:71], v98 offset:43808
	ds_read_b64_tr_b16 v[64:65], v98 offset:41536
	ds_read_b64_tr_b16 v[66:67], v98 offset:43840
	s_waitcnt lgkmcnt(0)
	v_mfma_f32_16x16x32_bf16 v[52:55], v[64:67], v[60:63], v[52:55]
	ds_read_b64_tr_b16 v[64:65], v98 offset:41568
	ds_read_b64_tr_b16 v[66:67], v98 offset:43872
	v_mfma_f32_16x16x32_bf16 v[48:51], v[68:71], v[60:63], v[48:51]
	s_waitcnt lgkmcnt(0)
	v_mfma_f32_16x16x32_bf16 v[40:43], v[64:67], v[60:63], v[40:43]
	v_cvt_pk_bf16_f32 v60, v30, v33
	v_cvt_pk_bf16_f32 v61, v34, v38
	v_cvt_pk_bf16_f32 v62, v80, v81
	v_cvt_pk_bf16_f32 v63, v82, v83
	ds_read_b64_tr_b16 v[66:67], v98 offset:48384
	ds_read_b64_tr_b16 v[64:65], v98 offset:46080
	ds_read_b64_tr_b16 v[68:69], v98 offset:46112
	s_waitcnt lgkmcnt(1)
	v_mfma_f32_16x16x32_bf16 v[44:47], v[64:67], v[60:63], v[44:47]
	ds_read_b64_tr_b16 v[70:71], v98 offset:48416
	ds_read_b64_tr_b16 v[64:65], v98 offset:46144
	ds_read_b64_tr_b16 v[66:67], v98 offset:48448
	s_waitcnt lgkmcnt(0)
	v_mfma_f32_16x16x32_bf16 v[52:55], v[64:67], v[60:63], v[52:55]
	ds_read_b64_tr_b16 v[64:65], v98 offset:46176
	ds_read_b64_tr_b16 v[66:67], v98 offset:48480
	v_cvt_pk_bf16_f32 v28, v27, v28
	v_cvt_pk_bf16_f32 v29, v29, v31
	s_waitcnt lgkmcnt(0)
	v_mfma_f32_16x16x32_bf16 v[38:41], v[64:67], v[60:63], v[40:43]
	v_cvt_pk_bf16_f32 v30, v32, v36
	v_cvt_pk_bf16_f32 v31, v37, v56
	ds_read_b64_tr_b16 v[34:35], v98 offset:52992
	ds_read_b64_tr_b16 v[32:33], v98 offset:50688
	s_nop 0
	ds_read_b64_tr_b16 v[42:43], v98 offset:50720
	s_waitcnt lgkmcnt(1)
	v_mfma_f32_16x16x32_bf16 v[32:35], v[32:35], v[28:31], v[44:47]
	s_nop 2
	ds_read_b64_tr_b16 v[44:45], v98 offset:53024
	v_mfma_f32_16x16x32_bf16 v[48:51], v[68:71], v[60:63], v[48:51]
	s_waitcnt lgkmcnt(0)
	v_mfma_f32_16x16x32_bf16 v[42:45], v[42:45], v[28:31], v[48:51]
	ds_read_b64_tr_b16 v[46:47], v98 offset:50752
	s_nop 4
	ds_read_b64_tr_b16 v[48:49], v98 offset:53056
	s_waitcnt lgkmcnt(0)
	v_mfma_f32_16x16x32_bf16 v[46:49], v[46:49], v[28:31], v[52:55]
	ds_read_b64_tr_b16 v[50:51], v98 offset:50784
	s_nop 1
	ds_read_b64_tr_b16 v[52:53], v98 offset:53088
	v_cvt_pk_bf16_f32 v20, v19, v20
	v_cvt_pk_bf16_f32 v21, v21, v22
	s_waitcnt lgkmcnt(0)
	v_mfma_f32_16x16x32_bf16 v[28:31], v[50:53], v[28:31], v[38:41]
	v_cvt_pk_bf16_f32 v22, v23, v24
	v_cvt_pk_bf16_f32 v23, v25, v26
	ds_read_b64_tr_b16 v[26:27], v98 offset:57600
	ds_read_b64_tr_b16 v[24:25], v98 offset:55296
	ds_read_b64_tr_b16 v[36:37], v98 offset:55328
	ds_read_b64_tr_b16 v[38:39], v98 offset:57632
	s_waitcnt lgkmcnt(2)
	v_mfma_f32_16x16x32_bf16 v[24:27], v[24:27], v[20:23], v[32:35]
	v_div_scale_f32 v19, s[4:5], v18, v18, 1.0
	s_or_b32 s4, s17, 7
	s_waitcnt lgkmcnt(0)
	v_mfma_f32_16x16x32_bf16 v[32:35], v[36:39], v[20:23], v[42:45]
	ds_read_b64_tr_b16 v[36:37], v98 offset:55360
	ds_read_b64_tr_b16 v[38:39], v98 offset:57664
	ds_read_b64_tr_b16 v[40:41], v98 offset:55392
	ds_read_b64_tr_b16 v[42:43], v98 offset:57696
	s_add_i32 s17, s17, 8
	s_waitcnt lgkmcnt(2)
	v_mfma_f32_16x16x32_bf16 v[36:39], v[36:39], v[20:23], v[46:49]
	s_cmpk_gt_i32 s9, 0xff
	s_waitcnt lgkmcnt(0)
	v_mfma_f32_16x16x32_bf16 v[20:23], v[40:43], v[20:23], v[28:31]
	s_nop 2
	v_rcp_f32_e32 v28, v19
	s_nop 0
	v_fma_f32 v29, -v19, v28, 1.0
	v_fmac_f32_e32 v28, v29, v28
	v_div_scale_f32 v29, vcc, 1.0, v18, 1.0
	v_mul_f32_e32 v30, v29, v28
	v_fma_f32 v31, -v19, v30, v29
	v_fmac_f32_e32 v30, v31, v28
	v_fma_f32 v19, -v19, v30, v29
	v_div_fmas_f32 v19, v19, v28, v30
	v_div_fixup_f32 v18, v19, v18, 1.0
	v_pk_mul_f32 v[26:27], v[18:19], v[26:27] op_sel_hi:[0,1]
	v_pk_mul_f32 v[24:25], v[18:19], v[24:25] op_sel_hi:[0,1]
	v_pk_mul_f32 v[28:29], v[18:19], v[34:35] op_sel_hi:[0,1]
	v_pk_mul_f32 v[30:31], v[18:19], v[32:33] op_sel_hi:[0,1]
	v_cvt_pk_bf16_f32 v24, v24, v25
	v_cvt_pk_bf16_f32 v25, v26, v27
	v_cvt_pk_bf16_f32 v26, v30, v31
	v_cvt_pk_bf16_f32 v27, v28, v29
	global_store_dwordx4 v[58:59], v[24:27], off offset:640
	v_pk_mul_f32 v[22:23], v[18:19], v[22:23] op_sel_hi:[0,1]
	v_pk_mul_f32 v[20:21], v[18:19], v[20:21] op_sel_hi:[0,1]
	v_pk_mul_f32 v[24:25], v[18:19], v[38:39] op_sel_hi:[0,1]
	v_pk_mul_f32 v[26:27], v[18:19], v[36:37] op_sel_hi:[0,1]
	v_cvt_pk_bf16_f32 v18, v26, v27
	v_cvt_pk_bf16_f32 v19, v24, v25
	v_cvt_pk_bf16_f32 v20, v20, v21
	v_cvt_pk_bf16_f32 v21, v22, v23
	global_store_dwordx4 v[58:59], v[18:21], off offset:704
	s_nop 1
	v_cvt_f32_ubyte0_e32 v18, s4
	v_mul_f32_e32 v18, -0.5, v18
	v_exp_f32_e32 v64, v18
	ds_read_b128 v[18:21], v100
	ds_read_b128 v[22:25], v100 offset:64
	s_waitcnt vmcnt(15) lgkmcnt(1)
	v_mfma_f32_16x16x32_bf16 v[18:21], v[18:21], v[14:17], 0
	v_readlane_b32 s4, v128, 6
	s_waitcnt vmcnt(14) lgkmcnt(0)
	v_mfma_f32_16x16x32_bf16 v[18:21], v[22:25], v[10:13], v[18:21]
	ds_read_b128 v[22:25], v100 offset:2304
	ds_read_b128 v[26:29], v100 offset:2368
	s_waitcnt lgkmcnt(1)
	v_mfma_f32_16x16x32_bf16 v[22:25], v[22:25], v[14:17], 0
	s_waitcnt lgkmcnt(0)
	v_mfma_f32_16x16x32_bf16 v[22:25], v[26:29], v[10:13], v[22:25]
	ds_read_b128 v[26:29], v100 offset:4608
	ds_read_b128 v[30:33], v100 offset:4672
	s_waitcnt lgkmcnt(1)
	v_mfma_f32_16x16x32_bf16 v[26:29], v[26:29], v[14:17], 0
	s_waitcnt lgkmcnt(0)
	v_mfma_f32_16x16x32_bf16 v[26:29], v[30:33], v[10:13], v[26:29]
	ds_read_b128 v[30:33], v100 offset:6912
	ds_read_b128 v[34:37], v100 offset:6976
	s_waitcnt lgkmcnt(1)
	v_mfma_f32_16x16x32_bf16 v[30:33], v[30:33], v[14:17], 0
	s_waitcnt lgkmcnt(0)
	v_mfma_f32_16x16x32_bf16 v[30:33], v[34:37], v[10:13], v[30:33]
	ds_read_b128 v[34:37], v100 offset:9216
	ds_read_b128 v[38:41], v100 offset:9280
	s_waitcnt lgkmcnt(1)
	v_mfma_f32_16x16x32_bf16 v[34:37], v[34:37], v[14:17], 0
	s_waitcnt lgkmcnt(0)
	v_mfma_f32_16x16x32_bf16 v[34:37], v[38:41], v[10:13], v[34:37]
	ds_read_b128 v[38:41], v100 offset:11520
	ds_read_b128 v[42:45], v100 offset:11584
	s_waitcnt lgkmcnt(1)
	v_mfma_f32_16x16x32_bf16 v[38:41], v[38:41], v[14:17], 0
	s_waitcnt lgkmcnt(0)
	v_mfma_f32_16x16x32_bf16 v[38:41], v[42:45], v[10:13], v[38:41]
	ds_read_b128 v[42:45], v100 offset:13824
	ds_read_b128 v[46:49], v100 offset:13888
	s_waitcnt lgkmcnt(1)
	v_mfma_f32_16x16x32_bf16 v[42:45], v[42:45], v[14:17], 0
	s_waitcnt lgkmcnt(0)
	v_mfma_f32_16x16x32_bf16 v[42:45], v[46:49], v[10:13], v[42:45]
	ds_read_b128 v[46:49], v100 offset:16128
	ds_read_b128 v[50:53], v100 offset:16192
	s_waitcnt lgkmcnt(1)
	v_mfma_f32_16x16x32_bf16 v[46:49], v[46:49], v[14:17], 0
	s_waitcnt lgkmcnt(0)
	v_mfma_f32_16x16x32_bf16 v[46:49], v[50:53], v[10:13], v[46:49]
	ds_read_b128 v[50:53], v100 offset:18432
	ds_read_b128 v[54:57], v100 offset:18496
	s_waitcnt lgkmcnt(1)
	v_mfma_f32_16x16x32_bf16 v[50:53], v[50:53], v[14:17], 0
	s_waitcnt lgkmcnt(0)
	v_mfma_f32_16x16x32_bf16 v[50:53], v[54:57], v[10:13], v[50:53]
	ds_read_b128 v[54:57], v100 offset:20736
	ds_read_b128 v[60:63], v100 offset:20800
	s_waitcnt lgkmcnt(1)
	v_mfma_f32_16x16x32_bf16 v[14:17], v[54:57], v[14:17], 0
	s_waitcnt lgkmcnt(0)
	v_mfma_f32_16x16x32_bf16 v[10:13], v[60:63], v[10:13], v[14:17]
	s_nop 5
	v_mul_f32_e32 v14, 0xbfb8aa3b, v64
	v_mul_f32_e32 v15, 0x3e38aa3b, v18
	v_mul_f32_e32 v16, 0x3e38aa3b, v19
	v_fmac_f32_e32 v15, v129, v14
	v_fmac_f32_e32 v16, v130, v14
	v_mul_f32_e32 v18, 0x3e38aa3b, v20
	v_mul_f32_e32 v19, 0x3e38aa3b, v21
	v_max3_f32 v17, v15, s75, v16
	v_fmac_f32_e32 v18, v131, v14
	v_fmac_f32_e32 v19, v132, v14
	v_mul_f32_e32 v20, 0x3e38aa3b, v22
	v_mul_f32_e32 v21, 0x3e38aa3b, v23
	v_max3_f32 v17, v17, v18, v19
	v_fmac_f32_e32 v20, v133, v14
	v_fmac_f32_e32 v21, v134, v14
	v_mul_f32_e32 v22, 0x3e38aa3b, v24
	v_mul_f32_e32 v23, 0x3e38aa3b, v25
	v_max3_f32 v17, v17, v20, v21
	v_fmac_f32_e32 v22, v135, v14
	v_fmac_f32_e32 v23, v136, v14
	v_mul_f32_e32 v24, 0x3e38aa3b, v26
	v_mul_f32_e32 v25, 0x3e38aa3b, v27
	v_max3_f32 v17, v17, v22, v23
	v_fmac_f32_e32 v24, v137, v14
	v_fmac_f32_e32 v25, v138, v14
	v_mul_f32_e32 v26, 0x3e38aa3b, v28
	v_mul_f32_e32 v28, 0x3e38aa3b, v29
	v_max3_f32 v17, v17, v24, v25
	v_fmac_f32_e32 v26, v139, v14
	v_fmac_f32_e32 v28, v140, v14
	v_mul_f32_e32 v29, 0x3e38aa3b, v30
	v_mul_f32_e32 v30, 0x3e38aa3b, v31
	v_max3_f32 v17, v17, v26, v28
	v_fmac_f32_e32 v29, v141, v14
	v_fmac_f32_e32 v30, v142, v14
	v_mul_f32_e32 v31, 0x3e38aa3b, v32
	v_mul_f32_e32 v32, 0x3e38aa3b, v33
	v_max3_f32 v17, v17, v29, v30
	v_fmac_f32_e32 v31, v143, v14
	v_fmac_f32_e32 v32, v144, v14
	v_mul_f32_e32 v33, 0x3e38aa3b, v34
	v_mul_f32_e32 v34, 0x3e38aa3b, v35
	v_max3_f32 v17, v17, v31, v32
	v_fmac_f32_e32 v33, v145, v14
	v_fmac_f32_e32 v34, v146, v14
	v_mul_f32_e32 v35, 0x3e38aa3b, v36
	v_mul_f32_e32 v36, 0x3e38aa3b, v37
	v_max3_f32 v17, v17, v33, v34
	v_fmac_f32_e32 v35, v147, v14
	v_fmac_f32_e32 v36, v148, v14
	v_mul_f32_e32 v37, 0x3e38aa3b, v38
	v_mul_f32_e32 v38, 0x3e38aa3b, v39
	v_max3_f32 v17, v17, v35, v36
	v_fmac_f32_e32 v37, v149, v14
	v_fmac_f32_e32 v38, v150, v14
	v_mul_f32_e32 v39, 0x3e38aa3b, v40
	v_mul_f32_e32 v40, 0x3e38aa3b, v41
	v_max3_f32 v17, v17, v37, v38
	v_fmac_f32_e32 v39, v151, v14
	v_fmac_f32_e32 v40, v152, v14
	v_mul_f32_e32 v41, 0x3e38aa3b, v42
	v_mul_f32_e32 v42, 0x3e38aa3b, v43
	v_max3_f32 v17, v17, v39, v40
	v_fmac_f32_e32 v41, v153, v14
	v_fmac_f32_e32 v42, v154, v14
	v_mul_f32_e32 v43, 0x3e38aa3b, v44
	v_mul_f32_e32 v44, 0x3e38aa3b, v45
	v_max3_f32 v17, v17, v41, v42
	v_fmac_f32_e32 v43, v155, v14
	v_fmac_f32_e32 v44, v156, v14
	v_mul_f32_e32 v45, 0x3e38aa3b, v46
	v_mul_f32_e32 v46, 0x3e38aa3b, v47
	v_max3_f32 v17, v17, v43, v44
	v_fmac_f32_e32 v45, v157, v14
	v_fmac_f32_e32 v46, v158, v14
	v_mul_f32_e32 v47, 0x3e38aa3b, v48
	v_mul_f32_e32 v48, 0x3e38aa3b, v49
	v_max3_f32 v17, v17, v45, v46
	v_fmac_f32_e32 v47, v159, v14
	v_fmac_f32_e32 v48, v160, v14
	v_mul_f32_e32 v49, 0x3e38aa3b, v50
	v_mul_f32_e32 v50, 0x3e38aa3b, v51
	v_max3_f32 v17, v17, v47, v48
	v_fmac_f32_e32 v49, v161, v14
	v_fmac_f32_e32 v50, v162, v14
	v_mul_f32_e32 v51, 0x3e38aa3b, v52
	v_mul_f32_e32 v52, 0x3e38aa3b, v53
	v_max3_f32 v17, v17, v49, v50
	v_fmac_f32_e32 v51, v163, v14
	v_fmac_f32_e32 v52, v164, v14
	v_mul_f32_e32 v10, 0x3e38aa3b, v10
	v_mul_f32_e32 v53, 0x3e38aa3b, v11
	v_max3_f32 v17, v17, v51, v52
	v_fmac_f32_e32 v10, v165, v14
	v_fmac_f32_e32 v53, v166, v14
	v_max3_f32 v11, v17, v10, v53
	v_mul_f32_e32 v17, 0x3e38aa3b, v12
	v_mul_f32_e32 v54, 0x3e38aa3b, v13
	v_fmac_f32_e32 v17, v167, v14
	v_fmac_f32_e32 v54, v168, v14
	v_max3_f32 v11, v11, v17, v54
	v_mov_b32_e32 v13, v11
	s_nop 1
	v_permlane16_swap_b32_e32 v13, v11
	v_mul_f32_e32 v12, s4, v249
	s_waitcnt lgkmcnt(0)
	v_max_f32_e32 v13, v13, v13
	v_max_f32_e32 v11, v11, v13
	v_mov_b32_e32 v13, v11
	s_nop 1
	v_permlane32_swap_b32_e32 v13, v11
	s_waitcnt lgkmcnt(0)
	v_max3_f32 v55, v11, v13, v12
	v_sub_f32_e32 v11, v15, v55
	v_exp_f32_e32 v56, v11
	v_sub_f32_e32 v12, v16, v55
	v_exp_f32_e32 v57, v12
	v_sub_f32_e32 v12, v18, v55
	v_exp_f32_e32 v60, v12
	v_sub_f32_e32 v12, v19, v55
	v_exp_f32_e32 v61, v12
	v_sub_f32_e32 v12, v20, v55
	v_add_f32_e32 v11, 0, v56
	v_exp_f32_e32 v62, v12
	v_sub_f32_e32 v12, v21, v55
	v_add_f32_e32 v11, v57, v11
	v_exp_f32_e32 v63, v12
	v_sub_f32_e32 v12, v22, v55
	v_add_f32_e32 v11, v60, v11
	v_exp_f32_e32 v64, v12
	v_sub_f32_e32 v12, v23, v55
	v_add_f32_e32 v11, v61, v11
	v_exp_f32_e32 v65, v12
	v_sub_f32_e32 v12, v24, v55
	v_add_f32_e32 v11, v62, v11
	v_exp_f32_e32 v27, v12
	v_sub_f32_e32 v12, v25, v55
	v_add_f32_e32 v11, v63, v11
	v_exp_f32_e32 v66, v12
	v_sub_f32_e32 v12, v26, v55
	v_add_f32_e32 v11, v64, v11
	v_exp_f32_e32 v67, v12
	v_sub_f32_e32 v12, v28, v55
	v_add_f32_e32 v11, v65, v11
	v_exp_f32_e32 v68, v12
	v_sub_f32_e32 v12, v29, v55
	v_add_f32_e32 v11, v27, v11
	v_exp_f32_e32 v69, v12
	v_sub_f32_e32 v12, v30, v55
	v_add_f32_e32 v11, v66, v11
	v_exp_f32_e32 v70, v12
	v_sub_f32_e32 v12, v31, v55
	v_add_f32_e32 v11, v67, v11
	v_exp_f32_e32 v31, v12
	v_sub_f32_e32 v12, v32, v55
	v_add_f32_e32 v11, v68, v11
	v_exp_f32_e32 v71, v12
	v_sub_f32_e32 v12, v33, v55
	v_add_f32_e32 v11, v69, v11
	v_exp_f32_e32 v22, v12
	v_sub_f32_e32 v12, v34, v55
	v_add_f32_e32 v11, v70, v11
	v_exp_f32_e32 v25, v12
	v_sub_f32_e32 v12, v35, v55
	v_add_f32_e32 v11, v31, v11
	v_exp_f32_e32 v26, v12
	v_sub_f32_e32 v12, v36, v55
	v_add_f32_e32 v11, v71, v11
	v_exp_f32_e32 v30, v12
	v_sub_f32_e32 v12, v37, v55
	v_add_f32_e32 v11, v22, v11
	v_exp_f32_e32 v72, v12
	v_sub_f32_e32 v12, v38, v55
	v_add_f32_e32 v11, v25, v11
	v_exp_f32_e32 v73, v12
	v_sub_f32_e32 v12, v39, v55
	v_add_f32_e32 v11, v26, v11
	v_exp_f32_e32 v74, v12
	v_sub_f32_e32 v12, v40, v55
	v_add_f32_e32 v11, v30, v11
	v_exp_f32_e32 v75, v12
	v_sub_f32_e32 v12, v41, v55
	v_add_f32_e32 v11, v72, v11
	v_exp_f32_e32 v19, v12
	v_sub_f32_e32 v12, v42, v55
	v_add_f32_e32 v11, v73, v11
	v_exp_f32_e32 v20, v12
	v_sub_f32_e32 v12, v43, v55
	v_add_f32_e32 v11, v74, v11
	v_exp_f32_e32 v21, v12
	v_sub_f32_e32 v12, v44, v55
	v_add_f32_e32 v11, v75, v11
	v_exp_f32_e32 v23, v12
	v_sub_f32_e32 v12, v45, v55
	v_add_f32_e32 v11, v19, v11
	v_exp_f32_e32 v24, v12
	v_sub_f32_e32 v12, v46, v55
	v_add_f32_e32 v11, v20, v11
	v_exp_f32_e32 v28, v12
	v_sub_f32_e32 v12, v47, v55
	v_add_f32_e32 v11, v21, v11
	v_exp_f32_e32 v29, v12
	v_sub_f32_e32 v12, v48, v55
	v_add_f32_e32 v11, v23, v11
	v_exp_f32_e32 v76, v12
	v_add_f32_e32 v11, v24, v11
	v_add_f32_e32 v11, v28, v11
	v_add_f32_e32 v11, v29, v11
	v_add_f32_e32 v12, v76, v11
	v_sub_f32_e32 v11, v49, v55
	v_exp_f32_e32 v11, v11
	v_sub_f32_e32 v10, v10, v55
	v_sub_f32_e32 v17, v17, v55
	v_exp_f32_e32 v17, v17
	v_add_f32_e32 v13, v11, v12
	v_sub_f32_e32 v12, v50, v55
	v_exp_f32_e32 v12, v12
	v_sub_f32_e32 v18, v54, v55
	v_exp_f32_e32 v18, v18
	v_add_f32_e32 v14, v12, v13
	v_sub_f32_e32 v13, v51, v55
	v_exp_f32_e32 v13, v13
	s_nop 0
	v_add_f32_e32 v15, v13, v14
	v_sub_f32_e32 v14, v52, v55
	v_exp_f32_e32 v14, v14
	s_nop 0
	v_add_f32_e32 v16, v14, v15
	v_exp_f32_e32 v15, v10
	s_nop 0
	v_add_f32_e32 v10, v15, v16
	v_sub_f32_e32 v16, v53, v55
	v_exp_f32_e32 v16, v16
	s_nop 0
	v_add_f32_e32 v10, v16, v10
	v_add_f32_e32 v10, v17, v10
	v_add_f32_e32 v10, v18, v10
	v_mov_b32_e32 v32, v10
	s_nop 1
	v_permlane16_swap_b32_e32 v32, v10
	s_waitcnt lgkmcnt(0)
	v_add_f32_e32 v10, v10, v32
	v_mov_b32_e32 v32, v10
	s_nop 1
	v_permlane32_swap_b32_e32 v32, v10
	s_waitcnt lgkmcnt(0)
	v_add_f32_e32 v10, v10, v32
	v_fma_f32 v32, s4, v249, -v55
	v_exp_f32_e32 v32, v32
	s_nop 0
	v_add_f32_e32 v10, v32, v10
	v_cvt_pk_bf16_f32 v32, v56, v57
	v_cvt_pk_bf16_f32 v33, v60, v61
	v_cvt_pk_bf16_f32 v34, v62, v63
	v_cvt_pk_bf16_f32 v35, v64, v65
	ds_read_b64_tr_b16 v[38:39], v98 offset:39168
	ds_read_b64_tr_b16 v[36:37], v98 offset:36864
	ds_read_b64_tr_b16 v[40:41], v98 offset:36896
	ds_read_b64_tr_b16 v[42:43], v98 offset:39200
	ds_read_b64_tr_b16 v[44:45], v98 offset:36928
	ds_read_b64_tr_b16 v[46:47], v98 offset:39232
	ds_read_b64_tr_b16 v[48:49], v98 offset:36960
	ds_read_b64_tr_b16 v[50:51], v98 offset:39264
	s_waitcnt lgkmcnt(6)
	v_mfma_f32_16x16x32_bf16 v[36:39], v[36:39], v[32:35], 0
	s_waitcnt lgkmcnt(4)
	v_mfma_f32_16x16x32_bf16 v[40:43], v[40:43], v[32:35], 0
	s_waitcnt lgkmcnt(2)
	v_mfma_f32_16x16x32_bf16 v[44:47], v[44:47], v[32:35], 0
	s_waitcnt lgkmcnt(0)
	v_mfma_f32_16x16x32_bf16 v[32:35], v[48:51], v[32:35], 0
	v_cvt_pk_bf16_f32 v48, v27, v66
	v_cvt_pk_bf16_f32 v49, v67, v68
	v_cvt_pk_bf16_f32 v50, v69, v70
	v_cvt_pk_bf16_f32 v51, v31, v71
	ds_read_b64_tr_b16 v[54:55], v98 offset:43776
	ds_read_b64_tr_b16 v[52:53], v98 offset:41472
	ds_read_b64_tr_b16 v[60:61], v98 offset:41504
	s_waitcnt lgkmcnt(1)
	v_mfma_f32_16x16x32_bf16 v[36:39], v[52:55], v[48:51], v[36:39]
	ds_read_b64_tr_b16 v[62:63], v98 offset:43808
	ds_read_b64_tr_b16 v[52:53], v98 offset:41536
	ds_read_b64_tr_b16 v[54:55], v98 offset:43840
	s_waitcnt lgkmcnt(0)
	v_mfma_f32_16x16x32_bf16 v[44:47], v[52:55], v[48:51], v[44:47]
	ds_read_b64_tr_b16 v[52:53], v98 offset:41568
	ds_read_b64_tr_b16 v[54:55], v98 offset:43872
	v_mfma_f32_16x16x32_bf16 v[40:43], v[60:63], v[48:51], v[40:43]
	s_waitcnt lgkmcnt(0)
	v_mfma_f32_16x16x32_bf16 v[32:35], v[52:55], v[48:51], v[32:35]
	v_cvt_pk_bf16_f32 v48, v22, v25
	v_cvt_pk_bf16_f32 v49, v26, v30
	v_cvt_pk_bf16_f32 v50, v72, v73
	v_cvt_pk_bf16_f32 v51, v74, v75
	ds_read_b64_tr_b16 v[54:55], v98 offset:48384
	ds_read_b64_tr_b16 v[52:53], v98 offset:46080
	ds_read_b64_tr_b16 v[60:61], v98 offset:46112
	s_waitcnt lgkmcnt(1)
	v_mfma_f32_16x16x32_bf16 v[36:39], v[52:55], v[48:51], v[36:39]
	ds_read_b64_tr_b16 v[62:63], v98 offset:48416
	ds_read_b64_tr_b16 v[52:53], v98 offset:46144
	ds_read_b64_tr_b16 v[54:55], v98 offset:48448
	s_waitcnt lgkmcnt(0)
	v_mfma_f32_16x16x32_bf16 v[44:47], v[52:55], v[48:51], v[44:47]
	ds_read_b64_tr_b16 v[52:53], v98 offset:46176
	ds_read_b64_tr_b16 v[54:55], v98 offset:48480
	v_cvt_pk_bf16_f32 v20, v19, v20
	v_cvt_pk_bf16_f32 v21, v21, v23
	s_waitcnt lgkmcnt(0)
	v_mfma_f32_16x16x32_bf16 v[30:33], v[52:55], v[48:51], v[32:35]
	v_cvt_pk_bf16_f32 v22, v24, v28
	v_cvt_pk_bf16_f32 v23, v29, v76
	ds_read_b64_tr_b16 v[26:27], v98 offset:52992
	ds_read_b64_tr_b16 v[24:25], v98 offset:50688
	s_nop 0
	ds_read_b64_tr_b16 v[34:35], v98 offset:50720
	s_waitcnt lgkmcnt(1)
	v_mfma_f32_16x16x32_bf16 v[24:27], v[24:27], v[20:23], v[36:39]
	s_nop 2
	ds_read_b64_tr_b16 v[36:37], v98 offset:53024
	v_mfma_f32_16x16x32_bf16 v[40:43], v[60:63], v[48:51], v[40:43]
	s_waitcnt lgkmcnt(0)
	v_mfma_f32_16x16x32_bf16 v[34:37], v[34:37], v[20:23], v[40:43]
	ds_read_b64_tr_b16 v[38:39], v98 offset:50752
	s_nop 4
	ds_read_b64_tr_b16 v[40:41], v98 offset:53056
	s_waitcnt lgkmcnt(0)
	v_mfma_f32_16x16x32_bf16 v[38:41], v[38:41], v[20:23], v[44:47]
	ds_read_b64_tr_b16 v[42:43], v98 offset:50784
	s_nop 1
	ds_read_b64_tr_b16 v[44:45], v98 offset:53088
	v_cvt_pk_bf16_f32 v12, v11, v12
	v_cvt_pk_bf16_f32 v13, v13, v14
	s_waitcnt lgkmcnt(0)
	v_mfma_f32_16x16x32_bf16 v[20:23], v[42:45], v[20:23], v[30:33]
	v_cvt_pk_bf16_f32 v14, v15, v16
	v_cvt_pk_bf16_f32 v15, v17, v18
	ds_read_b64_tr_b16 v[18:19], v98 offset:57600
	ds_read_b64_tr_b16 v[16:17], v98 offset:55296
	ds_read_b64_tr_b16 v[28:29], v98 offset:55328
	ds_read_b64_tr_b16 v[30:31], v98 offset:57632
	s_waitcnt lgkmcnt(2)
	v_mfma_f32_16x16x32_bf16 v[16:19], v[16:19], v[12:15], v[24:27]
	v_div_scale_f32 v11, s[4:5], v10, v10, 1.0
	v_readlane_b32 s4, v128, 7
	s_waitcnt lgkmcnt(0)
	v_mfma_f32_16x16x32_bf16 v[24:27], v[28:31], v[12:15], v[34:37]
	ds_read_b64_tr_b16 v[28:29], v98 offset:55360
	ds_read_b64_tr_b16 v[30:31], v98 offset:57664
	ds_read_b64_tr_b16 v[32:33], v98 offset:55392
	ds_read_b64_tr_b16 v[34:35], v98 offset:57696
	s_waitcnt lgkmcnt(2)
	v_mfma_f32_16x16x32_bf16 v[28:31], v[28:31], v[12:15], v[38:41]
	s_waitcnt lgkmcnt(0)
	v_mfma_f32_16x16x32_bf16 v[12:15], v[32:35], v[12:15], v[20:23]
	s_nop 2
	v_rcp_f32_e32 v20, v11
	s_nop 0
	v_fma_f32 v21, -v11, v20, 1.0
	v_fmac_f32_e32 v20, v21, v20
	v_div_scale_f32 v21, vcc, 1.0, v10, 1.0
	v_mul_f32_e32 v22, v21, v20
	v_fma_f32 v23, -v11, v22, v21
	v_fmac_f32_e32 v22, v23, v20
	v_fma_f32 v11, -v11, v22, v21
	v_div_fmas_f32 v11, v11, v20, v22
	v_div_fixup_f32 v10, v11, v10, 1.0
	v_pk_mul_f32 v[18:19], v[10:11], v[18:19] op_sel_hi:[0,1]
	v_pk_mul_f32 v[16:17], v[10:11], v[16:17] op_sel_hi:[0,1]
	v_pk_mul_f32 v[20:21], v[10:11], v[26:27] op_sel_hi:[0,1]
	v_pk_mul_f32 v[22:23], v[10:11], v[24:25] op_sel_hi:[0,1]
	v_cvt_pk_bf16_f32 v16, v16, v17
	v_cvt_pk_bf16_f32 v17, v18, v19
	v_cvt_pk_bf16_f32 v18, v22, v23
	v_cvt_pk_bf16_f32 v19, v20, v21
	global_store_dwordx4 v[58:59], v[16:19], off offset:768
	v_pk_mul_f32 v[14:15], v[10:11], v[14:15] op_sel_hi:[0,1]
	v_pk_mul_f32 v[12:13], v[10:11], v[12:13] op_sel_hi:[0,1]
	v_pk_mul_f32 v[16:17], v[10:11], v[30:31] op_sel_hi:[0,1]
	v_pk_mul_f32 v[18:19], v[10:11], v[28:29] op_sel_hi:[0,1]
	v_cvt_pk_bf16_f32 v10, v18, v19
	v_cvt_pk_bf16_f32 v11, v16, v17
	v_cvt_pk_bf16_f32 v12, v12, v13
	v_cvt_pk_bf16_f32 v13, v14, v15
	global_store_dwordx4 v[58:59], v[10:13], off offset:832
	s_nop 1
	v_cvt_f32_ubyte0_e32 v10, s17
	v_mul_f32_e32 v10, -0.5, v10
	v_exp_f32_e32 v54, v10
	ds_read_b128 v[10:13], v100
	ds_read_b128 v[14:17], v100 offset:64
	s_waitcnt vmcnt(15) lgkmcnt(1)
	v_mfma_f32_16x16x32_bf16 v[10:13], v[10:13], v[6:9], 0
	s_waitcnt vmcnt(14) lgkmcnt(0)
	v_mfma_f32_16x16x32_bf16 v[10:13], v[14:17], v[2:5], v[10:13]
	ds_read_b128 v[14:17], v100 offset:2304
	ds_read_b128 v[18:21], v100 offset:2368
	s_waitcnt lgkmcnt(1)
	v_mfma_f32_16x16x32_bf16 v[14:17], v[14:17], v[6:9], 0
	s_waitcnt lgkmcnt(0)
	v_mfma_f32_16x16x32_bf16 v[14:17], v[18:21], v[2:5], v[14:17]
	ds_read_b128 v[18:21], v100 offset:4608
	ds_read_b128 v[22:25], v100 offset:4672
	s_waitcnt lgkmcnt(1)
	v_mfma_f32_16x16x32_bf16 v[18:21], v[18:21], v[6:9], 0
	s_waitcnt lgkmcnt(0)
	v_mfma_f32_16x16x32_bf16 v[18:21], v[22:25], v[2:5], v[18:21]
	ds_read_b128 v[22:25], v100 offset:6912
	ds_read_b128 v[26:29], v100 offset:6976
	s_waitcnt lgkmcnt(1)
	v_mfma_f32_16x16x32_bf16 v[22:25], v[22:25], v[6:9], 0
	s_waitcnt lgkmcnt(0)
	v_mfma_f32_16x16x32_bf16 v[22:25], v[26:29], v[2:5], v[22:25]
	ds_read_b128 v[26:29], v100 offset:9216
	ds_read_b128 v[30:33], v100 offset:9280
	s_waitcnt lgkmcnt(1)
	v_mfma_f32_16x16x32_bf16 v[26:29], v[26:29], v[6:9], 0
	s_waitcnt lgkmcnt(0)
	v_mfma_f32_16x16x32_bf16 v[26:29], v[30:33], v[2:5], v[26:29]
	ds_read_b128 v[30:33], v100 offset:11520
	ds_read_b128 v[34:37], v100 offset:11584
	s_waitcnt lgkmcnt(1)
	v_mfma_f32_16x16x32_bf16 v[30:33], v[30:33], v[6:9], 0
	s_waitcnt lgkmcnt(0)
	v_mfma_f32_16x16x32_bf16 v[30:33], v[34:37], v[2:5], v[30:33]
	ds_read_b128 v[34:37], v100 offset:13824
	ds_read_b128 v[38:41], v100 offset:13888
	s_waitcnt lgkmcnt(1)
	v_mfma_f32_16x16x32_bf16 v[34:37], v[34:37], v[6:9], 0
	s_waitcnt lgkmcnt(0)
	v_mfma_f32_16x16x32_bf16 v[34:37], v[38:41], v[2:5], v[34:37]
	ds_read_b128 v[38:41], v100 offset:16128
	ds_read_b128 v[42:45], v100 offset:16192
	s_waitcnt lgkmcnt(1)
	v_mfma_f32_16x16x32_bf16 v[38:41], v[38:41], v[6:9], 0
	s_waitcnt lgkmcnt(0)
	v_mfma_f32_16x16x32_bf16 v[38:41], v[42:45], v[2:5], v[38:41]
	ds_read_b128 v[42:45], v100 offset:18432
	ds_read_b128 v[46:49], v100 offset:18496
	s_waitcnt lgkmcnt(1)
	v_mfma_f32_16x16x32_bf16 v[42:45], v[42:45], v[6:9], 0
	s_waitcnt lgkmcnt(0)
	v_mfma_f32_16x16x32_bf16 v[42:45], v[46:49], v[2:5], v[42:45]
	ds_read_b128 v[46:49], v100 offset:20736
	ds_read_b128 v[50:53], v100 offset:20800
	s_waitcnt lgkmcnt(1)
	v_mfma_f32_16x16x32_bf16 v[6:9], v[46:49], v[6:9], 0
	s_waitcnt lgkmcnt(0)
	v_mfma_f32_16x16x32_bf16 v[2:5], v[50:53], v[2:5], v[6:9]
	s_nop 5
	v_mul_f32_e32 v6, 0xbfb8aa3b, v54
	v_mul_f32_e32 v7, 0x3e38aa3b, v10
	v_mul_f32_e32 v8, 0x3e38aa3b, v11
	v_fmac_f32_e32 v7, v129, v6
	v_fmac_f32_e32 v8, v130, v6
	v_mul_f32_e32 v10, 0x3e38aa3b, v12
	v_mul_f32_e32 v11, 0x3e38aa3b, v13
	v_max3_f32 v9, v7, s75, v8
	v_fmac_f32_e32 v10, v131, v6
	v_fmac_f32_e32 v11, v132, v6
	v_mul_f32_e32 v12, 0x3e38aa3b, v14
	v_mul_f32_e32 v13, 0x3e38aa3b, v15
	v_max3_f32 v9, v9, v10, v11
	v_fmac_f32_e32 v12, v133, v6
	v_fmac_f32_e32 v13, v134, v6
	v_mul_f32_e32 v14, 0x3e38aa3b, v16
	v_mul_f32_e32 v15, 0x3e38aa3b, v17
	v_max3_f32 v9, v9, v12, v13
	v_fmac_f32_e32 v14, v135, v6
	v_fmac_f32_e32 v15, v136, v6
	v_mul_f32_e32 v16, 0x3e38aa3b, v18
	v_mul_f32_e32 v17, 0x3e38aa3b, v19
	v_max3_f32 v9, v9, v14, v15
	v_fmac_f32_e32 v16, v137, v6
	v_fmac_f32_e32 v17, v138, v6
	v_mul_f32_e32 v18, 0x3e38aa3b, v20
	v_mul_f32_e32 v20, 0x3e38aa3b, v21
	v_max3_f32 v9, v9, v16, v17
	v_fmac_f32_e32 v18, v139, v6
	v_fmac_f32_e32 v20, v140, v6
	v_mul_f32_e32 v21, 0x3e38aa3b, v22
	v_mul_f32_e32 v22, 0x3e38aa3b, v23
	v_max3_f32 v9, v9, v18, v20
	v_fmac_f32_e32 v21, v141, v6
	v_fmac_f32_e32 v22, v142, v6
	v_mul_f32_e32 v23, 0x3e38aa3b, v24
	v_mul_f32_e32 v24, 0x3e38aa3b, v25
	v_max3_f32 v9, v9, v21, v22
	v_fmac_f32_e32 v23, v143, v6
	v_fmac_f32_e32 v24, v144, v6
	v_mul_f32_e32 v25, 0x3e38aa3b, v26
	v_mul_f32_e32 v26, 0x3e38aa3b, v27
	v_max3_f32 v9, v9, v23, v24
	v_fmac_f32_e32 v25, v145, v6
	v_fmac_f32_e32 v26, v146, v6
	v_mul_f32_e32 v27, 0x3e38aa3b, v28
	v_mul_f32_e32 v28, 0x3e38aa3b, v29
	v_max3_f32 v9, v9, v25, v26
	v_fmac_f32_e32 v27, v147, v6
	v_fmac_f32_e32 v28, v148, v6
	v_mul_f32_e32 v29, 0x3e38aa3b, v30
	v_mul_f32_e32 v30, 0x3e38aa3b, v31
	v_max3_f32 v9, v9, v27, v28
	v_fmac_f32_e32 v29, v149, v6
	v_fmac_f32_e32 v30, v150, v6
	v_mul_f32_e32 v31, 0x3e38aa3b, v32
	v_mul_f32_e32 v32, 0x3e38aa3b, v33
	v_max3_f32 v9, v9, v29, v30
	v_fmac_f32_e32 v31, v151, v6
	v_fmac_f32_e32 v32, v152, v6
	v_mul_f32_e32 v33, 0x3e38aa3b, v34
	v_mul_f32_e32 v34, 0x3e38aa3b, v35
	v_max3_f32 v9, v9, v31, v32
	v_fmac_f32_e32 v33, v153, v6
	v_fmac_f32_e32 v34, v154, v6
	v_mul_f32_e32 v35, 0x3e38aa3b, v36
	v_mul_f32_e32 v36, 0x3e38aa3b, v37
	v_max3_f32 v9, v9, v33, v34
	v_fmac_f32_e32 v35, v155, v6
	v_fmac_f32_e32 v36, v156, v6
	v_mul_f32_e32 v37, 0x3e38aa3b, v38
	v_mul_f32_e32 v38, 0x3e38aa3b, v39
	v_max3_f32 v9, v9, v35, v36
	v_fmac_f32_e32 v37, v157, v6
	v_fmac_f32_e32 v38, v158, v6
	v_mul_f32_e32 v39, 0x3e38aa3b, v40
	v_mul_f32_e32 v40, 0x3e38aa3b, v41
	v_max3_f32 v9, v9, v37, v38
	v_fmac_f32_e32 v39, v159, v6
	v_fmac_f32_e32 v40, v160, v6
	v_mul_f32_e32 v41, 0x3e38aa3b, v42
	v_mul_f32_e32 v42, 0x3e38aa3b, v43
	v_max3_f32 v9, v9, v39, v40
	v_fmac_f32_e32 v41, v161, v6
	v_fmac_f32_e32 v42, v162, v6
	v_mul_f32_e32 v43, 0x3e38aa3b, v44
	v_mul_f32_e32 v44, 0x3e38aa3b, v45
	v_max3_f32 v9, v9, v41, v42
	v_fmac_f32_e32 v43, v163, v6
	v_fmac_f32_e32 v44, v164, v6
	v_mul_f32_e32 v2, 0x3e38aa3b, v2
	v_mul_f32_e32 v45, 0x3e38aa3b, v3
	v_max3_f32 v9, v9, v43, v44
	v_fmac_f32_e32 v2, v165, v6
	v_fmac_f32_e32 v45, v166, v6
	v_max3_f32 v3, v9, v2, v45
	v_mul_f32_e32 v9, 0x3e38aa3b, v4
	v_mul_f32_e32 v46, 0x3e38aa3b, v5
	v_fmac_f32_e32 v9, v167, v6
	v_fmac_f32_e32 v46, v168, v6
	v_max3_f32 v3, v3, v9, v46
	v_mov_b32_e32 v5, v3
	s_nop 1
	v_permlane16_swap_b32_e32 v5, v3
	v_mul_f32_e32 v4, s4, v249
	s_waitcnt lgkmcnt(0)
	v_max_f32_e32 v5, v5, v5
	v_max_f32_e32 v3, v3, v5
	v_mov_b32_e32 v5, v3
	s_nop 1
	v_permlane32_swap_b32_e32 v5, v3
	s_waitcnt lgkmcnt(0)
	v_max3_f32 v47, v3, v5, v4
	v_sub_f32_e32 v3, v7, v47
	v_exp_f32_e32 v48, v3
	v_sub_f32_e32 v4, v8, v47
	v_exp_f32_e32 v49, v4
	v_sub_f32_e32 v4, v10, v47
	v_exp_f32_e32 v50, v4
	v_sub_f32_e32 v4, v11, v47
	v_exp_f32_e32 v51, v4
	v_sub_f32_e32 v4, v12, v47
	v_add_f32_e32 v3, 0, v48
	v_exp_f32_e32 v52, v4
	v_sub_f32_e32 v4, v13, v47
	v_add_f32_e32 v3, v49, v3
	v_exp_f32_e32 v53, v4
	v_sub_f32_e32 v4, v14, v47
	v_add_f32_e32 v3, v50, v3
	v_exp_f32_e32 v54, v4
	v_sub_f32_e32 v4, v15, v47
	v_add_f32_e32 v3, v51, v3
	v_exp_f32_e32 v55, v4
	v_sub_f32_e32 v4, v16, v47
	v_add_f32_e32 v3, v52, v3
	v_exp_f32_e32 v19, v4
	v_sub_f32_e32 v4, v17, v47
	v_add_f32_e32 v3, v53, v3
	v_exp_f32_e32 v56, v4
	v_sub_f32_e32 v4, v18, v47
	v_add_f32_e32 v3, v54, v3
	v_exp_f32_e32 v57, v4
	v_sub_f32_e32 v4, v20, v47
	v_add_f32_e32 v3, v55, v3
	v_exp_f32_e32 v60, v4
	v_sub_f32_e32 v4, v21, v47
	v_add_f32_e32 v3, v19, v3
	v_exp_f32_e32 v61, v4
	v_sub_f32_e32 v4, v22, v47
	v_add_f32_e32 v3, v56, v3
	v_exp_f32_e32 v62, v4
	v_sub_f32_e32 v4, v23, v47
	v_add_f32_e32 v3, v57, v3
	v_exp_f32_e32 v23, v4
	v_sub_f32_e32 v4, v24, v47
	v_add_f32_e32 v3, v60, v3
	v_exp_f32_e32 v63, v4
	v_sub_f32_e32 v4, v25, v47
	v_add_f32_e32 v3, v61, v3
	v_exp_f32_e32 v14, v4
	v_sub_f32_e32 v4, v26, v47
	v_add_f32_e32 v3, v62, v3
	v_exp_f32_e32 v17, v4
	v_sub_f32_e32 v4, v27, v47
	v_add_f32_e32 v3, v23, v3
	v_exp_f32_e32 v18, v4
	v_sub_f32_e32 v4, v28, v47
	v_add_f32_e32 v3, v63, v3
	v_exp_f32_e32 v22, v4
	v_sub_f32_e32 v4, v29, v47
	v_add_f32_e32 v3, v14, v3
	v_exp_f32_e32 v64, v4
	v_sub_f32_e32 v4, v30, v47
	v_add_f32_e32 v3, v17, v3
	v_exp_f32_e32 v65, v4
	v_sub_f32_e32 v4, v31, v47
	v_add_f32_e32 v3, v18, v3
	v_exp_f32_e32 v66, v4
	v_sub_f32_e32 v4, v32, v47
	v_add_f32_e32 v3, v22, v3
	v_exp_f32_e32 v67, v4
	v_sub_f32_e32 v4, v33, v47
	v_add_f32_e32 v3, v64, v3
	v_exp_f32_e32 v11, v4
	v_sub_f32_e32 v4, v34, v47
	v_add_f32_e32 v3, v65, v3
	v_exp_f32_e32 v12, v4
	v_sub_f32_e32 v4, v35, v47
	v_add_f32_e32 v3, v66, v3
	v_exp_f32_e32 v13, v4
	v_sub_f32_e32 v4, v36, v47
	v_add_f32_e32 v3, v67, v3
	v_exp_f32_e32 v15, v4
	v_sub_f32_e32 v4, v37, v47
	v_add_f32_e32 v3, v11, v3
	v_exp_f32_e32 v16, v4
	v_sub_f32_e32 v4, v38, v47
	v_add_f32_e32 v3, v12, v3
	v_exp_f32_e32 v20, v4
	v_sub_f32_e32 v4, v39, v47
	v_add_f32_e32 v3, v13, v3
	v_exp_f32_e32 v21, v4
	v_sub_f32_e32 v4, v40, v47
	v_add_f32_e32 v3, v15, v3
	v_exp_f32_e32 v68, v4
	v_add_f32_e32 v3, v16, v3
	v_add_f32_e32 v3, v20, v3
	v_add_f32_e32 v3, v21, v3
	v_add_f32_e32 v4, v68, v3
	v_sub_f32_e32 v3, v41, v47
	v_exp_f32_e32 v3, v3
	v_sub_f32_e32 v2, v2, v47
	v_sub_f32_e32 v9, v9, v47
	v_exp_f32_e32 v9, v9
	v_add_f32_e32 v5, v3, v4
	v_sub_f32_e32 v4, v42, v47
	v_exp_f32_e32 v4, v4
	v_sub_f32_e32 v10, v46, v47
	v_exp_f32_e32 v10, v10
	v_add_f32_e32 v6, v4, v5
	v_sub_f32_e32 v5, v43, v47
	v_exp_f32_e32 v5, v5
	s_nop 0
	v_add_f32_e32 v7, v5, v6
	v_sub_f32_e32 v6, v44, v47
	v_exp_f32_e32 v6, v6
	s_nop 0
	v_add_f32_e32 v8, v6, v7
	v_exp_f32_e32 v7, v2
	s_nop 0
	v_add_f32_e32 v2, v7, v8
	v_sub_f32_e32 v8, v45, v47
	v_exp_f32_e32 v8, v8
	s_nop 0
	v_add_f32_e32 v2, v8, v2
	v_add_f32_e32 v2, v9, v2
	v_add_f32_e32 v2, v10, v2
	v_mov_b32_e32 v24, v2
	s_nop 1
	v_permlane16_swap_b32_e32 v24, v2
	s_waitcnt lgkmcnt(0)
	v_add_f32_e32 v2, v2, v24
	v_mov_b32_e32 v24, v2
	s_nop 1
	v_permlane32_swap_b32_e32 v24, v2
	s_waitcnt lgkmcnt(0)
	v_add_f32_e32 v2, v2, v24
	v_fma_f32 v24, s4, v249, -v47
	v_exp_f32_e32 v24, v24
	s_nop 0
	v_add_f32_e32 v2, v24, v2
	v_cvt_pk_bf16_f32 v24, v48, v49
	v_cvt_pk_bf16_f32 v25, v50, v51
	v_cvt_pk_bf16_f32 v26, v52, v53
	v_cvt_pk_bf16_f32 v27, v54, v55
	ds_read_b64_tr_b16 v[30:31], v98 offset:39168
	ds_read_b64_tr_b16 v[28:29], v98 offset:36864
	ds_read_b64_tr_b16 v[32:33], v98 offset:36896
	ds_read_b64_tr_b16 v[34:35], v98 offset:39200
	ds_read_b64_tr_b16 v[36:37], v98 offset:36928
	ds_read_b64_tr_b16 v[38:39], v98 offset:39232
	ds_read_b64_tr_b16 v[40:41], v98 offset:36960
	ds_read_b64_tr_b16 v[42:43], v98 offset:39264
	s_waitcnt lgkmcnt(6)
	v_mfma_f32_16x16x32_bf16 v[28:31], v[28:31], v[24:27], 0
	s_waitcnt lgkmcnt(4)
	v_mfma_f32_16x16x32_bf16 v[32:35], v[32:35], v[24:27], 0
	s_waitcnt lgkmcnt(2)
	v_mfma_f32_16x16x32_bf16 v[36:39], v[36:39], v[24:27], 0
	s_waitcnt lgkmcnt(0)
	v_mfma_f32_16x16x32_bf16 v[24:27], v[40:43], v[24:27], 0
	v_cvt_pk_bf16_f32 v40, v19, v56
	v_cvt_pk_bf16_f32 v41, v57, v60
	v_cvt_pk_bf16_f32 v42, v61, v62
	v_cvt_pk_bf16_f32 v43, v23, v63
	ds_read_b64_tr_b16 v[46:47], v98 offset:43776
	ds_read_b64_tr_b16 v[44:45], v98 offset:41472
	ds_read_b64_tr_b16 v[48:49], v98 offset:41504
	s_waitcnt lgkmcnt(1)
	v_mfma_f32_16x16x32_bf16 v[28:31], v[44:47], v[40:43], v[28:31]
	ds_read_b64_tr_b16 v[50:51], v98 offset:43808
	ds_read_b64_tr_b16 v[44:45], v98 offset:41536
	ds_read_b64_tr_b16 v[46:47], v98 offset:43840
	s_waitcnt lgkmcnt(0)
	v_mfma_f32_16x16x32_bf16 v[36:39], v[44:47], v[40:43], v[36:39]
	ds_read_b64_tr_b16 v[44:45], v98 offset:41568
	ds_read_b64_tr_b16 v[46:47], v98 offset:43872
	v_mfma_f32_16x16x32_bf16 v[32:35], v[48:51], v[40:43], v[32:35]
	s_waitcnt lgkmcnt(0)
	v_mfma_f32_16x16x32_bf16 v[24:27], v[44:47], v[40:43], v[24:27]
	v_cvt_pk_bf16_f32 v40, v14, v17
	v_cvt_pk_bf16_f32 v41, v18, v22
	v_cvt_pk_bf16_f32 v42, v64, v65
	v_cvt_pk_bf16_f32 v43, v66, v67
	ds_read_b64_tr_b16 v[46:47], v98 offset:48384
	ds_read_b64_tr_b16 v[44:45], v98 offset:46080
	ds_read_b64_tr_b16 v[48:49], v98 offset:46112
	s_waitcnt lgkmcnt(1)
	v_mfma_f32_16x16x32_bf16 v[28:31], v[44:47], v[40:43], v[28:31]
	ds_read_b64_tr_b16 v[50:51], v98 offset:48416
	ds_read_b64_tr_b16 v[44:45], v98 offset:46144
	ds_read_b64_tr_b16 v[46:47], v98 offset:48448
	s_waitcnt lgkmcnt(0)
	v_mfma_f32_16x16x32_bf16 v[36:39], v[44:47], v[40:43], v[36:39]
	ds_read_b64_tr_b16 v[44:45], v98 offset:46176
	ds_read_b64_tr_b16 v[46:47], v98 offset:48480
	v_cvt_pk_bf16_f32 v12, v11, v12
	v_cvt_pk_bf16_f32 v13, v13, v15
	s_waitcnt lgkmcnt(0)
	v_mfma_f32_16x16x32_bf16 v[22:25], v[44:47], v[40:43], v[24:27]
	v_cvt_pk_bf16_f32 v14, v16, v20
	v_cvt_pk_bf16_f32 v15, v21, v68
	ds_read_b64_tr_b16 v[18:19], v98 offset:52992
	ds_read_b64_tr_b16 v[16:17], v98 offset:50688
	s_nop 0
	ds_read_b64_tr_b16 v[26:27], v98 offset:50720
	s_waitcnt lgkmcnt(1)
	v_mfma_f32_16x16x32_bf16 v[16:19], v[16:19], v[12:15], v[28:31]
	s_nop 2
	ds_read_b64_tr_b16 v[28:29], v98 offset:53024
	v_mfma_f32_16x16x32_bf16 v[32:35], v[48:51], v[40:43], v[32:35]
	s_waitcnt lgkmcnt(0)
	v_mfma_f32_16x16x32_bf16 v[26:29], v[26:29], v[12:15], v[32:35]
	ds_read_b64_tr_b16 v[30:31], v98 offset:50752
	s_nop 4
	ds_read_b64_tr_b16 v[32:33], v98 offset:53056
	s_waitcnt lgkmcnt(0)
	v_mfma_f32_16x16x32_bf16 v[30:33], v[30:33], v[12:15], v[36:39]
	ds_read_b64_tr_b16 v[34:35], v98 offset:50784
	s_nop 1
	ds_read_b64_tr_b16 v[36:37], v98 offset:53088
	v_cvt_pk_bf16_f32 v4, v3, v4
	v_cvt_pk_bf16_f32 v5, v5, v6
	s_waitcnt lgkmcnt(0)
	v_mfma_f32_16x16x32_bf16 v[12:15], v[34:37], v[12:15], v[22:25]
	v_cvt_pk_bf16_f32 v6, v7, v8
	v_cvt_pk_bf16_f32 v7, v9, v10
	ds_read_b64_tr_b16 v[10:11], v98 offset:57600
	ds_read_b64_tr_b16 v[8:9], v98 offset:55296
	ds_read_b64_tr_b16 v[20:21], v98 offset:55328
	ds_read_b64_tr_b16 v[22:23], v98 offset:57632
	s_waitcnt lgkmcnt(2)
	v_mfma_f32_16x16x32_bf16 v[8:11], v[8:11], v[4:7], v[16:19]
	v_div_scale_f32 v3, s[4:5], v2, v2, 1.0
	s_waitcnt lgkmcnt(0)
	v_mfma_f32_16x16x32_bf16 v[16:19], v[20:23], v[4:7], v[26:29]
	ds_read_b64_tr_b16 v[20:21], v98 offset:55360
	ds_read_b64_tr_b16 v[22:23], v98 offset:57664
	ds_read_b64_tr_b16 v[24:25], v98 offset:55392
	ds_read_b64_tr_b16 v[26:27], v98 offset:57696
	s_waitcnt lgkmcnt(2)
	v_mfma_f32_16x16x32_bf16 v[20:23], v[20:23], v[4:7], v[30:33]
	s_waitcnt lgkmcnt(0)
	v_mfma_f32_16x16x32_bf16 v[4:7], v[24:27], v[4:7], v[12:15]
	s_nop 2
	v_rcp_f32_e32 v12, v3
	s_nop 0
	v_fma_f32 v13, -v3, v12, 1.0
	v_fmac_f32_e32 v12, v13, v12
	v_div_scale_f32 v13, vcc, 1.0, v2, 1.0
	v_mul_f32_e32 v14, v13, v12
	v_fma_f32 v15, -v3, v14, v13
	v_fmac_f32_e32 v14, v15, v12
	v_fma_f32 v3, -v3, v14, v13
	v_div_fmas_f32 v3, v3, v12, v14
	v_div_fixup_f32 v2, v3, v2, 1.0
	v_pk_mul_f32 v[10:11], v[2:3], v[10:11] op_sel_hi:[0,1]
	v_pk_mul_f32 v[8:9], v[2:3], v[8:9] op_sel_hi:[0,1]
	v_pk_mul_f32 v[12:13], v[2:3], v[18:19] op_sel_hi:[0,1]
	v_pk_mul_f32 v[14:15], v[2:3], v[16:17] op_sel_hi:[0,1]
	v_cvt_pk_bf16_f32 v8, v8, v9
	v_cvt_pk_bf16_f32 v9, v10, v11
	v_cvt_pk_bf16_f32 v10, v14, v15
	v_cvt_pk_bf16_f32 v11, v12, v13
	v_pk_mul_f32 v[4:5], v[2:3], v[4:5] op_sel_hi:[0,1]
	global_store_dwordx4 v[58:59], v[8:11], off offset:896
	v_pk_mul_f32 v[6:7], v[2:3], v[6:7] op_sel_hi:[0,1]
	s_nop 0
	v_pk_mul_f32 v[8:9], v[2:3], v[22:23] op_sel_hi:[0,1]
	v_pk_mul_f32 v[10:11], v[2:3], v[20:21] op_sel_hi:[0,1]
	v_cvt_pk_bf16_f32 v2, v10, v11
	v_cvt_pk_bf16_f32 v3, v8, v9
	v_cvt_pk_bf16_f32 v4, v4, v5
	v_cvt_pk_bf16_f32 v5, v6, v7
	global_store_dwordx4 v[58:59], v[2:5], off offset:960
	s_barrier
	s_cbranch_scc1 .LBB0_925
